# E31: E27 + FFN-up sample-row epilogue touches its 16 conv-history lines up front via LDS-DMA (L2 prefetch for the 4-deep history ring)
# speedup vs baseline: 1.0047x; 1.0047x over previous
.Lmy_ffnA_sample:
	s_load_dwordx2 s[36:37], s[78:79], 0x268
	s_load_dwordx2 s[38:39], s[78:79], 0x2a0
	s_load_dwordx4 s[40:43], s[78:79], 0x70
	s_load_dwordx2 s[44:45], s[78:79], 0x128
	s_load_dwordx2 s[16:17], s[78:79], 0x28
	v_and_b32_e32 v204, 15, v248
	v_bfe_u32 v205, v248, 8, 1
	v_bfe_u32 v206, v248, 6, 2
	v_bfe_u32 v207, v248, 4, 2
	v_lshlrev_b32_e32 v206, 5, v206
	v_lshl_or_b32 v206, v207, 3, v206
	s_lshl_b32 s13, s14, 7
	v_add_u32_e32 v206, s13, v206
	s_lshl_b32 s13, s12, 8
	v_lshl_add_u32 v207, v205, 6, v204
	v_add_u32_e32 v207, s13, v207
	v_mul_u32_u24_e32 v231, 0x1600, v207
	v_lshl_add_u32 v231, v206, 1, v231
	v_lshlrev_b32_e32 v232, 2, v206
	s_lshl_b32 s13, s12, 4
	v_lshl_add_u32 v233, v205, 2, s13
	v_add_u32_e32 v208, -12, v204
	v_cmp_gt_u32_e32 vcc, 2, v204
	s_nop 1
	v_cndmask_b32_e32 v208, v208, v204, vcc
	v_add_u32_e32 v233, v233, v208
	v_mul_u32_u24_e32 v233, 0x2c00, v233
	v_lshl_add_u32 v233, v206, 1, v233
	s_sub_u32 s13, s12, 64
	s_lshl_b32 s13, s13, 5
	s_add_u32 s13, s13, 0
	v_lshrrev_b32_e32 v208, 3, v204
	v_lshl_add_u32 v208, v205, 3, v208
	v_add_u32_e32 v208, s13, v208
	v_mul_u32_u24_e32 v234, 0xb000, v208
	v_add_u32_e32 v234, v234, v232
	v_and_b32_e32 v209, 7, v204
	v_mul_u32_u24_e32 v190, 0x5800, v209
	v_add_u32_e32 v235, 0xfffdf000, v190
	v_add_u32_e32 v235, v235, v234
	v_add_u32_e32 v190, v190, v234
	s_mov_b32 s46, 0x01010101
	s_mov_b32 s47, 0x01010101
	s_mov_b32 s48, 0x03030303
	s_mov_b32 s49, 0x03030303
	s_mov_b32 s50, 0xc0c0c0c0
	s_mov_b32 s51, 0xc0c0c0c0
	s_waitcnt lgkmcnt(0)
	global_load_dwordx4 v[130:133], v232, s[40:41]
	v_add_u32_e32 v213, 0x5800, v232
	global_load_dwordx4 v[134:137], v213, s[40:41]
	v_add_u32_e32 v214, 0xb000, v232
	global_load_dwordx4 v[138:141], v214, s[40:41]
	global_load_dwordx4 v[142:145], v232, s[42:43]
	v_add_u32_e32 v215, 0x2c00, v232
	global_load_dwordx4 v[146:149], v215, s[40:41]
	v_add_u32_e32 v216, 0x8400, v232
	global_load_dwordx4 v[150:153], v216, s[40:41]
	v_add_u32_e32 v217, 0xdc00, v232
	global_load_dwordx4 v[154:157], v217, s[40:41]
	v_add_u32_e32 v218, 0x2c00, v232
	global_load_dwordx4 v[158:161], v218, s[42:43]
	s_mov_b32 s4, m0
	s_mov_b32 m0, 0x23000
	s_mov_b64 exec, s[48:49]
	global_load_lds_dword v190, s[16:17]
	v_add_u32_e32 v222, 0x2c00, v190
	global_load_lds_dword v222, s[16:17]
	v_add_u32_e32 v222, 0x16000, v190
	global_load_lds_dword v222, s[16:17]
	v_add_u32_e32 v222, 0x18c00, v190
	global_load_lds_dword v222, s[16:17]
	v_add_u32_e32 v222, 0x2c000, v190
	global_load_lds_dword v222, s[16:17]
	v_add_u32_e32 v222, 0x2ec00, v190
	global_load_lds_dword v222, s[16:17]
	v_add_u32_e32 v222, 0x42000, v190
	global_load_lds_dword v222, s[16:17]
	v_add_u32_e32 v222, 0x44c00, v190
	global_load_lds_dword v222, s[16:17]
	v_add_u32_e32 v222, 0xb0000, v190
	global_load_lds_dword v222, s[16:17]
	v_add_u32_e32 v222, 0xb2c00, v190
	global_load_lds_dword v222, s[16:17]
	v_add_u32_e32 v222, 0xc6000, v190
	global_load_lds_dword v222, s[16:17]
	v_add_u32_e32 v222, 0xc8c00, v190
	global_load_lds_dword v222, s[16:17]
	v_add_u32_e32 v222, 0xdc000, v190
	global_load_lds_dword v222, s[16:17]
	v_add_u32_e32 v222, 0xdec00, v190
	global_load_lds_dword v222, s[16:17]
	v_add_u32_e32 v222, 0xf2000, v190
	global_load_lds_dword v222, s[16:17]
	v_add_u32_e32 v222, 0xf4c00, v190
	global_load_lds_dword v222, s[16:17]
	s_mov_b64 exec, -1
	s_mov_b32 m0, s4
	s_mov_b64 exec, s[48:49]
	global_load_dwordx4 v[162:165], v190, s[16:17]
	s_mov_b64 exec, -1
	s_mov_b64 exec, s[48:49]
	v_add_u32_e32 v222, 0x2c00, v190
	global_load_dwordx4 v[166:169], v222, s[16:17]
	s_mov_b64 exec, -1
	s_mov_b64 exec, s[48:49]
	v_add_u32_e32 v222, 0x16000, v190
	global_load_dwordx4 v[170:173], v222, s[16:17]
	s_mov_b64 exec, -1
	s_mov_b64 exec, s[48:49]
	v_add_u32_e32 v222, 0x18c00, v190
	global_load_dwordx4 v[174:177], v222, s[16:17]
	s_mov_b64 exec, -1
	s_mov_b32 exec_lo, 0x30003
	s_mov_b32 exec_hi, 0x30003
	v_cvt_pk_bf16_f32 v204, v126, v127
	v_cvt_pk_bf16_f32 v205, v128, v129
	global_store_dwordx2 v233, v[204:205], s[38:39]
	v_cvt_pk_bf16_f32 v206, v122, v123
	v_cvt_pk_bf16_f32 v207, v124, v125
	v_add_u32_e32 v220, 0x1600, v233
	global_store_dwordx2 v220, v[206:207], s[38:39]
	v_cvt_pk_bf16_f32 v208, v94, v95
	v_cvt_pk_bf16_f32 v209, v96, v97
	v_add_u32_e32 v221, 0x16000, v233
	global_store_dwordx2 v221, v[208:209], s[38:39]
	v_cvt_pk_bf16_f32 v210, v90, v91
	v_cvt_pk_bf16_f32 v211, v92, v93
	v_add_u32_e32 v222, 0x17600, v233
	global_store_dwordx2 v222, v[210:211], s[38:39]
	v_cvt_pk_bf16_f32 v212, v62, v63
	v_cvt_pk_bf16_f32 v213, v64, v65
	v_add_u32_e32 v223, 0x8, v233
	global_store_dwordx2 v223, v[212:213], s[38:39]
	v_cvt_pk_bf16_f32 v214, v58, v59
	v_cvt_pk_bf16_f32 v215, v60, v61
	v_add_u32_e32 v224, 0x1608, v233
	global_store_dwordx2 v224, v[214:215], s[38:39]
	v_cvt_pk_bf16_f32 v216, v30, v31
	v_cvt_pk_bf16_f32 v217, v32, v33
	v_add_u32_e32 v225, 0x16008, v233
	global_store_dwordx2 v225, v[216:217], s[38:39]
	v_cvt_pk_bf16_f32 v218, v26, v27
	v_cvt_pk_bf16_f32 v219, v28, v29
	v_add_u32_e32 v226, 0x17608, v233
	global_store_dwordx2 v226, v[218:219], s[38:39]
	s_mov_b32 exec_lo, 0xc000c000
	s_mov_b32 exec_hi, 0xc000c000
	v_cvt_pk_bf16_f32 v204, v102, v103
	v_cvt_pk_bf16_f32 v205, v104, v105
	global_store_dwordx2 v233, v[204:205], s[38:39]
	v_cvt_pk_bf16_f32 v206, v98, v99
	v_cvt_pk_bf16_f32 v207, v100, v101
	v_add_u32_e32 v220, 0x1600, v233
	global_store_dwordx2 v220, v[206:207], s[38:39]
	v_cvt_pk_bf16_f32 v208, v70, v71
	v_cvt_pk_bf16_f32 v209, v72, v73
	v_add_u32_e32 v221, 0x16000, v233
	global_store_dwordx2 v221, v[208:209], s[38:39]
	v_cvt_pk_bf16_f32 v210, v66, v67
	v_cvt_pk_bf16_f32 v211, v68, v69
	v_add_u32_e32 v222, 0x17600, v233
	global_store_dwordx2 v222, v[210:211], s[38:39]
	v_cvt_pk_bf16_f32 v212, v38, v39
	v_cvt_pk_bf16_f32 v213, v40, v41
	v_add_u32_e32 v223, 0x8, v233
	global_store_dwordx2 v223, v[212:213], s[38:39]
	v_cvt_pk_bf16_f32 v214, v34, v35
	v_cvt_pk_bf16_f32 v215, v36, v37
	v_add_u32_e32 v224, 0x1608, v233
	global_store_dwordx2 v224, v[214:215], s[38:39]
	v_cvt_pk_bf16_f32 v216, v6, v7
	v_cvt_pk_bf16_f32 v217, v8, v9
	v_add_u32_e32 v225, 0x16008, v233
	global_store_dwordx2 v225, v[216:217], s[38:39]
	v_cvt_pk_bf16_f32 v218, v2, v3
	v_cvt_pk_bf16_f32 v219, v4, v5
	v_add_u32_e32 v226, 0x17608, v233
	global_store_dwordx2 v226, v[218:219], s[38:39]
	s_mov_b64 exec, -1
	s_waitcnt vmcnt(36)
	s_mov_b64 exec, s[50:51]
	global_store_dwordx4 v235, v[126:129], s[44:45]
	v_add_u32_e32 v224, 0x2c00, v235
	global_store_dwordx4 v224, v[122:125], s[44:45]
	v_add_u32_e32 v225, 0x16000, v235
	global_store_dwordx4 v225, v[118:121], s[44:45]
	v_add_u32_e32 v226, 0x18c00, v235
	global_store_dwordx4 v226, v[114:117], s[44:45]
	v_add_u32_e32 v223, 0x2c000, v235
	global_store_dwordx4 v223, v[110:113], s[44:45]
	v_add_u32_e32 v224, 0x2ec00, v235
	global_store_dwordx4 v224, v[106:109], s[44:45]
	v_add_u32_e32 v225, 0x42000, v235
	global_store_dwordx4 v225, v[102:105], s[44:45]
	v_add_u32_e32 v226, 0x44c00, v235
	global_store_dwordx4 v226, v[98:101], s[44:45]
	v_add_u32_e32 v223, 0xb0000, v235
	global_store_dwordx4 v223, v[94:97], s[44:45]
	v_add_u32_e32 v224, 0xb2c00, v235
	global_store_dwordx4 v224, v[90:93], s[44:45]
	v_add_u32_e32 v225, 0xc6000, v235
	global_store_dwordx4 v225, v[86:89], s[44:45]
	v_add_u32_e32 v226, 0xc8c00, v235
	global_store_dwordx4 v226, v[82:85], s[44:45]
	v_add_u32_e32 v223, 0xdc000, v235
	global_store_dwordx4 v223, v[78:81], s[44:45]
	v_add_u32_e32 v224, 0xdec00, v235
	global_store_dwordx4 v224, v[74:77], s[44:45]
	v_add_u32_e32 v225, 0xf2000, v235
	global_store_dwordx4 v225, v[70:73], s[44:45]
	v_add_u32_e32 v226, 0xf4c00, v235
	global_store_dwordx4 v226, v[66:69], s[44:45]
	s_mov_b64 exec, -1
	v_pk_fma_f32 v[212:213], v[138:139], v[126:127], v[142:143]
	v_pk_fma_f32 v[214:215], v[140:141], v[128:129], v[144:145]
	s_nop 2
	v_mov_b32_dpp v204, v126 row_shr:1 row_mask:0xf bank_mask:0xf
	v_mov_b32_dpp v208, v126 row_shr:2 row_mask:0xf bank_mask:0xf
	v_mov_b32_dpp v205, v127 row_shr:1 row_mask:0xf bank_mask:0xf
	v_mov_b32_dpp v209, v127 row_shr:2 row_mask:0xf bank_mask:0xf
	v_mov_b32_dpp v206, v128 row_shr:1 row_mask:0xf bank_mask:0xf
	v_mov_b32_dpp v210, v128 row_shr:2 row_mask:0xf bank_mask:0xf
	v_mov_b32_dpp v207, v129 row_shr:1 row_mask:0xf bank_mask:0xf
	v_mov_b32_dpp v211, v129 row_shr:2 row_mask:0xf bank_mask:0xf
	s_waitcnt vmcnt(35)
	v_mov_b32_dpp v223, v162 row_shl:1 row_mask:0xf bank_mask:0xf
	v_mov_b32_dpp v224, v163 row_shl:1 row_mask:0xf bank_mask:0xf
	v_mov_b32_dpp v225, v164 row_shl:1 row_mask:0xf bank_mask:0xf
	v_mov_b32_dpp v226, v165 row_shl:1 row_mask:0xf bank_mask:0xf
	v_cndmask_b32_e64 v208, v208, v162, s[48:49]
	v_cndmask_b32_e64 v209, v209, v163, s[48:49]
	v_cndmask_b32_e64 v210, v210, v164, s[48:49]
	v_cndmask_b32_e64 v211, v211, v165, s[48:49]
	v_cndmask_b32_e64 v204, v204, v223, s[46:47]
	v_cndmask_b32_e64 v205, v205, v224, s[46:47]
	v_cndmask_b32_e64 v206, v206, v225, s[46:47]
	v_cndmask_b32_e64 v207, v207, v226, s[46:47]
	s_mov_b64 exec, s[48:49]
	v_add_u32_e32 v222, 0x2c000, v190
	global_load_dwordx4 v[162:165], v222, s[16:17]
	s_mov_b64 exec, -1
	v_pk_fma_f32 v[212:213], v[134:135], v[204:205], v[212:213]
	v_pk_fma_f32 v[214:215], v[136:137], v[206:207], v[214:215]
	v_pk_fma_f32 v[212:213], v[130:131], v[208:209], v[212:213]
	v_pk_fma_f32 v[214:215], v[132:133], v[210:211], v[214:215]
	v_pk_fma_f32 v[216:217], v[154:155], v[122:123], v[158:159]
	v_pk_fma_f32 v[218:219], v[156:157], v[124:125], v[160:161]
	s_nop 2
	v_mov_b32_dpp v204, v122 row_shr:1 row_mask:0xf bank_mask:0xf
	v_mov_b32_dpp v208, v122 row_shr:2 row_mask:0xf bank_mask:0xf
	v_mov_b32_dpp v205, v123 row_shr:1 row_mask:0xf bank_mask:0xf
	v_mov_b32_dpp v209, v123 row_shr:2 row_mask:0xf bank_mask:0xf
	v_mov_b32_dpp v206, v124 row_shr:1 row_mask:0xf bank_mask:0xf
	v_mov_b32_dpp v210, v124 row_shr:2 row_mask:0xf bank_mask:0xf
	v_mov_b32_dpp v207, v125 row_shr:1 row_mask:0xf bank_mask:0xf
	v_mov_b32_dpp v211, v125 row_shr:2 row_mask:0xf bank_mask:0xf
	s_waitcnt vmcnt(35)
	v_mov_b32_dpp v223, v166 row_shl:1 row_mask:0xf bank_mask:0xf
	v_mov_b32_dpp v224, v167 row_shl:1 row_mask:0xf bank_mask:0xf
	v_mov_b32_dpp v225, v168 row_shl:1 row_mask:0xf bank_mask:0xf
	v_mov_b32_dpp v226, v169 row_shl:1 row_mask:0xf bank_mask:0xf
	v_cndmask_b32_e64 v208, v208, v166, s[48:49]
	v_cndmask_b32_e64 v209, v209, v167, s[48:49]
	v_cndmask_b32_e64 v210, v210, v168, s[48:49]
	v_cndmask_b32_e64 v211, v211, v169, s[48:49]
	v_cndmask_b32_e64 v204, v204, v223, s[46:47]
	v_cndmask_b32_e64 v205, v205, v224, s[46:47]
	v_cndmask_b32_e64 v206, v206, v225, s[46:47]
	v_cndmask_b32_e64 v207, v207, v226, s[46:47]
	s_mov_b64 exec, s[48:49]
	v_add_u32_e32 v222, 0x2ec00, v190
	global_load_dwordx4 v[166:169], v222, s[16:17]
	s_mov_b64 exec, -1
	v_pk_fma_f32 v[216:217], v[150:151], v[204:205], v[216:217]
	v_pk_fma_f32 v[218:219], v[152:153], v[206:207], v[218:219]
	v_pk_fma_f32 v[216:217], v[146:147], v[208:209], v[216:217]
	v_pk_fma_f32 v[218:219], v[148:149], v[210:211], v[218:219]
	v_mul_f32_e32 v204, 0xbfb8aa3b, v216
	v_mul_f32_e32 v205, 0xbfb8aa3b, v217
	v_mul_f32_e32 v206, 0xbfb8aa3b, v218
	v_mul_f32_e32 v207, 0xbfb8aa3b, v219
	v_exp_f32_e32 v204, v204
	v_exp_f32_e32 v205, v205
	v_exp_f32_e32 v206, v206
	v_exp_f32_e32 v207, v207
	v_add_f32_e32 v204, 1.0, v204
	v_add_f32_e32 v205, 1.0, v205
	v_add_f32_e32 v206, 1.0, v206
	v_add_f32_e32 v207, 1.0, v207
	v_rcp_f32_e32 v204, v204
	v_rcp_f32_e32 v205, v205
	v_rcp_f32_e32 v206, v206
	v_rcp_f32_e32 v207, v207
	v_mul_f32_e32 v204, v216, v204
	v_mul_f32_e32 v205, v217, v205
	v_mul_f32_e32 v206, v218, v206
	v_mul_f32_e32 v207, v219, v207
	v_mul_f32_e32 v204, v212, v204
	v_mul_f32_e32 v205, v213, v205
	v_mul_f32_e32 v206, v214, v206
	v_mul_f32_e32 v207, v215, v207
	v_cvt_pk_bf16_f32 v220, v204, v205
	v_cvt_pk_bf16_f32 v221, v206, v207
	v_mov_b32_e32 v222, v231
	s_mov_b32 exec_lo, 0xfffcfffc
	s_mov_b32 exec_hi, 0xfffcfffc
	global_store_dwordx2 v222, v[220:221], s[36:37]
	s_mov_b64 exec, -1
	v_pk_fma_f32 v[212:213], v[138:139], v[118:119], v[142:143]
	v_pk_fma_f32 v[214:215], v[140:141], v[120:121], v[144:145]
	s_nop 2
	v_mov_b32_dpp v204, v118 row_shr:1 row_mask:0xf bank_mask:0xf
	v_mov_b32_dpp v208, v118 row_shr:2 row_mask:0xf bank_mask:0xf
	v_mov_b32_dpp v205, v119 row_shr:1 row_mask:0xf bank_mask:0xf
	v_mov_b32_dpp v209, v119 row_shr:2 row_mask:0xf bank_mask:0xf
	v_mov_b32_dpp v206, v120 row_shr:1 row_mask:0xf bank_mask:0xf
	v_mov_b32_dpp v210, v120 row_shr:2 row_mask:0xf bank_mask:0xf
	v_mov_b32_dpp v207, v121 row_shr:1 row_mask:0xf bank_mask:0xf
	v_mov_b32_dpp v211, v121 row_shr:2 row_mask:0xf bank_mask:0xf
	s_waitcnt vmcnt(36)
	v_mov_b32_dpp v223, v170 row_shl:1 row_mask:0xf bank_mask:0xf
	v_mov_b32_dpp v224, v171 row_shl:1 row_mask:0xf bank_mask:0xf
	v_mov_b32_dpp v225, v172 row_shl:1 row_mask:0xf bank_mask:0xf
	v_mov_b32_dpp v226, v173 row_shl:1 row_mask:0xf bank_mask:0xf
	v_cndmask_b32_e64 v208, v208, v170, s[48:49]
	v_cndmask_b32_e64 v209, v209, v171, s[48:49]
	v_cndmask_b32_e64 v210, v210, v172, s[48:49]
	v_cndmask_b32_e64 v211, v211, v173, s[48:49]
	v_cndmask_b32_e64 v204, v204, v223, s[46:47]
	v_cndmask_b32_e64 v205, v205, v224, s[46:47]
	v_cndmask_b32_e64 v206, v206, v225, s[46:47]
	v_cndmask_b32_e64 v207, v207, v226, s[46:47]
	s_mov_b64 exec, s[48:49]
	v_add_u32_e32 v222, 0x42000, v190
	global_load_dwordx4 v[170:173], v222, s[16:17]
	s_mov_b64 exec, -1
	v_pk_fma_f32 v[212:213], v[134:135], v[204:205], v[212:213]
	v_pk_fma_f32 v[214:215], v[136:137], v[206:207], v[214:215]
	v_pk_fma_f32 v[212:213], v[130:131], v[208:209], v[212:213]
	v_pk_fma_f32 v[214:215], v[132:133], v[210:211], v[214:215]
	v_pk_fma_f32 v[216:217], v[154:155], v[114:115], v[158:159]
	v_pk_fma_f32 v[218:219], v[156:157], v[116:117], v[160:161]
	s_nop 2
	v_mov_b32_dpp v204, v114 row_shr:1 row_mask:0xf bank_mask:0xf
	v_mov_b32_dpp v208, v114 row_shr:2 row_mask:0xf bank_mask:0xf
	v_mov_b32_dpp v205, v115 row_shr:1 row_mask:0xf bank_mask:0xf
	v_mov_b32_dpp v209, v115 row_shr:2 row_mask:0xf bank_mask:0xf
	v_mov_b32_dpp v206, v116 row_shr:1 row_mask:0xf bank_mask:0xf
	v_mov_b32_dpp v210, v116 row_shr:2 row_mask:0xf bank_mask:0xf
	v_mov_b32_dpp v207, v117 row_shr:1 row_mask:0xf bank_mask:0xf
	v_mov_b32_dpp v211, v117 row_shr:2 row_mask:0xf bank_mask:0xf
	s_waitcnt vmcnt(36)
	v_mov_b32_dpp v223, v174 row_shl:1 row_mask:0xf bank_mask:0xf
	v_mov_b32_dpp v224, v175 row_shl:1 row_mask:0xf bank_mask:0xf
	v_mov_b32_dpp v225, v176 row_shl:1 row_mask:0xf bank_mask:0xf
	v_mov_b32_dpp v226, v177 row_shl:1 row_mask:0xf bank_mask:0xf
	v_cndmask_b32_e64 v208, v208, v174, s[48:49]
	v_cndmask_b32_e64 v209, v209, v175, s[48:49]
	v_cndmask_b32_e64 v210, v210, v176, s[48:49]
	v_cndmask_b32_e64 v211, v211, v177, s[48:49]
	v_cndmask_b32_e64 v204, v204, v223, s[46:47]
	v_cndmask_b32_e64 v205, v205, v224, s[46:47]
	v_cndmask_b32_e64 v206, v206, v225, s[46:47]
	v_cndmask_b32_e64 v207, v207, v226, s[46:47]
	s_mov_b64 exec, s[48:49]
	v_add_u32_e32 v222, 0x44c00, v190
	global_load_dwordx4 v[174:177], v222, s[16:17]
	s_mov_b64 exec, -1
	v_pk_fma_f32 v[216:217], v[150:151], v[204:205], v[216:217]
	v_pk_fma_f32 v[218:219], v[152:153], v[206:207], v[218:219]
	v_pk_fma_f32 v[216:217], v[146:147], v[208:209], v[216:217]
	v_pk_fma_f32 v[218:219], v[148:149], v[210:211], v[218:219]
	v_mul_f32_e32 v204, 0xbfb8aa3b, v216
	v_mul_f32_e32 v205, 0xbfb8aa3b, v217
	v_mul_f32_e32 v206, 0xbfb8aa3b, v218
	v_mul_f32_e32 v207, 0xbfb8aa3b, v219
	v_exp_f32_e32 v204, v204
	v_exp_f32_e32 v205, v205
	v_exp_f32_e32 v206, v206
	v_exp_f32_e32 v207, v207
	v_add_f32_e32 v204, 1.0, v204
	v_add_f32_e32 v205, 1.0, v205
	v_add_f32_e32 v206, 1.0, v206
	v_add_f32_e32 v207, 1.0, v207
	v_rcp_f32_e32 v204, v204
	v_rcp_f32_e32 v205, v205
	v_rcp_f32_e32 v206, v206
	v_rcp_f32_e32 v207, v207
	v_mul_f32_e32 v204, v216, v204
	v_mul_f32_e32 v205, v217, v205
	v_mul_f32_e32 v206, v218, v206
	v_mul_f32_e32 v207, v219, v207
	v_mul_f32_e32 v204, v212, v204
	v_mul_f32_e32 v205, v213, v205
	v_mul_f32_e32 v206, v214, v206
	v_mul_f32_e32 v207, v215, v207
	v_cvt_pk_bf16_f32 v220, v204, v205
	v_cvt_pk_bf16_f32 v221, v206, v207
	v_add_u32_e32 v222, 0x16000, v231
	global_store_dwordx2 v222, v[220:221], s[36:37]
	v_pk_fma_f32 v[212:213], v[138:139], v[110:111], v[142:143]
	v_pk_fma_f32 v[214:215], v[140:141], v[112:113], v[144:145]
	s_nop 2
	v_mov_b32_dpp v204, v110 row_shr:1 row_mask:0xf bank_mask:0xf
	v_mov_b32_dpp v208, v110 row_shr:2 row_mask:0xf bank_mask:0xf
	v_mov_b32_dpp v205, v111 row_shr:1 row_mask:0xf bank_mask:0xf
	v_mov_b32_dpp v209, v111 row_shr:2 row_mask:0xf bank_mask:0xf
	v_mov_b32_dpp v206, v112 row_shr:1 row_mask:0xf bank_mask:0xf
	v_mov_b32_dpp v210, v112 row_shr:2 row_mask:0xf bank_mask:0xf
	v_mov_b32_dpp v207, v113 row_shr:1 row_mask:0xf bank_mask:0xf
	v_mov_b32_dpp v211, v113 row_shr:2 row_mask:0xf bank_mask:0xf
	s_waitcnt vmcnt(5)
	v_mov_b32_dpp v223, v162 row_shl:1 row_mask:0xf bank_mask:0xf
	v_mov_b32_dpp v224, v163 row_shl:1 row_mask:0xf bank_mask:0xf
	v_mov_b32_dpp v225, v164 row_shl:1 row_mask:0xf bank_mask:0xf
	v_mov_b32_dpp v226, v165 row_shl:1 row_mask:0xf bank_mask:0xf
	v_cndmask_b32_e64 v208, v208, v162, s[48:49]
	v_cndmask_b32_e64 v209, v209, v163, s[48:49]
	v_cndmask_b32_e64 v210, v210, v164, s[48:49]
	v_cndmask_b32_e64 v211, v211, v165, s[48:49]
	v_cndmask_b32_e64 v204, v204, v223, s[46:47]
	v_cndmask_b32_e64 v205, v205, v224, s[46:47]
	v_cndmask_b32_e64 v206, v206, v225, s[46:47]
	v_cndmask_b32_e64 v207, v207, v226, s[46:47]
	s_mov_b64 exec, s[48:49]
	v_add_u32_e32 v222, 0xb0000, v190
	global_load_dwordx4 v[162:165], v222, s[16:17]
	s_mov_b64 exec, -1
	v_pk_fma_f32 v[212:213], v[134:135], v[204:205], v[212:213]
	v_pk_fma_f32 v[214:215], v[136:137], v[206:207], v[214:215]
	v_pk_fma_f32 v[212:213], v[130:131], v[208:209], v[212:213]
	v_pk_fma_f32 v[214:215], v[132:133], v[210:211], v[214:215]
	v_pk_fma_f32 v[216:217], v[154:155], v[106:107], v[158:159]
	v_pk_fma_f32 v[218:219], v[156:157], v[108:109], v[160:161]
	s_nop 2
	v_mov_b32_dpp v204, v106 row_shr:1 row_mask:0xf bank_mask:0xf
	v_mov_b32_dpp v208, v106 row_shr:2 row_mask:0xf bank_mask:0xf
	v_mov_b32_dpp v205, v107 row_shr:1 row_mask:0xf bank_mask:0xf
	v_mov_b32_dpp v209, v107 row_shr:2 row_mask:0xf bank_mask:0xf
	v_mov_b32_dpp v206, v108 row_shr:1 row_mask:0xf bank_mask:0xf
	v_mov_b32_dpp v210, v108 row_shr:2 row_mask:0xf bank_mask:0xf
	v_mov_b32_dpp v207, v109 row_shr:1 row_mask:0xf bank_mask:0xf
	v_mov_b32_dpp v211, v109 row_shr:2 row_mask:0xf bank_mask:0xf
	s_waitcnt vmcnt(5)
	v_mov_b32_dpp v223, v166 row_shl:1 row_mask:0xf bank_mask:0xf
	v_mov_b32_dpp v224, v167 row_shl:1 row_mask:0xf bank_mask:0xf
	v_mov_b32_dpp v225, v168 row_shl:1 row_mask:0xf bank_mask:0xf
	v_mov_b32_dpp v226, v169 row_shl:1 row_mask:0xf bank_mask:0xf
	v_cndmask_b32_e64 v208, v208, v166, s[48:49]
	v_cndmask_b32_e64 v209, v209, v167, s[48:49]
	v_cndmask_b32_e64 v210, v210, v168, s[48:49]
	v_cndmask_b32_e64 v211, v211, v169, s[48:49]
	v_cndmask_b32_e64 v204, v204, v223, s[46:47]
	v_cndmask_b32_e64 v205, v205, v224, s[46:47]
	v_cndmask_b32_e64 v206, v206, v225, s[46:47]
	v_cndmask_b32_e64 v207, v207, v226, s[46:47]
	s_mov_b64 exec, s[48:49]
	v_add_u32_e32 v222, 0xb2c00, v190
	global_load_dwordx4 v[166:169], v222, s[16:17]
	s_mov_b64 exec, -1
	v_pk_fma_f32 v[216:217], v[150:151], v[204:205], v[216:217]
	v_pk_fma_f32 v[218:219], v[152:153], v[206:207], v[218:219]
	v_pk_fma_f32 v[216:217], v[146:147], v[208:209], v[216:217]
	v_pk_fma_f32 v[218:219], v[148:149], v[210:211], v[218:219]
	v_mul_f32_e32 v204, 0xbfb8aa3b, v216
	v_mul_f32_e32 v205, 0xbfb8aa3b, v217
	v_mul_f32_e32 v206, 0xbfb8aa3b, v218
	v_mul_f32_e32 v207, 0xbfb8aa3b, v219
	v_exp_f32_e32 v204, v204
	v_exp_f32_e32 v205, v205
	v_exp_f32_e32 v206, v206
	v_exp_f32_e32 v207, v207
	v_add_f32_e32 v204, 1.0, v204
	v_add_f32_e32 v205, 1.0, v205
	v_add_f32_e32 v206, 1.0, v206
	v_add_f32_e32 v207, 1.0, v207
	v_rcp_f32_e32 v204, v204
	v_rcp_f32_e32 v205, v205
	v_rcp_f32_e32 v206, v206
	v_rcp_f32_e32 v207, v207
	v_mul_f32_e32 v204, v216, v204
	v_mul_f32_e32 v205, v217, v205
	v_mul_f32_e32 v206, v218, v206
	v_mul_f32_e32 v207, v219, v207
	v_mul_f32_e32 v204, v212, v204
	v_mul_f32_e32 v205, v213, v205
	v_mul_f32_e32 v206, v214, v206
	v_mul_f32_e32 v207, v215, v207
	v_cvt_pk_bf16_f32 v220, v204, v205
	v_cvt_pk_bf16_f32 v221, v206, v207
	v_add_u32_e32 v222, 0x2c000, v231
	global_store_dwordx2 v222, v[220:221], s[36:37]
	v_pk_fma_f32 v[212:213], v[138:139], v[102:103], v[142:143]
	v_pk_fma_f32 v[214:215], v[140:141], v[104:105], v[144:145]
	s_nop 2
	v_mov_b32_dpp v204, v102 row_shr:1 row_mask:0xf bank_mask:0xf
	v_mov_b32_dpp v208, v102 row_shr:2 row_mask:0xf bank_mask:0xf
	v_mov_b32_dpp v205, v103 row_shr:1 row_mask:0xf bank_mask:0xf
	v_mov_b32_dpp v209, v103 row_shr:2 row_mask:0xf bank_mask:0xf
	v_mov_b32_dpp v206, v104 row_shr:1 row_mask:0xf bank_mask:0xf
	v_mov_b32_dpp v210, v104 row_shr:2 row_mask:0xf bank_mask:0xf
	v_mov_b32_dpp v207, v105 row_shr:1 row_mask:0xf bank_mask:0xf
	v_mov_b32_dpp v211, v105 row_shr:2 row_mask:0xf bank_mask:0xf
	s_waitcnt vmcnt(5)
	v_mov_b32_dpp v223, v170 row_shl:1 row_mask:0xf bank_mask:0xf
	v_mov_b32_dpp v224, v171 row_shl:1 row_mask:0xf bank_mask:0xf
	v_mov_b32_dpp v225, v172 row_shl:1 row_mask:0xf bank_mask:0xf
	v_mov_b32_dpp v226, v173 row_shl:1 row_mask:0xf bank_mask:0xf
	v_cndmask_b32_e64 v208, v208, v170, s[48:49]
	v_cndmask_b32_e64 v209, v209, v171, s[48:49]
	v_cndmask_b32_e64 v210, v210, v172, s[48:49]
	v_cndmask_b32_e64 v211, v211, v173, s[48:49]
	v_cndmask_b32_e64 v204, v204, v223, s[46:47]
	v_cndmask_b32_e64 v205, v205, v224, s[46:47]
	v_cndmask_b32_e64 v206, v206, v225, s[46:47]
	v_cndmask_b32_e64 v207, v207, v226, s[46:47]
	s_mov_b64 exec, s[48:49]
	v_add_u32_e32 v222, 0xc6000, v190
	global_load_dwordx4 v[170:173], v222, s[16:17]
	s_mov_b64 exec, -1
	v_pk_fma_f32 v[212:213], v[134:135], v[204:205], v[212:213]
	v_pk_fma_f32 v[214:215], v[136:137], v[206:207], v[214:215]
	v_pk_fma_f32 v[212:213], v[130:131], v[208:209], v[212:213]
	v_pk_fma_f32 v[214:215], v[132:133], v[210:211], v[214:215]
	v_pk_fma_f32 v[216:217], v[154:155], v[98:99], v[158:159]
	v_pk_fma_f32 v[218:219], v[156:157], v[100:101], v[160:161]
	s_nop 2
	v_mov_b32_dpp v204, v98 row_shr:1 row_mask:0xf bank_mask:0xf
	v_mov_b32_dpp v208, v98 row_shr:2 row_mask:0xf bank_mask:0xf
	v_mov_b32_dpp v205, v99 row_shr:1 row_mask:0xf bank_mask:0xf
	v_mov_b32_dpp v209, v99 row_shr:2 row_mask:0xf bank_mask:0xf
	v_mov_b32_dpp v206, v100 row_shr:1 row_mask:0xf bank_mask:0xf
	v_mov_b32_dpp v210, v100 row_shr:2 row_mask:0xf bank_mask:0xf
	v_mov_b32_dpp v207, v101 row_shr:1 row_mask:0xf bank_mask:0xf
	v_mov_b32_dpp v211, v101 row_shr:2 row_mask:0xf bank_mask:0xf
	s_waitcnt vmcnt(5)
	v_mov_b32_dpp v223, v174 row_shl:1 row_mask:0xf bank_mask:0xf
	v_mov_b32_dpp v224, v175 row_shl:1 row_mask:0xf bank_mask:0xf
	v_mov_b32_dpp v225, v176 row_shl:1 row_mask:0xf bank_mask:0xf
	v_mov_b32_dpp v226, v177 row_shl:1 row_mask:0xf bank_mask:0xf
	v_cndmask_b32_e64 v208, v208, v174, s[48:49]
	v_cndmask_b32_e64 v209, v209, v175, s[48:49]
	v_cndmask_b32_e64 v210, v210, v176, s[48:49]
	v_cndmask_b32_e64 v211, v211, v177, s[48:49]
	v_cndmask_b32_e64 v204, v204, v223, s[46:47]
	v_cndmask_b32_e64 v205, v205, v224, s[46:47]
	v_cndmask_b32_e64 v206, v206, v225, s[46:47]
	v_cndmask_b32_e64 v207, v207, v226, s[46:47]
	s_mov_b64 exec, s[48:49]
	v_add_u32_e32 v222, 0xc8c00, v190
	global_load_dwordx4 v[174:177], v222, s[16:17]
	s_mov_b64 exec, -1
	v_pk_fma_f32 v[216:217], v[150:151], v[204:205], v[216:217]
	v_pk_fma_f32 v[218:219], v[152:153], v[206:207], v[218:219]
	v_pk_fma_f32 v[216:217], v[146:147], v[208:209], v[216:217]
	v_pk_fma_f32 v[218:219], v[148:149], v[210:211], v[218:219]
	v_mul_f32_e32 v204, 0xbfb8aa3b, v216
	v_mul_f32_e32 v205, 0xbfb8aa3b, v217
	v_mul_f32_e32 v206, 0xbfb8aa3b, v218
	v_mul_f32_e32 v207, 0xbfb8aa3b, v219
	v_exp_f32_e32 v204, v204
	v_exp_f32_e32 v205, v205
	v_exp_f32_e32 v206, v206
	v_exp_f32_e32 v207, v207
	v_add_f32_e32 v204, 1.0, v204
	v_add_f32_e32 v205, 1.0, v205
	v_add_f32_e32 v206, 1.0, v206
	v_add_f32_e32 v207, 1.0, v207
	v_rcp_f32_e32 v204, v204
	v_rcp_f32_e32 v205, v205
	v_rcp_f32_e32 v206, v206
	v_rcp_f32_e32 v207, v207
	v_mul_f32_e32 v204, v216, v204
	v_mul_f32_e32 v205, v217, v205
	v_mul_f32_e32 v206, v218, v206
	v_mul_f32_e32 v207, v219, v207
	v_mul_f32_e32 v204, v212, v204
	v_mul_f32_e32 v205, v213, v205
	v_mul_f32_e32 v206, v214, v206
	v_mul_f32_e32 v207, v215, v207
	v_cvt_pk_bf16_f32 v220, v204, v205
	v_cvt_pk_bf16_f32 v221, v206, v207
	v_add_u32_e32 v222, 0x42000, v231
	global_store_dwordx2 v222, v[220:221], s[36:37]
	global_load_dwordx4 v[98:101], v232, s[40:41] offset:16
	v_add_u32_e32 v204, 0x5800, v232
	global_load_dwordx4 v[102:105], v204, s[40:41] offset:16
	v_add_u32_e32 v205, 0xb000, v232
	global_load_dwordx4 v[106:109], v205, s[40:41] offset:16
	global_load_dwordx4 v[110:113], v232, s[42:43] offset:16
	v_add_u32_e32 v206, 0x2c00, v232
	global_load_dwordx4 v[114:117], v206, s[40:41] offset:16
	v_add_u32_e32 v207, 0x8400, v232
	global_load_dwordx4 v[118:121], v207, s[40:41] offset:16
	v_add_u32_e32 v208, 0xdc00, v232
	global_load_dwordx4 v[122:125], v208, s[40:41] offset:16
	v_add_u32_e32 v209, 0x2c00, v232
	global_load_dwordx4 v[126:129], v209, s[42:43] offset:16
	s_mov_b64 exec, s[50:51]
	v_add_u32_e32 v223, 0x10, v235
	global_store_dwordx4 v223, v[62:65], s[44:45]
	v_add_u32_e32 v224, 0x2c10, v235
	global_store_dwordx4 v224, v[58:61], s[44:45]
	v_add_u32_e32 v225, 0x16010, v235
	global_store_dwordx4 v225, v[54:57], s[44:45]
	v_add_u32_e32 v226, 0x18c10, v235
	global_store_dwordx4 v226, v[50:53], s[44:45]
	v_add_u32_e32 v223, 0x2c010, v235
	global_store_dwordx4 v223, v[46:49], s[44:45]
	v_add_u32_e32 v224, 0x2ec10, v235
	global_store_dwordx4 v224, v[42:45], s[44:45]
	v_add_u32_e32 v225, 0x42010, v235
	global_store_dwordx4 v225, v[38:41], s[44:45]
	v_add_u32_e32 v226, 0x44c10, v235
	global_store_dwordx4 v226, v[34:37], s[44:45]
	v_add_u32_e32 v223, 0xb0010, v235
	global_store_dwordx4 v223, v[30:33], s[44:45]
	v_add_u32_e32 v224, 0xb2c10, v235
	global_store_dwordx4 v224, v[26:29], s[44:45]
	v_add_u32_e32 v225, 0xc6010, v235
	global_store_dwordx4 v225, v[22:25], s[44:45]
	v_add_u32_e32 v226, 0xc8c10, v235
	global_store_dwordx4 v226, v[18:21], s[44:45]
	v_add_u32_e32 v223, 0xdc010, v235
	global_store_dwordx4 v223, v[14:17], s[44:45]
	v_add_u32_e32 v224, 0xdec10, v235
	global_store_dwordx4 v224, v[10:13], s[44:45]
	v_add_u32_e32 v225, 0xf2010, v235
	global_store_dwordx4 v225, v[6:9], s[44:45]
	v_add_u32_e32 v226, 0xf4c10, v235
	global_store_dwordx4 v226, v[2:5], s[44:45]
	s_mov_b64 exec, -1
	v_pk_fma_f32 v[212:213], v[138:139], v[94:95], v[142:143]
	v_pk_fma_f32 v[214:215], v[140:141], v[96:97], v[144:145]
	s_nop 2
	v_mov_b32_dpp v204, v94 row_shr:1 row_mask:0xf bank_mask:0xf
	v_mov_b32_dpp v208, v94 row_shr:2 row_mask:0xf bank_mask:0xf
	v_mov_b32_dpp v205, v95 row_shr:1 row_mask:0xf bank_mask:0xf
	v_mov_b32_dpp v209, v95 row_shr:2 row_mask:0xf bank_mask:0xf
	v_mov_b32_dpp v206, v96 row_shr:1 row_mask:0xf bank_mask:0xf
	v_mov_b32_dpp v210, v96 row_shr:2 row_mask:0xf bank_mask:0xf
	v_mov_b32_dpp v207, v97 row_shr:1 row_mask:0xf bank_mask:0xf
	v_mov_b32_dpp v211, v97 row_shr:2 row_mask:0xf bank_mask:0xf
	s_waitcnt vmcnt(29)
	v_mov_b32_dpp v223, v162 row_shl:1 row_mask:0xf bank_mask:0xf
	v_mov_b32_dpp v224, v163 row_shl:1 row_mask:0xf bank_mask:0xf
	v_mov_b32_dpp v225, v164 row_shl:1 row_mask:0xf bank_mask:0xf
	v_mov_b32_dpp v226, v165 row_shl:1 row_mask:0xf bank_mask:0xf
	v_cndmask_b32_e64 v208, v208, v162, s[48:49]
	v_cndmask_b32_e64 v209, v209, v163, s[48:49]
	v_cndmask_b32_e64 v210, v210, v164, s[48:49]
	v_cndmask_b32_e64 v211, v211, v165, s[48:49]
	v_cndmask_b32_e64 v204, v204, v223, s[46:47]
	v_cndmask_b32_e64 v205, v205, v224, s[46:47]
	v_cndmask_b32_e64 v206, v206, v225, s[46:47]
	v_cndmask_b32_e64 v207, v207, v226, s[46:47]
	s_mov_b64 exec, s[48:49]
	v_add_u32_e32 v222, 0xdc000, v190
	global_load_dwordx4 v[162:165], v222, s[16:17]
	s_mov_b64 exec, -1
	v_pk_fma_f32 v[212:213], v[134:135], v[204:205], v[212:213]
	v_pk_fma_f32 v[214:215], v[136:137], v[206:207], v[214:215]
	v_pk_fma_f32 v[212:213], v[130:131], v[208:209], v[212:213]
	v_pk_fma_f32 v[214:215], v[132:133], v[210:211], v[214:215]
	v_pk_fma_f32 v[216:217], v[154:155], v[90:91], v[158:159]
	v_pk_fma_f32 v[218:219], v[156:157], v[92:93], v[160:161]
	s_nop 2
	v_mov_b32_dpp v204, v90 row_shr:1 row_mask:0xf bank_mask:0xf
	v_mov_b32_dpp v208, v90 row_shr:2 row_mask:0xf bank_mask:0xf
	v_mov_b32_dpp v205, v91 row_shr:1 row_mask:0xf bank_mask:0xf
	v_mov_b32_dpp v209, v91 row_shr:2 row_mask:0xf bank_mask:0xf
	v_mov_b32_dpp v206, v92 row_shr:1 row_mask:0xf bank_mask:0xf
	v_mov_b32_dpp v210, v92 row_shr:2 row_mask:0xf bank_mask:0xf
	v_mov_b32_dpp v207, v93 row_shr:1 row_mask:0xf bank_mask:0xf
	v_mov_b32_dpp v211, v93 row_shr:2 row_mask:0xf bank_mask:0xf
	s_waitcnt vmcnt(29)
	v_mov_b32_dpp v223, v166 row_shl:1 row_mask:0xf bank_mask:0xf
	v_mov_b32_dpp v224, v167 row_shl:1 row_mask:0xf bank_mask:0xf
	v_mov_b32_dpp v225, v168 row_shl:1 row_mask:0xf bank_mask:0xf
	v_mov_b32_dpp v226, v169 row_shl:1 row_mask:0xf bank_mask:0xf
	v_cndmask_b32_e64 v208, v208, v166, s[48:49]
	v_cndmask_b32_e64 v209, v209, v167, s[48:49]
	v_cndmask_b32_e64 v210, v210, v168, s[48:49]
	v_cndmask_b32_e64 v211, v211, v169, s[48:49]
	v_cndmask_b32_e64 v204, v204, v223, s[46:47]
	v_cndmask_b32_e64 v205, v205, v224, s[46:47]
	v_cndmask_b32_e64 v206, v206, v225, s[46:47]
	v_cndmask_b32_e64 v207, v207, v226, s[46:47]
	s_mov_b64 exec, s[48:49]
	v_add_u32_e32 v222, 0xdec00, v190
	global_load_dwordx4 v[166:169], v222, s[16:17]
	s_mov_b64 exec, -1
	v_pk_fma_f32 v[216:217], v[150:151], v[204:205], v[216:217]
	v_pk_fma_f32 v[218:219], v[152:153], v[206:207], v[218:219]
	v_pk_fma_f32 v[216:217], v[146:147], v[208:209], v[216:217]
	v_pk_fma_f32 v[218:219], v[148:149], v[210:211], v[218:219]
	v_mul_f32_e32 v204, 0xbfb8aa3b, v216
	v_mul_f32_e32 v205, 0xbfb8aa3b, v217
	v_mul_f32_e32 v206, 0xbfb8aa3b, v218
	v_mul_f32_e32 v207, 0xbfb8aa3b, v219
	v_exp_f32_e32 v204, v204
	v_exp_f32_e32 v205, v205
	v_exp_f32_e32 v206, v206
	v_exp_f32_e32 v207, v207
	v_add_f32_e32 v204, 1.0, v204
	v_add_f32_e32 v205, 1.0, v205
	v_add_f32_e32 v206, 1.0, v206
	v_add_f32_e32 v207, 1.0, v207
	v_rcp_f32_e32 v204, v204
	v_rcp_f32_e32 v205, v205
	v_rcp_f32_e32 v206, v206
	v_rcp_f32_e32 v207, v207
	v_mul_f32_e32 v204, v216, v204
	v_mul_f32_e32 v205, v217, v205
	v_mul_f32_e32 v206, v218, v206
	v_mul_f32_e32 v207, v219, v207
	v_mul_f32_e32 v204, v212, v204
	v_mul_f32_e32 v205, v213, v205
	v_mul_f32_e32 v206, v214, v206
	v_mul_f32_e32 v207, v215, v207
	v_cvt_pk_bf16_f32 v94, v204, v205
	v_cvt_pk_bf16_f32 v95, v206, v207
	v_pk_fma_f32 v[212:213], v[138:139], v[86:87], v[142:143]
	v_pk_fma_f32 v[214:215], v[140:141], v[88:89], v[144:145]
	s_nop 2
	v_mov_b32_dpp v204, v86 row_shr:1 row_mask:0xf bank_mask:0xf
	v_mov_b32_dpp v208, v86 row_shr:2 row_mask:0xf bank_mask:0xf
	v_mov_b32_dpp v205, v87 row_shr:1 row_mask:0xf bank_mask:0xf
	v_mov_b32_dpp v209, v87 row_shr:2 row_mask:0xf bank_mask:0xf
	v_mov_b32_dpp v206, v88 row_shr:1 row_mask:0xf bank_mask:0xf
	v_mov_b32_dpp v210, v88 row_shr:2 row_mask:0xf bank_mask:0xf
	v_mov_b32_dpp v207, v89 row_shr:1 row_mask:0xf bank_mask:0xf
	v_mov_b32_dpp v211, v89 row_shr:2 row_mask:0xf bank_mask:0xf
	s_waitcnt vmcnt(28)
	v_mov_b32_dpp v223, v170 row_shl:1 row_mask:0xf bank_mask:0xf
	v_mov_b32_dpp v224, v171 row_shl:1 row_mask:0xf bank_mask:0xf
	v_mov_b32_dpp v225, v172 row_shl:1 row_mask:0xf bank_mask:0xf
	v_mov_b32_dpp v226, v173 row_shl:1 row_mask:0xf bank_mask:0xf
	v_cndmask_b32_e64 v208, v208, v170, s[48:49]
	v_cndmask_b32_e64 v209, v209, v171, s[48:49]
	v_cndmask_b32_e64 v210, v210, v172, s[48:49]
	v_cndmask_b32_e64 v211, v211, v173, s[48:49]
	v_cndmask_b32_e64 v204, v204, v223, s[46:47]
	v_cndmask_b32_e64 v205, v205, v224, s[46:47]
	v_cndmask_b32_e64 v206, v206, v225, s[46:47]
	v_cndmask_b32_e64 v207, v207, v226, s[46:47]
	s_mov_b64 exec, s[48:49]
	v_add_u32_e32 v222, 0xf2000, v190
	global_load_dwordx4 v[170:173], v222, s[16:17]
	s_mov_b64 exec, -1
	v_pk_fma_f32 v[212:213], v[134:135], v[204:205], v[212:213]
	v_pk_fma_f32 v[214:215], v[136:137], v[206:207], v[214:215]
	v_pk_fma_f32 v[212:213], v[130:131], v[208:209], v[212:213]
	v_pk_fma_f32 v[214:215], v[132:133], v[210:211], v[214:215]
	v_pk_fma_f32 v[216:217], v[154:155], v[82:83], v[158:159]
	v_pk_fma_f32 v[218:219], v[156:157], v[84:85], v[160:161]
	s_nop 2
	v_mov_b32_dpp v204, v82 row_shr:1 row_mask:0xf bank_mask:0xf
	v_mov_b32_dpp v208, v82 row_shr:2 row_mask:0xf bank_mask:0xf
	v_mov_b32_dpp v205, v83 row_shr:1 row_mask:0xf bank_mask:0xf
	v_mov_b32_dpp v209, v83 row_shr:2 row_mask:0xf bank_mask:0xf
	v_mov_b32_dpp v206, v84 row_shr:1 row_mask:0xf bank_mask:0xf
	v_mov_b32_dpp v210, v84 row_shr:2 row_mask:0xf bank_mask:0xf
	v_mov_b32_dpp v207, v85 row_shr:1 row_mask:0xf bank_mask:0xf
	v_mov_b32_dpp v211, v85 row_shr:2 row_mask:0xf bank_mask:0xf
	s_waitcnt vmcnt(28)
	v_mov_b32_dpp v223, v174 row_shl:1 row_mask:0xf bank_mask:0xf
	v_mov_b32_dpp v224, v175 row_shl:1 row_mask:0xf bank_mask:0xf
	v_mov_b32_dpp v225, v176 row_shl:1 row_mask:0xf bank_mask:0xf
	v_mov_b32_dpp v226, v177 row_shl:1 row_mask:0xf bank_mask:0xf
	v_cndmask_b32_e64 v208, v208, v174, s[48:49]
	v_cndmask_b32_e64 v209, v209, v175, s[48:49]
	v_cndmask_b32_e64 v210, v210, v176, s[48:49]
	v_cndmask_b32_e64 v211, v211, v177, s[48:49]
	v_cndmask_b32_e64 v204, v204, v223, s[46:47]
	v_cndmask_b32_e64 v205, v205, v224, s[46:47]
	v_cndmask_b32_e64 v206, v206, v225, s[46:47]
	v_cndmask_b32_e64 v207, v207, v226, s[46:47]
	s_mov_b64 exec, s[48:49]
	v_add_u32_e32 v222, 0xf4c00, v190
	global_load_dwordx4 v[174:177], v222, s[16:17]
	s_mov_b64 exec, -1
	v_pk_fma_f32 v[216:217], v[150:151], v[204:205], v[216:217]
	v_pk_fma_f32 v[218:219], v[152:153], v[206:207], v[218:219]
	v_pk_fma_f32 v[216:217], v[146:147], v[208:209], v[216:217]
	v_pk_fma_f32 v[218:219], v[148:149], v[210:211], v[218:219]
	v_mul_f32_e32 v204, 0xbfb8aa3b, v216
	v_mul_f32_e32 v205, 0xbfb8aa3b, v217
	v_mul_f32_e32 v206, 0xbfb8aa3b, v218
	v_mul_f32_e32 v207, 0xbfb8aa3b, v219
	v_exp_f32_e32 v204, v204
	v_exp_f32_e32 v205, v205
	v_exp_f32_e32 v206, v206
	v_exp_f32_e32 v207, v207
	v_add_f32_e32 v204, 1.0, v204
	v_add_f32_e32 v205, 1.0, v205
	v_add_f32_e32 v206, 1.0, v206
	v_add_f32_e32 v207, 1.0, v207
	v_rcp_f32_e32 v204, v204
	v_rcp_f32_e32 v205, v205
	v_rcp_f32_e32 v206, v206
	v_rcp_f32_e32 v207, v207
	v_mul_f32_e32 v204, v216, v204
	v_mul_f32_e32 v205, v217, v205
	v_mul_f32_e32 v206, v218, v206
	v_mul_f32_e32 v207, v219, v207
	v_mul_f32_e32 v204, v212, v204
	v_mul_f32_e32 v205, v213, v205
	v_mul_f32_e32 v206, v214, v206
	v_mul_f32_e32 v207, v215, v207
	v_cvt_pk_bf16_f32 v86, v204, v205
	v_cvt_pk_bf16_f32 v87, v206, v207
	v_pk_fma_f32 v[212:213], v[138:139], v[78:79], v[142:143]
	v_pk_fma_f32 v[214:215], v[140:141], v[80:81], v[144:145]
	s_nop 2
	v_mov_b32_dpp v204, v78 row_shr:1 row_mask:0xf bank_mask:0xf
	v_mov_b32_dpp v208, v78 row_shr:2 row_mask:0xf bank_mask:0xf
	v_mov_b32_dpp v205, v79 row_shr:1 row_mask:0xf bank_mask:0xf
	v_mov_b32_dpp v209, v79 row_shr:2 row_mask:0xf bank_mask:0xf
	v_mov_b32_dpp v206, v80 row_shr:1 row_mask:0xf bank_mask:0xf
	v_mov_b32_dpp v210, v80 row_shr:2 row_mask:0xf bank_mask:0xf
	v_mov_b32_dpp v207, v81 row_shr:1 row_mask:0xf bank_mask:0xf
	v_mov_b32_dpp v211, v81 row_shr:2 row_mask:0xf bank_mask:0xf
	s_waitcnt vmcnt(3)
	v_mov_b32_dpp v223, v162 row_shl:1 row_mask:0xf bank_mask:0xf
	v_mov_b32_dpp v224, v163 row_shl:1 row_mask:0xf bank_mask:0xf
	v_mov_b32_dpp v225, v164 row_shl:1 row_mask:0xf bank_mask:0xf
	v_mov_b32_dpp v226, v165 row_shl:1 row_mask:0xf bank_mask:0xf
	v_cndmask_b32_e64 v208, v208, v162, s[48:49]
	v_cndmask_b32_e64 v209, v209, v163, s[48:49]
	v_cndmask_b32_e64 v210, v210, v164, s[48:49]
	v_cndmask_b32_e64 v211, v211, v165, s[48:49]
	v_cndmask_b32_e64 v204, v204, v223, s[46:47]
	v_cndmask_b32_e64 v205, v205, v224, s[46:47]
	v_cndmask_b32_e64 v206, v206, v225, s[46:47]
	v_cndmask_b32_e64 v207, v207, v226, s[46:47]
	s_mov_b64 exec, s[48:49]
	global_load_dwordx4 v[162:165], v190, s[16:17] offset:16
	s_mov_b64 exec, -1
	v_pk_fma_f32 v[212:213], v[134:135], v[204:205], v[212:213]
	v_pk_fma_f32 v[214:215], v[136:137], v[206:207], v[214:215]
	v_pk_fma_f32 v[212:213], v[130:131], v[208:209], v[212:213]
	v_pk_fma_f32 v[214:215], v[132:133], v[210:211], v[214:215]
	v_pk_fma_f32 v[216:217], v[154:155], v[74:75], v[158:159]
	v_pk_fma_f32 v[218:219], v[156:157], v[76:77], v[160:161]
	s_nop 2
	v_mov_b32_dpp v204, v74 row_shr:1 row_mask:0xf bank_mask:0xf
	v_mov_b32_dpp v208, v74 row_shr:2 row_mask:0xf bank_mask:0xf
	v_mov_b32_dpp v205, v75 row_shr:1 row_mask:0xf bank_mask:0xf
	v_mov_b32_dpp v209, v75 row_shr:2 row_mask:0xf bank_mask:0xf
	v_mov_b32_dpp v206, v76 row_shr:1 row_mask:0xf bank_mask:0xf
	v_mov_b32_dpp v210, v76 row_shr:2 row_mask:0xf bank_mask:0xf
	v_mov_b32_dpp v207, v77 row_shr:1 row_mask:0xf bank_mask:0xf
	v_mov_b32_dpp v211, v77 row_shr:2 row_mask:0xf bank_mask:0xf
	s_waitcnt vmcnt(3)
	v_mov_b32_dpp v223, v166 row_shl:1 row_mask:0xf bank_mask:0xf
	v_mov_b32_dpp v224, v167 row_shl:1 row_mask:0xf bank_mask:0xf
	v_mov_b32_dpp v225, v168 row_shl:1 row_mask:0xf bank_mask:0xf
	v_mov_b32_dpp v226, v169 row_shl:1 row_mask:0xf bank_mask:0xf
	v_cndmask_b32_e64 v208, v208, v166, s[48:49]
	v_cndmask_b32_e64 v209, v209, v167, s[48:49]
	v_cndmask_b32_e64 v210, v210, v168, s[48:49]
	v_cndmask_b32_e64 v211, v211, v169, s[48:49]
	v_cndmask_b32_e64 v204, v204, v223, s[46:47]
	v_cndmask_b32_e64 v205, v205, v224, s[46:47]
	v_cndmask_b32_e64 v206, v206, v225, s[46:47]
	v_cndmask_b32_e64 v207, v207, v226, s[46:47]
	s_mov_b64 exec, s[48:49]
	v_add_u32_e32 v222, 0x2c00, v190
	global_load_dwordx4 v[166:169], v222, s[16:17] offset:16
	s_mov_b64 exec, -1
	v_pk_fma_f32 v[216:217], v[150:151], v[204:205], v[216:217]
	v_pk_fma_f32 v[218:219], v[152:153], v[206:207], v[218:219]
	v_pk_fma_f32 v[216:217], v[146:147], v[208:209], v[216:217]
	v_pk_fma_f32 v[218:219], v[148:149], v[210:211], v[218:219]
	v_mul_f32_e32 v204, 0xbfb8aa3b, v216
	v_mul_f32_e32 v205, 0xbfb8aa3b, v217
	v_mul_f32_e32 v206, 0xbfb8aa3b, v218
	v_mul_f32_e32 v207, 0xbfb8aa3b, v219
	v_exp_f32_e32 v204, v204
	v_exp_f32_e32 v205, v205
	v_exp_f32_e32 v206, v206
	v_exp_f32_e32 v207, v207
	v_add_f32_e32 v204, 1.0, v204
	v_add_f32_e32 v205, 1.0, v205
	v_add_f32_e32 v206, 1.0, v206
	v_add_f32_e32 v207, 1.0, v207
	v_rcp_f32_e32 v204, v204
	v_rcp_f32_e32 v205, v205
	v_rcp_f32_e32 v206, v206
	v_rcp_f32_e32 v207, v207
	v_mul_f32_e32 v204, v216, v204
	v_mul_f32_e32 v205, v217, v205
	v_mul_f32_e32 v206, v218, v206
	v_mul_f32_e32 v207, v219, v207
	v_mul_f32_e32 v204, v212, v204
	v_mul_f32_e32 v205, v213, v205
	v_mul_f32_e32 v206, v214, v206
	v_mul_f32_e32 v207, v215, v207
	v_cvt_pk_bf16_f32 v78, v204, v205
	v_cvt_pk_bf16_f32 v79, v206, v207
	v_pk_fma_f32 v[212:213], v[138:139], v[70:71], v[142:143]
	v_pk_fma_f32 v[214:215], v[140:141], v[72:73], v[144:145]
	s_nop 2
	v_mov_b32_dpp v204, v70 row_shr:1 row_mask:0xf bank_mask:0xf
	v_mov_b32_dpp v208, v70 row_shr:2 row_mask:0xf bank_mask:0xf
	v_mov_b32_dpp v205, v71 row_shr:1 row_mask:0xf bank_mask:0xf
	v_mov_b32_dpp v209, v71 row_shr:2 row_mask:0xf bank_mask:0xf
	v_mov_b32_dpp v206, v72 row_shr:1 row_mask:0xf bank_mask:0xf
	v_mov_b32_dpp v210, v72 row_shr:2 row_mask:0xf bank_mask:0xf
	v_mov_b32_dpp v207, v73 row_shr:1 row_mask:0xf bank_mask:0xf
	v_mov_b32_dpp v211, v73 row_shr:2 row_mask:0xf bank_mask:0xf
	s_waitcnt vmcnt(3)
	v_mov_b32_dpp v223, v170 row_shl:1 row_mask:0xf bank_mask:0xf
	v_mov_b32_dpp v224, v171 row_shl:1 row_mask:0xf bank_mask:0xf
	v_mov_b32_dpp v225, v172 row_shl:1 row_mask:0xf bank_mask:0xf
	v_mov_b32_dpp v226, v173 row_shl:1 row_mask:0xf bank_mask:0xf
	v_cndmask_b32_e64 v208, v208, v170, s[48:49]
	v_cndmask_b32_e64 v209, v209, v171, s[48:49]
	v_cndmask_b32_e64 v210, v210, v172, s[48:49]
	v_cndmask_b32_e64 v211, v211, v173, s[48:49]
	v_cndmask_b32_e64 v204, v204, v223, s[46:47]
	v_cndmask_b32_e64 v205, v205, v224, s[46:47]
	v_cndmask_b32_e64 v206, v206, v225, s[46:47]
	v_cndmask_b32_e64 v207, v207, v226, s[46:47]
	s_mov_b64 exec, s[48:49]
	v_add_u32_e32 v222, 0x16000, v190
	global_load_dwordx4 v[170:173], v222, s[16:17] offset:16
	s_mov_b64 exec, -1
	v_pk_fma_f32 v[212:213], v[134:135], v[204:205], v[212:213]
	v_pk_fma_f32 v[214:215], v[136:137], v[206:207], v[214:215]
	v_pk_fma_f32 v[212:213], v[130:131], v[208:209], v[212:213]
	v_pk_fma_f32 v[214:215], v[132:133], v[210:211], v[214:215]
	v_pk_fma_f32 v[216:217], v[154:155], v[66:67], v[158:159]
	v_pk_fma_f32 v[218:219], v[156:157], v[68:69], v[160:161]
	s_nop 2
	v_mov_b32_dpp v204, v66 row_shr:1 row_mask:0xf bank_mask:0xf
	v_mov_b32_dpp v208, v66 row_shr:2 row_mask:0xf bank_mask:0xf
	v_mov_b32_dpp v205, v67 row_shr:1 row_mask:0xf bank_mask:0xf
	v_mov_b32_dpp v209, v67 row_shr:2 row_mask:0xf bank_mask:0xf
	v_mov_b32_dpp v206, v68 row_shr:1 row_mask:0xf bank_mask:0xf
	v_mov_b32_dpp v210, v68 row_shr:2 row_mask:0xf bank_mask:0xf
	v_mov_b32_dpp v207, v69 row_shr:1 row_mask:0xf bank_mask:0xf
	v_mov_b32_dpp v211, v69 row_shr:2 row_mask:0xf bank_mask:0xf
	s_waitcnt vmcnt(3)
	v_mov_b32_dpp v223, v174 row_shl:1 row_mask:0xf bank_mask:0xf
	v_mov_b32_dpp v224, v175 row_shl:1 row_mask:0xf bank_mask:0xf
	v_mov_b32_dpp v225, v176 row_shl:1 row_mask:0xf bank_mask:0xf
	v_mov_b32_dpp v226, v177 row_shl:1 row_mask:0xf bank_mask:0xf
	v_cndmask_b32_e64 v208, v208, v174, s[48:49]
	v_cndmask_b32_e64 v209, v209, v175, s[48:49]
	v_cndmask_b32_e64 v210, v210, v176, s[48:49]
	v_cndmask_b32_e64 v211, v211, v177, s[48:49]
	v_cndmask_b32_e64 v204, v204, v223, s[46:47]
	v_cndmask_b32_e64 v205, v205, v224, s[46:47]
	v_cndmask_b32_e64 v206, v206, v225, s[46:47]
	v_cndmask_b32_e64 v207, v207, v226, s[46:47]
	s_mov_b64 exec, s[48:49]
	v_add_u32_e32 v222, 0x18c00, v190
	global_load_dwordx4 v[174:177], v222, s[16:17] offset:16
	s_mov_b64 exec, -1
	v_pk_fma_f32 v[216:217], v[150:151], v[204:205], v[216:217]
	v_pk_fma_f32 v[218:219], v[152:153], v[206:207], v[218:219]
	v_pk_fma_f32 v[216:217], v[146:147], v[208:209], v[216:217]
	v_pk_fma_f32 v[218:219], v[148:149], v[210:211], v[218:219]
	v_mul_f32_e32 v204, 0xbfb8aa3b, v216
	v_mul_f32_e32 v205, 0xbfb8aa3b, v217
	v_mul_f32_e32 v206, 0xbfb8aa3b, v218
	v_mul_f32_e32 v207, 0xbfb8aa3b, v219
	v_exp_f32_e32 v204, v204
	v_exp_f32_e32 v205, v205
	v_exp_f32_e32 v206, v206
	v_exp_f32_e32 v207, v207
	v_add_f32_e32 v204, 1.0, v204
	v_add_f32_e32 v205, 1.0, v205
	v_add_f32_e32 v206, 1.0, v206
	v_add_f32_e32 v207, 1.0, v207
	v_rcp_f32_e32 v204, v204
	v_rcp_f32_e32 v205, v205
	v_rcp_f32_e32 v206, v206
	v_rcp_f32_e32 v207, v207
	v_mul_f32_e32 v204, v216, v204
	v_mul_f32_e32 v205, v217, v205
	v_mul_f32_e32 v206, v218, v206
	v_mul_f32_e32 v207, v219, v207
	v_mul_f32_e32 v204, v212, v204
	v_mul_f32_e32 v205, v213, v205
	v_mul_f32_e32 v206, v214, v206
	v_mul_f32_e32 v207, v215, v207
	v_cvt_pk_bf16_f32 v70, v204, v205
	v_cvt_pk_bf16_f32 v71, v206, v207
	s_waitcnt vmcnt(24)
	v_pk_fma_f32 v[212:213], v[106:107], v[62:63], v[110:111]
	v_pk_fma_f32 v[214:215], v[108:109], v[64:65], v[112:113]
	s_nop 2
	v_mov_b32_dpp v204, v62 row_shr:1 row_mask:0xf bank_mask:0xf
	v_mov_b32_dpp v208, v62 row_shr:2 row_mask:0xf bank_mask:0xf
	v_mov_b32_dpp v205, v63 row_shr:1 row_mask:0xf bank_mask:0xf
	v_mov_b32_dpp v209, v63 row_shr:2 row_mask:0xf bank_mask:0xf
	v_mov_b32_dpp v206, v64 row_shr:1 row_mask:0xf bank_mask:0xf
	v_mov_b32_dpp v210, v64 row_shr:2 row_mask:0xf bank_mask:0xf
	v_mov_b32_dpp v207, v65 row_shr:1 row_mask:0xf bank_mask:0xf
	v_mov_b32_dpp v211, v65 row_shr:2 row_mask:0xf bank_mask:0xf
	s_waitcnt vmcnt(3)
	v_mov_b32_dpp v223, v162 row_shl:1 row_mask:0xf bank_mask:0xf
	v_mov_b32_dpp v224, v163 row_shl:1 row_mask:0xf bank_mask:0xf
	v_mov_b32_dpp v225, v164 row_shl:1 row_mask:0xf bank_mask:0xf
	v_mov_b32_dpp v226, v165 row_shl:1 row_mask:0xf bank_mask:0xf
	v_cndmask_b32_e64 v208, v208, v162, s[48:49]
	v_cndmask_b32_e64 v209, v209, v163, s[48:49]
	v_cndmask_b32_e64 v210, v210, v164, s[48:49]
	v_cndmask_b32_e64 v211, v211, v165, s[48:49]
	v_cndmask_b32_e64 v204, v204, v223, s[46:47]
	v_cndmask_b32_e64 v205, v205, v224, s[46:47]
	v_cndmask_b32_e64 v206, v206, v225, s[46:47]
	v_cndmask_b32_e64 v207, v207, v226, s[46:47]
	s_mov_b64 exec, s[48:49]
	v_add_u32_e32 v222, 0x2c000, v190
	global_load_dwordx4 v[162:165], v222, s[16:17] offset:16
	s_mov_b64 exec, -1
	v_pk_fma_f32 v[212:213], v[102:103], v[204:205], v[212:213]
	v_pk_fma_f32 v[214:215], v[104:105], v[206:207], v[214:215]
	v_pk_fma_f32 v[212:213], v[98:99], v[208:209], v[212:213]
	v_pk_fma_f32 v[214:215], v[100:101], v[210:211], v[214:215]
	v_pk_fma_f32 v[216:217], v[122:123], v[58:59], v[126:127]
	v_pk_fma_f32 v[218:219], v[124:125], v[60:61], v[128:129]
	s_nop 2
	v_mov_b32_dpp v204, v58 row_shr:1 row_mask:0xf bank_mask:0xf
	v_mov_b32_dpp v208, v58 row_shr:2 row_mask:0xf bank_mask:0xf
	v_mov_b32_dpp v205, v59 row_shr:1 row_mask:0xf bank_mask:0xf
	v_mov_b32_dpp v209, v59 row_shr:2 row_mask:0xf bank_mask:0xf
	v_mov_b32_dpp v206, v60 row_shr:1 row_mask:0xf bank_mask:0xf
	v_mov_b32_dpp v210, v60 row_shr:2 row_mask:0xf bank_mask:0xf
	v_mov_b32_dpp v207, v61 row_shr:1 row_mask:0xf bank_mask:0xf
	v_mov_b32_dpp v211, v61 row_shr:2 row_mask:0xf bank_mask:0xf
	s_waitcnt vmcnt(3)
	v_mov_b32_dpp v223, v166 row_shl:1 row_mask:0xf bank_mask:0xf
	v_mov_b32_dpp v224, v167 row_shl:1 row_mask:0xf bank_mask:0xf
	v_mov_b32_dpp v225, v168 row_shl:1 row_mask:0xf bank_mask:0xf
	v_mov_b32_dpp v226, v169 row_shl:1 row_mask:0xf bank_mask:0xf
	v_cndmask_b32_e64 v208, v208, v166, s[48:49]
	v_cndmask_b32_e64 v209, v209, v167, s[48:49]
	v_cndmask_b32_e64 v210, v210, v168, s[48:49]
	v_cndmask_b32_e64 v211, v211, v169, s[48:49]
	v_cndmask_b32_e64 v204, v204, v223, s[46:47]
	v_cndmask_b32_e64 v205, v205, v224, s[46:47]
	v_cndmask_b32_e64 v206, v206, v225, s[46:47]
	v_cndmask_b32_e64 v207, v207, v226, s[46:47]
	s_mov_b64 exec, s[48:49]
	v_add_u32_e32 v222, 0x2ec00, v190
	global_load_dwordx4 v[166:169], v222, s[16:17] offset:16
	s_mov_b64 exec, -1
	v_pk_fma_f32 v[216:217], v[118:119], v[204:205], v[216:217]
	v_pk_fma_f32 v[218:219], v[120:121], v[206:207], v[218:219]
	v_pk_fma_f32 v[216:217], v[114:115], v[208:209], v[216:217]
	v_pk_fma_f32 v[218:219], v[116:117], v[210:211], v[218:219]
	v_mul_f32_e32 v204, 0xbfb8aa3b, v216
	v_mul_f32_e32 v205, 0xbfb8aa3b, v217
	v_mul_f32_e32 v206, 0xbfb8aa3b, v218
	v_mul_f32_e32 v207, 0xbfb8aa3b, v219
	v_exp_f32_e32 v204, v204
	v_exp_f32_e32 v205, v205
	v_exp_f32_e32 v206, v206
	v_exp_f32_e32 v207, v207
	v_add_f32_e32 v204, 1.0, v204
	v_add_f32_e32 v205, 1.0, v205
	v_add_f32_e32 v206, 1.0, v206
	v_add_f32_e32 v207, 1.0, v207
	v_rcp_f32_e32 v204, v204
	v_rcp_f32_e32 v205, v205
	v_rcp_f32_e32 v206, v206
	v_rcp_f32_e32 v207, v207
	v_mul_f32_e32 v204, v216, v204
	v_mul_f32_e32 v205, v217, v205
	v_mul_f32_e32 v206, v218, v206
	v_mul_f32_e32 v207, v219, v207
	v_mul_f32_e32 v204, v212, v204
	v_mul_f32_e32 v205, v213, v205
	v_mul_f32_e32 v206, v214, v206
	v_mul_f32_e32 v207, v215, v207
	v_cvt_pk_bf16_f32 v62, v204, v205
	v_cvt_pk_bf16_f32 v63, v206, v207
	v_pk_fma_f32 v[212:213], v[106:107], v[54:55], v[110:111]
	v_pk_fma_f32 v[214:215], v[108:109], v[56:57], v[112:113]
	s_nop 2
	v_mov_b32_dpp v204, v54 row_shr:1 row_mask:0xf bank_mask:0xf
	v_mov_b32_dpp v208, v54 row_shr:2 row_mask:0xf bank_mask:0xf
	v_mov_b32_dpp v205, v55 row_shr:1 row_mask:0xf bank_mask:0xf
	v_mov_b32_dpp v209, v55 row_shr:2 row_mask:0xf bank_mask:0xf
	v_mov_b32_dpp v206, v56 row_shr:1 row_mask:0xf bank_mask:0xf
	v_mov_b32_dpp v210, v56 row_shr:2 row_mask:0xf bank_mask:0xf
	v_mov_b32_dpp v207, v57 row_shr:1 row_mask:0xf bank_mask:0xf
	v_mov_b32_dpp v211, v57 row_shr:2 row_mask:0xf bank_mask:0xf
	s_waitcnt vmcnt(3)
	v_mov_b32_dpp v223, v170 row_shl:1 row_mask:0xf bank_mask:0xf
	v_mov_b32_dpp v224, v171 row_shl:1 row_mask:0xf bank_mask:0xf
	v_mov_b32_dpp v225, v172 row_shl:1 row_mask:0xf bank_mask:0xf
	v_mov_b32_dpp v226, v173 row_shl:1 row_mask:0xf bank_mask:0xf
	v_cndmask_b32_e64 v208, v208, v170, s[48:49]
	v_cndmask_b32_e64 v209, v209, v171, s[48:49]
	v_cndmask_b32_e64 v210, v210, v172, s[48:49]
	v_cndmask_b32_e64 v211, v211, v173, s[48:49]
	v_cndmask_b32_e64 v204, v204, v223, s[46:47]
	v_cndmask_b32_e64 v205, v205, v224, s[46:47]
	v_cndmask_b32_e64 v206, v206, v225, s[46:47]
	v_cndmask_b32_e64 v207, v207, v226, s[46:47]
	s_mov_b64 exec, s[48:49]
	v_add_u32_e32 v222, 0x42000, v190
	global_load_dwordx4 v[170:173], v222, s[16:17] offset:16
	s_mov_b64 exec, -1
	v_pk_fma_f32 v[212:213], v[102:103], v[204:205], v[212:213]
	v_pk_fma_f32 v[214:215], v[104:105], v[206:207], v[214:215]
	v_pk_fma_f32 v[212:213], v[98:99], v[208:209], v[212:213]
	v_pk_fma_f32 v[214:215], v[100:101], v[210:211], v[214:215]
	v_pk_fma_f32 v[216:217], v[122:123], v[50:51], v[126:127]
	v_pk_fma_f32 v[218:219], v[124:125], v[52:53], v[128:129]
	s_nop 2
	v_mov_b32_dpp v204, v50 row_shr:1 row_mask:0xf bank_mask:0xf
	v_mov_b32_dpp v208, v50 row_shr:2 row_mask:0xf bank_mask:0xf
	v_mov_b32_dpp v205, v51 row_shr:1 row_mask:0xf bank_mask:0xf
	v_mov_b32_dpp v209, v51 row_shr:2 row_mask:0xf bank_mask:0xf
	v_mov_b32_dpp v206, v52 row_shr:1 row_mask:0xf bank_mask:0xf
	v_mov_b32_dpp v210, v52 row_shr:2 row_mask:0xf bank_mask:0xf
	v_mov_b32_dpp v207, v53 row_shr:1 row_mask:0xf bank_mask:0xf
	v_mov_b32_dpp v211, v53 row_shr:2 row_mask:0xf bank_mask:0xf
	s_waitcnt vmcnt(3)
	v_mov_b32_dpp v223, v174 row_shl:1 row_mask:0xf bank_mask:0xf
	v_mov_b32_dpp v224, v175 row_shl:1 row_mask:0xf bank_mask:0xf
	v_mov_b32_dpp v225, v176 row_shl:1 row_mask:0xf bank_mask:0xf
	v_mov_b32_dpp v226, v177 row_shl:1 row_mask:0xf bank_mask:0xf
	v_cndmask_b32_e64 v208, v208, v174, s[48:49]
	v_cndmask_b32_e64 v209, v209, v175, s[48:49]
	v_cndmask_b32_e64 v210, v210, v176, s[48:49]
	v_cndmask_b32_e64 v211, v211, v177, s[48:49]
	v_cndmask_b32_e64 v204, v204, v223, s[46:47]
	v_cndmask_b32_e64 v205, v205, v224, s[46:47]
	v_cndmask_b32_e64 v206, v206, v225, s[46:47]
	v_cndmask_b32_e64 v207, v207, v226, s[46:47]
	s_mov_b64 exec, s[48:49]
	v_add_u32_e32 v222, 0x44c00, v190
	global_load_dwordx4 v[174:177], v222, s[16:17] offset:16
	s_mov_b64 exec, -1
	v_pk_fma_f32 v[216:217], v[118:119], v[204:205], v[216:217]
	v_pk_fma_f32 v[218:219], v[120:121], v[206:207], v[218:219]
	v_pk_fma_f32 v[216:217], v[114:115], v[208:209], v[216:217]
	v_pk_fma_f32 v[218:219], v[116:117], v[210:211], v[218:219]
	v_mul_f32_e32 v204, 0xbfb8aa3b, v216
	v_mul_f32_e32 v205, 0xbfb8aa3b, v217
	v_mul_f32_e32 v206, 0xbfb8aa3b, v218
	v_mul_f32_e32 v207, 0xbfb8aa3b, v219
	v_exp_f32_e32 v204, v204
	v_exp_f32_e32 v205, v205
	v_exp_f32_e32 v206, v206
	v_exp_f32_e32 v207, v207
	v_add_f32_e32 v204, 1.0, v204
	v_add_f32_e32 v205, 1.0, v205
	v_add_f32_e32 v206, 1.0, v206
	v_add_f32_e32 v207, 1.0, v207
	v_rcp_f32_e32 v204, v204
	v_rcp_f32_e32 v205, v205
	v_rcp_f32_e32 v206, v206
	v_rcp_f32_e32 v207, v207
	v_mul_f32_e32 v204, v216, v204
	v_mul_f32_e32 v205, v217, v205
	v_mul_f32_e32 v206, v218, v206
	v_mul_f32_e32 v207, v219, v207
	v_mul_f32_e32 v204, v212, v204
	v_mul_f32_e32 v205, v213, v205
	v_mul_f32_e32 v206, v214, v206
	v_mul_f32_e32 v207, v215, v207
	v_cvt_pk_bf16_f32 v54, v204, v205
	v_cvt_pk_bf16_f32 v55, v206, v207
	v_pk_fma_f32 v[212:213], v[106:107], v[46:47], v[110:111]
	v_pk_fma_f32 v[214:215], v[108:109], v[48:49], v[112:113]
	s_nop 2
	v_mov_b32_dpp v204, v46 row_shr:1 row_mask:0xf bank_mask:0xf
	v_mov_b32_dpp v208, v46 row_shr:2 row_mask:0xf bank_mask:0xf
	v_mov_b32_dpp v205, v47 row_shr:1 row_mask:0xf bank_mask:0xf
	v_mov_b32_dpp v209, v47 row_shr:2 row_mask:0xf bank_mask:0xf
	v_mov_b32_dpp v206, v48 row_shr:1 row_mask:0xf bank_mask:0xf
	v_mov_b32_dpp v210, v48 row_shr:2 row_mask:0xf bank_mask:0xf
	v_mov_b32_dpp v207, v49 row_shr:1 row_mask:0xf bank_mask:0xf
	v_mov_b32_dpp v211, v49 row_shr:2 row_mask:0xf bank_mask:0xf
	s_waitcnt vmcnt(3)
	v_mov_b32_dpp v223, v162 row_shl:1 row_mask:0xf bank_mask:0xf
	v_mov_b32_dpp v224, v163 row_shl:1 row_mask:0xf bank_mask:0xf
	v_mov_b32_dpp v225, v164 row_shl:1 row_mask:0xf bank_mask:0xf
	v_mov_b32_dpp v226, v165 row_shl:1 row_mask:0xf bank_mask:0xf
	v_cndmask_b32_e64 v208, v208, v162, s[48:49]
	v_cndmask_b32_e64 v209, v209, v163, s[48:49]
	v_cndmask_b32_e64 v210, v210, v164, s[48:49]
	v_cndmask_b32_e64 v211, v211, v165, s[48:49]
	v_cndmask_b32_e64 v204, v204, v223, s[46:47]
	v_cndmask_b32_e64 v205, v205, v224, s[46:47]
	v_cndmask_b32_e64 v206, v206, v225, s[46:47]
	v_cndmask_b32_e64 v207, v207, v226, s[46:47]
	s_mov_b64 exec, s[48:49]
	v_add_u32_e32 v222, 0xb0000, v190
	global_load_dwordx4 v[162:165], v222, s[16:17] offset:16
	s_mov_b64 exec, -1
	v_pk_fma_f32 v[212:213], v[102:103], v[204:205], v[212:213]
	v_pk_fma_f32 v[214:215], v[104:105], v[206:207], v[214:215]
	v_pk_fma_f32 v[212:213], v[98:99], v[208:209], v[212:213]
	v_pk_fma_f32 v[214:215], v[100:101], v[210:211], v[214:215]
	v_pk_fma_f32 v[216:217], v[122:123], v[42:43], v[126:127]
	v_pk_fma_f32 v[218:219], v[124:125], v[44:45], v[128:129]
	s_nop 2
	v_mov_b32_dpp v204, v42 row_shr:1 row_mask:0xf bank_mask:0xf
	v_mov_b32_dpp v208, v42 row_shr:2 row_mask:0xf bank_mask:0xf
	v_mov_b32_dpp v205, v43 row_shr:1 row_mask:0xf bank_mask:0xf
	v_mov_b32_dpp v209, v43 row_shr:2 row_mask:0xf bank_mask:0xf
	v_mov_b32_dpp v206, v44 row_shr:1 row_mask:0xf bank_mask:0xf
	v_mov_b32_dpp v210, v44 row_shr:2 row_mask:0xf bank_mask:0xf
	v_mov_b32_dpp v207, v45 row_shr:1 row_mask:0xf bank_mask:0xf
	v_mov_b32_dpp v211, v45 row_shr:2 row_mask:0xf bank_mask:0xf
	s_waitcnt vmcnt(3)
	v_mov_b32_dpp v223, v166 row_shl:1 row_mask:0xf bank_mask:0xf
	v_mov_b32_dpp v224, v167 row_shl:1 row_mask:0xf bank_mask:0xf
	v_mov_b32_dpp v225, v168 row_shl:1 row_mask:0xf bank_mask:0xf
	v_mov_b32_dpp v226, v169 row_shl:1 row_mask:0xf bank_mask:0xf
	v_cndmask_b32_e64 v208, v208, v166, s[48:49]
	v_cndmask_b32_e64 v209, v209, v167, s[48:49]
	v_cndmask_b32_e64 v210, v210, v168, s[48:49]
	v_cndmask_b32_e64 v211, v211, v169, s[48:49]
	v_cndmask_b32_e64 v204, v204, v223, s[46:47]
	v_cndmask_b32_e64 v205, v205, v224, s[46:47]
	v_cndmask_b32_e64 v206, v206, v225, s[46:47]
	v_cndmask_b32_e64 v207, v207, v226, s[46:47]
	s_mov_b64 exec, s[48:49]
	v_add_u32_e32 v222, 0xb2c00, v190
	global_load_dwordx4 v[166:169], v222, s[16:17] offset:16
	s_mov_b64 exec, -1
	v_pk_fma_f32 v[216:217], v[118:119], v[204:205], v[216:217]
	v_pk_fma_f32 v[218:219], v[120:121], v[206:207], v[218:219]
	v_pk_fma_f32 v[216:217], v[114:115], v[208:209], v[216:217]
	v_pk_fma_f32 v[218:219], v[116:117], v[210:211], v[218:219]
	v_mul_f32_e32 v204, 0xbfb8aa3b, v216
	v_mul_f32_e32 v205, 0xbfb8aa3b, v217
	v_mul_f32_e32 v206, 0xbfb8aa3b, v218
	v_mul_f32_e32 v207, 0xbfb8aa3b, v219
	v_exp_f32_e32 v204, v204
	v_exp_f32_e32 v205, v205
	v_exp_f32_e32 v206, v206
	v_exp_f32_e32 v207, v207
	v_add_f32_e32 v204, 1.0, v204
	v_add_f32_e32 v205, 1.0, v205
	v_add_f32_e32 v206, 1.0, v206
	v_add_f32_e32 v207, 1.0, v207
	v_rcp_f32_e32 v204, v204
	v_rcp_f32_e32 v205, v205
	v_rcp_f32_e32 v206, v206
	v_rcp_f32_e32 v207, v207
	v_mul_f32_e32 v204, v216, v204
	v_mul_f32_e32 v205, v217, v205
	v_mul_f32_e32 v206, v218, v206
	v_mul_f32_e32 v207, v219, v207
	v_mul_f32_e32 v204, v212, v204
	v_mul_f32_e32 v205, v213, v205
	v_mul_f32_e32 v206, v214, v206
	v_mul_f32_e32 v207, v215, v207
	v_cvt_pk_bf16_f32 v46, v204, v205
	v_cvt_pk_bf16_f32 v47, v206, v207
	v_pk_fma_f32 v[212:213], v[106:107], v[38:39], v[110:111]
	v_pk_fma_f32 v[214:215], v[108:109], v[40:41], v[112:113]
	s_nop 2
	v_mov_b32_dpp v204, v38 row_shr:1 row_mask:0xf bank_mask:0xf
	v_mov_b32_dpp v208, v38 row_shr:2 row_mask:0xf bank_mask:0xf
	v_mov_b32_dpp v205, v39 row_shr:1 row_mask:0xf bank_mask:0xf
	v_mov_b32_dpp v209, v39 row_shr:2 row_mask:0xf bank_mask:0xf
	v_mov_b32_dpp v206, v40 row_shr:1 row_mask:0xf bank_mask:0xf
	v_mov_b32_dpp v210, v40 row_shr:2 row_mask:0xf bank_mask:0xf
	v_mov_b32_dpp v207, v41 row_shr:1 row_mask:0xf bank_mask:0xf
	v_mov_b32_dpp v211, v41 row_shr:2 row_mask:0xf bank_mask:0xf
	s_waitcnt vmcnt(3)
	v_mov_b32_dpp v223, v170 row_shl:1 row_mask:0xf bank_mask:0xf
	v_mov_b32_dpp v224, v171 row_shl:1 row_mask:0xf bank_mask:0xf
	v_mov_b32_dpp v225, v172 row_shl:1 row_mask:0xf bank_mask:0xf
	v_mov_b32_dpp v226, v173 row_shl:1 row_mask:0xf bank_mask:0xf
	v_cndmask_b32_e64 v208, v208, v170, s[48:49]
	v_cndmask_b32_e64 v209, v209, v171, s[48:49]
	v_cndmask_b32_e64 v210, v210, v172, s[48:49]
	v_cndmask_b32_e64 v211, v211, v173, s[48:49]
	v_cndmask_b32_e64 v204, v204, v223, s[46:47]
	v_cndmask_b32_e64 v205, v205, v224, s[46:47]
	v_cndmask_b32_e64 v206, v206, v225, s[46:47]
	v_cndmask_b32_e64 v207, v207, v226, s[46:47]
	s_mov_b64 exec, s[48:49]
	v_add_u32_e32 v222, 0xc6000, v190
	global_load_dwordx4 v[170:173], v222, s[16:17] offset:16
	s_mov_b64 exec, -1
	v_pk_fma_f32 v[212:213], v[102:103], v[204:205], v[212:213]
	v_pk_fma_f32 v[214:215], v[104:105], v[206:207], v[214:215]
	v_pk_fma_f32 v[212:213], v[98:99], v[208:209], v[212:213]
	v_pk_fma_f32 v[214:215], v[100:101], v[210:211], v[214:215]
	v_pk_fma_f32 v[216:217], v[122:123], v[34:35], v[126:127]
	v_pk_fma_f32 v[218:219], v[124:125], v[36:37], v[128:129]
	s_nop 2
	v_mov_b32_dpp v204, v34 row_shr:1 row_mask:0xf bank_mask:0xf
	v_mov_b32_dpp v208, v34 row_shr:2 row_mask:0xf bank_mask:0xf
	v_mov_b32_dpp v205, v35 row_shr:1 row_mask:0xf bank_mask:0xf
	v_mov_b32_dpp v209, v35 row_shr:2 row_mask:0xf bank_mask:0xf
	v_mov_b32_dpp v206, v36 row_shr:1 row_mask:0xf bank_mask:0xf
	v_mov_b32_dpp v210, v36 row_shr:2 row_mask:0xf bank_mask:0xf
	v_mov_b32_dpp v207, v37 row_shr:1 row_mask:0xf bank_mask:0xf
	v_mov_b32_dpp v211, v37 row_shr:2 row_mask:0xf bank_mask:0xf
	s_waitcnt vmcnt(3)
	v_mov_b32_dpp v223, v174 row_shl:1 row_mask:0xf bank_mask:0xf
	v_mov_b32_dpp v224, v175 row_shl:1 row_mask:0xf bank_mask:0xf
	v_mov_b32_dpp v225, v176 row_shl:1 row_mask:0xf bank_mask:0xf
	v_mov_b32_dpp v226, v177 row_shl:1 row_mask:0xf bank_mask:0xf
	v_cndmask_b32_e64 v208, v208, v174, s[48:49]
	v_cndmask_b32_e64 v209, v209, v175, s[48:49]
	v_cndmask_b32_e64 v210, v210, v176, s[48:49]
	v_cndmask_b32_e64 v211, v211, v177, s[48:49]
	v_cndmask_b32_e64 v204, v204, v223, s[46:47]
	v_cndmask_b32_e64 v205, v205, v224, s[46:47]
	v_cndmask_b32_e64 v206, v206, v225, s[46:47]
	v_cndmask_b32_e64 v207, v207, v226, s[46:47]
	s_mov_b64 exec, s[48:49]
	v_add_u32_e32 v222, 0xc8c00, v190
	global_load_dwordx4 v[174:177], v222, s[16:17] offset:16
	s_mov_b64 exec, -1
	v_pk_fma_f32 v[216:217], v[118:119], v[204:205], v[216:217]
	v_pk_fma_f32 v[218:219], v[120:121], v[206:207], v[218:219]
	v_pk_fma_f32 v[216:217], v[114:115], v[208:209], v[216:217]
	v_pk_fma_f32 v[218:219], v[116:117], v[210:211], v[218:219]
	v_mul_f32_e32 v204, 0xbfb8aa3b, v216
	v_mul_f32_e32 v205, 0xbfb8aa3b, v217
	v_mul_f32_e32 v206, 0xbfb8aa3b, v218
	v_mul_f32_e32 v207, 0xbfb8aa3b, v219
	v_exp_f32_e32 v204, v204
	v_exp_f32_e32 v205, v205
	v_exp_f32_e32 v206, v206
	v_exp_f32_e32 v207, v207
	v_add_f32_e32 v204, 1.0, v204
	v_add_f32_e32 v205, 1.0, v205
	v_add_f32_e32 v206, 1.0, v206
	v_add_f32_e32 v207, 1.0, v207
	v_rcp_f32_e32 v204, v204
	v_rcp_f32_e32 v205, v205
	v_rcp_f32_e32 v206, v206
	v_rcp_f32_e32 v207, v207
	v_mul_f32_e32 v204, v216, v204
	v_mul_f32_e32 v205, v217, v205
	v_mul_f32_e32 v206, v218, v206
	v_mul_f32_e32 v207, v219, v207
	v_mul_f32_e32 v204, v212, v204
	v_mul_f32_e32 v205, v213, v205
	v_mul_f32_e32 v206, v214, v206
	v_mul_f32_e32 v207, v215, v207
	v_cvt_pk_bf16_f32 v38, v204, v205
	v_cvt_pk_bf16_f32 v39, v206, v207
	v_pk_fma_f32 v[212:213], v[106:107], v[30:31], v[110:111]
	v_pk_fma_f32 v[214:215], v[108:109], v[32:33], v[112:113]
	s_nop 2
	v_mov_b32_dpp v204, v30 row_shr:1 row_mask:0xf bank_mask:0xf
	v_mov_b32_dpp v208, v30 row_shr:2 row_mask:0xf bank_mask:0xf
	v_mov_b32_dpp v205, v31 row_shr:1 row_mask:0xf bank_mask:0xf
	v_mov_b32_dpp v209, v31 row_shr:2 row_mask:0xf bank_mask:0xf
	v_mov_b32_dpp v206, v32 row_shr:1 row_mask:0xf bank_mask:0xf
	v_mov_b32_dpp v210, v32 row_shr:2 row_mask:0xf bank_mask:0xf
	v_mov_b32_dpp v207, v33 row_shr:1 row_mask:0xf bank_mask:0xf
	v_mov_b32_dpp v211, v33 row_shr:2 row_mask:0xf bank_mask:0xf
	s_waitcnt vmcnt(3)
	v_mov_b32_dpp v223, v162 row_shl:1 row_mask:0xf bank_mask:0xf
	v_mov_b32_dpp v224, v163 row_shl:1 row_mask:0xf bank_mask:0xf
	v_mov_b32_dpp v225, v164 row_shl:1 row_mask:0xf bank_mask:0xf
	v_mov_b32_dpp v226, v165 row_shl:1 row_mask:0xf bank_mask:0xf
	v_cndmask_b32_e64 v208, v208, v162, s[48:49]
	v_cndmask_b32_e64 v209, v209, v163, s[48:49]
	v_cndmask_b32_e64 v210, v210, v164, s[48:49]
	v_cndmask_b32_e64 v211, v211, v165, s[48:49]
	v_cndmask_b32_e64 v204, v204, v223, s[46:47]
	v_cndmask_b32_e64 v205, v205, v224, s[46:47]
	v_cndmask_b32_e64 v206, v206, v225, s[46:47]
	v_cndmask_b32_e64 v207, v207, v226, s[46:47]
	s_mov_b64 exec, s[48:49]
	v_add_u32_e32 v222, 0xdc000, v190
	global_load_dwordx4 v[162:165], v222, s[16:17] offset:16
	s_mov_b64 exec, -1
	v_pk_fma_f32 v[212:213], v[102:103], v[204:205], v[212:213]
	v_pk_fma_f32 v[214:215], v[104:105], v[206:207], v[214:215]
	v_pk_fma_f32 v[212:213], v[98:99], v[208:209], v[212:213]
	v_pk_fma_f32 v[214:215], v[100:101], v[210:211], v[214:215]
	v_pk_fma_f32 v[216:217], v[122:123], v[26:27], v[126:127]
	v_pk_fma_f32 v[218:219], v[124:125], v[28:29], v[128:129]
	s_nop 2
	v_mov_b32_dpp v204, v26 row_shr:1 row_mask:0xf bank_mask:0xf
	v_mov_b32_dpp v208, v26 row_shr:2 row_mask:0xf bank_mask:0xf
	v_mov_b32_dpp v205, v27 row_shr:1 row_mask:0xf bank_mask:0xf
	v_mov_b32_dpp v209, v27 row_shr:2 row_mask:0xf bank_mask:0xf
	v_mov_b32_dpp v206, v28 row_shr:1 row_mask:0xf bank_mask:0xf
	v_mov_b32_dpp v210, v28 row_shr:2 row_mask:0xf bank_mask:0xf
	v_mov_b32_dpp v207, v29 row_shr:1 row_mask:0xf bank_mask:0xf
	v_mov_b32_dpp v211, v29 row_shr:2 row_mask:0xf bank_mask:0xf
	s_waitcnt vmcnt(3)
	v_mov_b32_dpp v223, v166 row_shl:1 row_mask:0xf bank_mask:0xf
	v_mov_b32_dpp v224, v167 row_shl:1 row_mask:0xf bank_mask:0xf
	v_mov_b32_dpp v225, v168 row_shl:1 row_mask:0xf bank_mask:0xf
	v_mov_b32_dpp v226, v169 row_shl:1 row_mask:0xf bank_mask:0xf
	v_cndmask_b32_e64 v208, v208, v166, s[48:49]
	v_cndmask_b32_e64 v209, v209, v167, s[48:49]
	v_cndmask_b32_e64 v210, v210, v168, s[48:49]
	v_cndmask_b32_e64 v211, v211, v169, s[48:49]
	v_cndmask_b32_e64 v204, v204, v223, s[46:47]
	v_cndmask_b32_e64 v205, v205, v224, s[46:47]
	v_cndmask_b32_e64 v206, v206, v225, s[46:47]
	v_cndmask_b32_e64 v207, v207, v226, s[46:47]
	s_mov_b64 exec, s[48:49]
	v_add_u32_e32 v222, 0xdec00, v190
	global_load_dwordx4 v[166:169], v222, s[16:17] offset:16
	s_mov_b64 exec, -1
	v_pk_fma_f32 v[216:217], v[118:119], v[204:205], v[216:217]
	v_pk_fma_f32 v[218:219], v[120:121], v[206:207], v[218:219]
	v_pk_fma_f32 v[216:217], v[114:115], v[208:209], v[216:217]
	v_pk_fma_f32 v[218:219], v[116:117], v[210:211], v[218:219]
	v_mul_f32_e32 v204, 0xbfb8aa3b, v216
	v_mul_f32_e32 v205, 0xbfb8aa3b, v217
	v_mul_f32_e32 v206, 0xbfb8aa3b, v218
	v_mul_f32_e32 v207, 0xbfb8aa3b, v219
	v_exp_f32_e32 v204, v204
	v_exp_f32_e32 v205, v205
	v_exp_f32_e32 v206, v206
	v_exp_f32_e32 v207, v207
	v_add_f32_e32 v204, 1.0, v204
	v_add_f32_e32 v205, 1.0, v205
	v_add_f32_e32 v206, 1.0, v206
	v_add_f32_e32 v207, 1.0, v207
	v_rcp_f32_e32 v204, v204
	v_rcp_f32_e32 v205, v205
	v_rcp_f32_e32 v206, v206
	v_rcp_f32_e32 v207, v207
	v_mul_f32_e32 v204, v216, v204
	v_mul_f32_e32 v205, v217, v205
	v_mul_f32_e32 v206, v218, v206
	v_mul_f32_e32 v207, v219, v207
	v_mul_f32_e32 v204, v212, v204
	v_mul_f32_e32 v205, v213, v205
	v_mul_f32_e32 v206, v214, v206
	v_mul_f32_e32 v207, v215, v207
	v_cvt_pk_bf16_f32 v30, v204, v205
	v_cvt_pk_bf16_f32 v31, v206, v207
	v_pk_fma_f32 v[212:213], v[106:107], v[22:23], v[110:111]
	v_pk_fma_f32 v[214:215], v[108:109], v[24:25], v[112:113]
	s_nop 2
	v_mov_b32_dpp v204, v22 row_shr:1 row_mask:0xf bank_mask:0xf
	v_mov_b32_dpp v208, v22 row_shr:2 row_mask:0xf bank_mask:0xf
	v_mov_b32_dpp v205, v23 row_shr:1 row_mask:0xf bank_mask:0xf
	v_mov_b32_dpp v209, v23 row_shr:2 row_mask:0xf bank_mask:0xf
	v_mov_b32_dpp v206, v24 row_shr:1 row_mask:0xf bank_mask:0xf
	v_mov_b32_dpp v210, v24 row_shr:2 row_mask:0xf bank_mask:0xf
	v_mov_b32_dpp v207, v25 row_shr:1 row_mask:0xf bank_mask:0xf
	v_mov_b32_dpp v211, v25 row_shr:2 row_mask:0xf bank_mask:0xf
	s_waitcnt vmcnt(3)
	v_mov_b32_dpp v223, v170 row_shl:1 row_mask:0xf bank_mask:0xf
	v_mov_b32_dpp v224, v171 row_shl:1 row_mask:0xf bank_mask:0xf
	v_mov_b32_dpp v225, v172 row_shl:1 row_mask:0xf bank_mask:0xf
	v_mov_b32_dpp v226, v173 row_shl:1 row_mask:0xf bank_mask:0xf
	v_cndmask_b32_e64 v208, v208, v170, s[48:49]
	v_cndmask_b32_e64 v209, v209, v171, s[48:49]
	v_cndmask_b32_e64 v210, v210, v172, s[48:49]
	v_cndmask_b32_e64 v211, v211, v173, s[48:49]
	v_cndmask_b32_e64 v204, v204, v223, s[46:47]
	v_cndmask_b32_e64 v205, v205, v224, s[46:47]
	v_cndmask_b32_e64 v206, v206, v225, s[46:47]
	v_cndmask_b32_e64 v207, v207, v226, s[46:47]
	s_mov_b64 exec, s[48:49]
	v_add_u32_e32 v222, 0xf2000, v190
	global_load_dwordx4 v[170:173], v222, s[16:17] offset:16
	s_mov_b64 exec, -1
	v_pk_fma_f32 v[212:213], v[102:103], v[204:205], v[212:213]
	v_pk_fma_f32 v[214:215], v[104:105], v[206:207], v[214:215]
	v_pk_fma_f32 v[212:213], v[98:99], v[208:209], v[212:213]
	v_pk_fma_f32 v[214:215], v[100:101], v[210:211], v[214:215]
	v_pk_fma_f32 v[216:217], v[122:123], v[18:19], v[126:127]
	v_pk_fma_f32 v[218:219], v[124:125], v[20:21], v[128:129]
	s_nop 2
	v_mov_b32_dpp v204, v18 row_shr:1 row_mask:0xf bank_mask:0xf
	v_mov_b32_dpp v208, v18 row_shr:2 row_mask:0xf bank_mask:0xf
	v_mov_b32_dpp v205, v19 row_shr:1 row_mask:0xf bank_mask:0xf
	v_mov_b32_dpp v209, v19 row_shr:2 row_mask:0xf bank_mask:0xf
	v_mov_b32_dpp v206, v20 row_shr:1 row_mask:0xf bank_mask:0xf
	v_mov_b32_dpp v210, v20 row_shr:2 row_mask:0xf bank_mask:0xf
	v_mov_b32_dpp v207, v21 row_shr:1 row_mask:0xf bank_mask:0xf
	v_mov_b32_dpp v211, v21 row_shr:2 row_mask:0xf bank_mask:0xf
	s_waitcnt vmcnt(3)
	v_mov_b32_dpp v223, v174 row_shl:1 row_mask:0xf bank_mask:0xf
	v_mov_b32_dpp v224, v175 row_shl:1 row_mask:0xf bank_mask:0xf
	v_mov_b32_dpp v225, v176 row_shl:1 row_mask:0xf bank_mask:0xf
	v_mov_b32_dpp v226, v177 row_shl:1 row_mask:0xf bank_mask:0xf
	v_cndmask_b32_e64 v208, v208, v174, s[48:49]
	v_cndmask_b32_e64 v209, v209, v175, s[48:49]
	v_cndmask_b32_e64 v210, v210, v176, s[48:49]
	v_cndmask_b32_e64 v211, v211, v177, s[48:49]
	v_cndmask_b32_e64 v204, v204, v223, s[46:47]
	v_cndmask_b32_e64 v205, v205, v224, s[46:47]
	v_cndmask_b32_e64 v206, v206, v225, s[46:47]
	v_cndmask_b32_e64 v207, v207, v226, s[46:47]
	s_mov_b64 exec, s[48:49]
	v_add_u32_e32 v222, 0xf4c00, v190
	global_load_dwordx4 v[174:177], v222, s[16:17] offset:16
	s_mov_b64 exec, -1
	v_pk_fma_f32 v[216:217], v[118:119], v[204:205], v[216:217]
	v_pk_fma_f32 v[218:219], v[120:121], v[206:207], v[218:219]
	v_pk_fma_f32 v[216:217], v[114:115], v[208:209], v[216:217]
	v_pk_fma_f32 v[218:219], v[116:117], v[210:211], v[218:219]
	v_mul_f32_e32 v204, 0xbfb8aa3b, v216
	v_mul_f32_e32 v205, 0xbfb8aa3b, v217
	v_mul_f32_e32 v206, 0xbfb8aa3b, v218
	v_mul_f32_e32 v207, 0xbfb8aa3b, v219
	v_exp_f32_e32 v204, v204
	v_exp_f32_e32 v205, v205
	v_exp_f32_e32 v206, v206
	v_exp_f32_e32 v207, v207
	v_add_f32_e32 v204, 1.0, v204
	v_add_f32_e32 v205, 1.0, v205
	v_add_f32_e32 v206, 1.0, v206
	v_add_f32_e32 v207, 1.0, v207
	v_rcp_f32_e32 v204, v204
	v_rcp_f32_e32 v205, v205
	v_rcp_f32_e32 v206, v206
	v_rcp_f32_e32 v207, v207
	v_mul_f32_e32 v204, v216, v204
	v_mul_f32_e32 v205, v217, v205
	v_mul_f32_e32 v206, v218, v206
	v_mul_f32_e32 v207, v219, v207
	v_mul_f32_e32 v204, v212, v204
	v_mul_f32_e32 v205, v213, v205
	v_mul_f32_e32 v206, v214, v206
	v_mul_f32_e32 v207, v215, v207
	v_cvt_pk_bf16_f32 v22, v204, v205
	v_cvt_pk_bf16_f32 v23, v206, v207
	v_pk_fma_f32 v[212:213], v[106:107], v[14:15], v[110:111]
	v_pk_fma_f32 v[214:215], v[108:109], v[16:17], v[112:113]
	s_nop 2
	v_mov_b32_dpp v204, v14 row_shr:1 row_mask:0xf bank_mask:0xf
	v_mov_b32_dpp v208, v14 row_shr:2 row_mask:0xf bank_mask:0xf
	v_mov_b32_dpp v205, v15 row_shr:1 row_mask:0xf bank_mask:0xf
	v_mov_b32_dpp v209, v15 row_shr:2 row_mask:0xf bank_mask:0xf
	v_mov_b32_dpp v206, v16 row_shr:1 row_mask:0xf bank_mask:0xf
	v_mov_b32_dpp v210, v16 row_shr:2 row_mask:0xf bank_mask:0xf
	v_mov_b32_dpp v207, v17 row_shr:1 row_mask:0xf bank_mask:0xf
	v_mov_b32_dpp v211, v17 row_shr:2 row_mask:0xf bank_mask:0xf
	s_waitcnt vmcnt(3)
	v_mov_b32_dpp v223, v162 row_shl:1 row_mask:0xf bank_mask:0xf
	v_mov_b32_dpp v224, v163 row_shl:1 row_mask:0xf bank_mask:0xf
	v_mov_b32_dpp v225, v164 row_shl:1 row_mask:0xf bank_mask:0xf
	v_mov_b32_dpp v226, v165 row_shl:1 row_mask:0xf bank_mask:0xf
	v_cndmask_b32_e64 v208, v208, v162, s[48:49]
	v_cndmask_b32_e64 v209, v209, v163, s[48:49]
	v_cndmask_b32_e64 v210, v210, v164, s[48:49]
	v_cndmask_b32_e64 v211, v211, v165, s[48:49]
	v_cndmask_b32_e64 v204, v204, v223, s[46:47]
	v_cndmask_b32_e64 v205, v205, v224, s[46:47]
	v_cndmask_b32_e64 v206, v206, v225, s[46:47]
	v_cndmask_b32_e64 v207, v207, v226, s[46:47]
	v_pk_fma_f32 v[212:213], v[102:103], v[204:205], v[212:213]
	v_pk_fma_f32 v[214:215], v[104:105], v[206:207], v[214:215]
	v_pk_fma_f32 v[212:213], v[98:99], v[208:209], v[212:213]
	v_pk_fma_f32 v[214:215], v[100:101], v[210:211], v[214:215]
	v_pk_fma_f32 v[216:217], v[122:123], v[10:11], v[126:127]
	v_pk_fma_f32 v[218:219], v[124:125], v[12:13], v[128:129]
	s_nop 2
	v_mov_b32_dpp v204, v10 row_shr:1 row_mask:0xf bank_mask:0xf
	v_mov_b32_dpp v208, v10 row_shr:2 row_mask:0xf bank_mask:0xf
	v_mov_b32_dpp v205, v11 row_shr:1 row_mask:0xf bank_mask:0xf
	v_mov_b32_dpp v209, v11 row_shr:2 row_mask:0xf bank_mask:0xf
	v_mov_b32_dpp v206, v12 row_shr:1 row_mask:0xf bank_mask:0xf
	v_mov_b32_dpp v210, v12 row_shr:2 row_mask:0xf bank_mask:0xf
	v_mov_b32_dpp v207, v13 row_shr:1 row_mask:0xf bank_mask:0xf
	v_mov_b32_dpp v211, v13 row_shr:2 row_mask:0xf bank_mask:0xf
	s_waitcnt vmcnt(2)
	v_mov_b32_dpp v223, v166 row_shl:1 row_mask:0xf bank_mask:0xf
	v_mov_b32_dpp v224, v167 row_shl:1 row_mask:0xf bank_mask:0xf
	v_mov_b32_dpp v225, v168 row_shl:1 row_mask:0xf bank_mask:0xf
	v_mov_b32_dpp v226, v169 row_shl:1 row_mask:0xf bank_mask:0xf
	v_cndmask_b32_e64 v208, v208, v166, s[48:49]
	v_cndmask_b32_e64 v209, v209, v167, s[48:49]
	v_cndmask_b32_e64 v210, v210, v168, s[48:49]
	v_cndmask_b32_e64 v211, v211, v169, s[48:49]
	v_cndmask_b32_e64 v204, v204, v223, s[46:47]
	v_cndmask_b32_e64 v205, v205, v224, s[46:47]
	v_cndmask_b32_e64 v206, v206, v225, s[46:47]
	v_cndmask_b32_e64 v207, v207, v226, s[46:47]
	v_pk_fma_f32 v[216:217], v[118:119], v[204:205], v[216:217]
	v_pk_fma_f32 v[218:219], v[120:121], v[206:207], v[218:219]
	v_pk_fma_f32 v[216:217], v[114:115], v[208:209], v[216:217]
	v_pk_fma_f32 v[218:219], v[116:117], v[210:211], v[218:219]
	v_mul_f32_e32 v204, 0xbfb8aa3b, v216
	v_mul_f32_e32 v205, 0xbfb8aa3b, v217
	v_mul_f32_e32 v206, 0xbfb8aa3b, v218
	v_mul_f32_e32 v207, 0xbfb8aa3b, v219
	v_exp_f32_e32 v204, v204
	v_exp_f32_e32 v205, v205
	v_exp_f32_e32 v206, v206
	v_exp_f32_e32 v207, v207
	v_add_f32_e32 v204, 1.0, v204
	v_add_f32_e32 v205, 1.0, v205
	v_add_f32_e32 v206, 1.0, v206
	v_add_f32_e32 v207, 1.0, v207
	v_rcp_f32_e32 v204, v204
	v_rcp_f32_e32 v205, v205
	v_rcp_f32_e32 v206, v206
	v_rcp_f32_e32 v207, v207
	v_mul_f32_e32 v204, v216, v204
	v_mul_f32_e32 v205, v217, v205
	v_mul_f32_e32 v206, v218, v206
	v_mul_f32_e32 v207, v219, v207
	v_mul_f32_e32 v204, v212, v204
	v_mul_f32_e32 v205, v213, v205
	v_mul_f32_e32 v206, v214, v206
	v_mul_f32_e32 v207, v215, v207
	v_cvt_pk_bf16_f32 v14, v204, v205
	v_cvt_pk_bf16_f32 v15, v206, v207
	v_pk_fma_f32 v[212:213], v[106:107], v[6:7], v[110:111]
	v_pk_fma_f32 v[214:215], v[108:109], v[8:9], v[112:113]
	s_nop 2
	v_mov_b32_dpp v204, v6 row_shr:1 row_mask:0xf bank_mask:0xf
	v_mov_b32_dpp v208, v6 row_shr:2 row_mask:0xf bank_mask:0xf
	v_mov_b32_dpp v205, v7 row_shr:1 row_mask:0xf bank_mask:0xf
	v_mov_b32_dpp v209, v7 row_shr:2 row_mask:0xf bank_mask:0xf
	v_mov_b32_dpp v206, v8 row_shr:1 row_mask:0xf bank_mask:0xf
	v_mov_b32_dpp v210, v8 row_shr:2 row_mask:0xf bank_mask:0xf
	v_mov_b32_dpp v207, v9 row_shr:1 row_mask:0xf bank_mask:0xf
	v_mov_b32_dpp v211, v9 row_shr:2 row_mask:0xf bank_mask:0xf
	s_waitcnt vmcnt(1)
	v_mov_b32_dpp v223, v170 row_shl:1 row_mask:0xf bank_mask:0xf
	v_mov_b32_dpp v224, v171 row_shl:1 row_mask:0xf bank_mask:0xf
	v_mov_b32_dpp v225, v172 row_shl:1 row_mask:0xf bank_mask:0xf
	v_mov_b32_dpp v226, v173 row_shl:1 row_mask:0xf bank_mask:0xf
	v_cndmask_b32_e64 v208, v208, v170, s[48:49]
	v_cndmask_b32_e64 v209, v209, v171, s[48:49]
	v_cndmask_b32_e64 v210, v210, v172, s[48:49]
	v_cndmask_b32_e64 v211, v211, v173, s[48:49]
	v_cndmask_b32_e64 v204, v204, v223, s[46:47]
	v_cndmask_b32_e64 v205, v205, v224, s[46:47]
	v_cndmask_b32_e64 v206, v206, v225, s[46:47]
	v_cndmask_b32_e64 v207, v207, v226, s[46:47]
	v_pk_fma_f32 v[212:213], v[102:103], v[204:205], v[212:213]
	v_pk_fma_f32 v[214:215], v[104:105], v[206:207], v[214:215]
	v_pk_fma_f32 v[212:213], v[98:99], v[208:209], v[212:213]
	v_pk_fma_f32 v[214:215], v[100:101], v[210:211], v[214:215]
	v_pk_fma_f32 v[216:217], v[122:123], v[2:3], v[126:127]
	v_pk_fma_f32 v[218:219], v[124:125], v[4:5], v[128:129]
	s_nop 2
	v_mov_b32_dpp v204, v2 row_shr:1 row_mask:0xf bank_mask:0xf
	v_mov_b32_dpp v208, v2 row_shr:2 row_mask:0xf bank_mask:0xf
	v_mov_b32_dpp v205, v3 row_shr:1 row_mask:0xf bank_mask:0xf
	v_mov_b32_dpp v209, v3 row_shr:2 row_mask:0xf bank_mask:0xf
	v_mov_b32_dpp v206, v4 row_shr:1 row_mask:0xf bank_mask:0xf
	v_mov_b32_dpp v210, v4 row_shr:2 row_mask:0xf bank_mask:0xf
	v_mov_b32_dpp v207, v5 row_shr:1 row_mask:0xf bank_mask:0xf
	v_mov_b32_dpp v211, v5 row_shr:2 row_mask:0xf bank_mask:0xf
	s_waitcnt vmcnt(0)
	v_mov_b32_dpp v223, v174 row_shl:1 row_mask:0xf bank_mask:0xf
	v_mov_b32_dpp v224, v175 row_shl:1 row_mask:0xf bank_mask:0xf
	v_mov_b32_dpp v225, v176 row_shl:1 row_mask:0xf bank_mask:0xf
	v_mov_b32_dpp v226, v177 row_shl:1 row_mask:0xf bank_mask:0xf
	v_cndmask_b32_e64 v208, v208, v174, s[48:49]
	v_cndmask_b32_e64 v209, v209, v175, s[48:49]
	v_cndmask_b32_e64 v210, v210, v176, s[48:49]
	v_cndmask_b32_e64 v211, v211, v177, s[48:49]
	v_cndmask_b32_e64 v204, v204, v223, s[46:47]
	v_cndmask_b32_e64 v205, v205, v224, s[46:47]
	v_cndmask_b32_e64 v206, v206, v225, s[46:47]
	v_cndmask_b32_e64 v207, v207, v226, s[46:47]
	v_pk_fma_f32 v[216:217], v[118:119], v[204:205], v[216:217]
	v_pk_fma_f32 v[218:219], v[120:121], v[206:207], v[218:219]
	v_pk_fma_f32 v[216:217], v[114:115], v[208:209], v[216:217]
	v_pk_fma_f32 v[218:219], v[116:117], v[210:211], v[218:219]
	v_mul_f32_e32 v204, 0xbfb8aa3b, v216
	v_mul_f32_e32 v205, 0xbfb8aa3b, v217
	v_mul_f32_e32 v206, 0xbfb8aa3b, v218
	v_mul_f32_e32 v207, 0xbfb8aa3b, v219
	v_exp_f32_e32 v204, v204
	v_exp_f32_e32 v205, v205
	v_exp_f32_e32 v206, v206
	v_exp_f32_e32 v207, v207
	v_add_f32_e32 v204, 1.0, v204
	v_add_f32_e32 v205, 1.0, v205
	v_add_f32_e32 v206, 1.0, v206
	v_add_f32_e32 v207, 1.0, v207
	v_rcp_f32_e32 v204, v204
	v_rcp_f32_e32 v205, v205
	v_rcp_f32_e32 v206, v206
	v_rcp_f32_e32 v207, v207
	v_mul_f32_e32 v204, v216, v204
	v_mul_f32_e32 v205, v217, v205
	v_mul_f32_e32 v206, v218, v206
	v_mul_f32_e32 v207, v219, v207
	v_mul_f32_e32 v204, v212, v204
	v_mul_f32_e32 v205, v213, v205
	v_mul_f32_e32 v206, v214, v206
	v_mul_f32_e32 v207, v215, v207
	v_cvt_pk_bf16_f32 v6, v204, v205
	v_cvt_pk_bf16_f32 v7, v206, v207
	v_add_u32_e32 v204, 0xb0000, v231
	s_mov_b32 exec_lo, 0xfffcfffc
	s_mov_b32 exec_hi, 0xfffcfffc
	global_store_dwordx2 v204, v[94:95], s[36:37]
	s_mov_b64 exec, -1
	v_add_u32_e32 v205, 0xc6000, v231
	global_store_dwordx2 v205, v[86:87], s[36:37]
	v_add_u32_e32 v206, 0xdc000, v231
	global_store_dwordx2 v206, v[78:79], s[36:37]
	v_add_u32_e32 v207, 0xf2000, v231
	global_store_dwordx2 v207, v[70:71], s[36:37]
	v_add_u32_e32 v208, 0x8, v231
	s_mov_b32 exec_lo, 0xfffcfffc
	s_mov_b32 exec_hi, 0xfffcfffc
	global_store_dwordx2 v208, v[62:63], s[36:37]
	s_mov_b64 exec, -1
	v_add_u32_e32 v209, 0x16008, v231
	global_store_dwordx2 v209, v[54:55], s[36:37]
	v_add_u32_e32 v210, 0x2c008, v231
	global_store_dwordx2 v210, v[46:47], s[36:37]
	v_add_u32_e32 v211, 0x42008, v231
	global_store_dwordx2 v211, v[38:39], s[36:37]
	v_add_u32_e32 v204, 0xb0008, v231
	s_mov_b32 exec_lo, 0xfffcfffc
	s_mov_b32 exec_hi, 0xfffcfffc
	global_store_dwordx2 v204, v[30:31], s[36:37]
	s_mov_b64 exec, -1
	v_add_u32_e32 v205, 0xc6008, v231
	global_store_dwordx2 v205, v[22:23], s[36:37]
	v_add_u32_e32 v206, 0xdc008, v231
	global_store_dwordx2 v206, v[14:15], s[36:37]
	v_add_u32_e32 v207, 0xf2008, v231
	global_store_dwordx2 v207, v[6:7], s[36:37]
	s_branch .LBB0_2026

.Lmy_ffnB_sample:
	s_load_dwordx2 s[36:37], s[78:79], 0x268
	s_load_dwordx2 s[38:39], s[78:79], 0x2a0
	s_load_dwordx4 s[40:43], s[78:79], 0x70
	s_load_dwordx2 s[44:45], s[78:79], 0x128
	s_load_dwordx2 s[16:17], s[78:79], 0x28
	v_and_b32_e32 v204, 15, v248
	v_bfe_u32 v205, v248, 8, 1
	v_bfe_u32 v206, v248, 6, 2
	v_bfe_u32 v207, v248, 4, 2
	v_lshlrev_b32_e32 v206, 5, v206
	v_lshl_or_b32 v206, v207, 3, v206
	s_lshl_b32 s13, s14, 7
	v_add_u32_e32 v206, s13, v206
	s_lshl_b32 s13, s12, 8
	v_lshl_add_u32 v207, v205, 6, v204
	v_add_u32_e32 v207, s13, v207
	v_mul_u32_u24_e32 v231, 0x1600, v207
	v_lshl_add_u32 v231, v206, 1, v231
	v_lshlrev_b32_e32 v232, 2, v206
	s_lshl_b32 s13, s12, 4
	v_lshl_add_u32 v233, v205, 2, s13
	v_add_u32_e32 v208, -12, v204
	v_cmp_gt_u32_e32 vcc, 2, v204
	s_nop 1
	v_cndmask_b32_e32 v208, v208, v204, vcc
	v_add_u32_e32 v233, v233, v208
	v_mul_u32_u24_e32 v233, 0x2c00, v233
	v_lshl_add_u32 v233, v206, 1, v233
	s_sub_u32 s13, s12, 64
	s_lshl_b32 s13, s13, 5
	s_add_u32 s13, s13, 128
	v_lshrrev_b32_e32 v208, 3, v204
	v_lshl_add_u32 v208, v205, 3, v208
	v_add_u32_e32 v208, s13, v208
	v_mul_u32_u24_e32 v234, 0xb000, v208
	v_add_u32_e32 v234, v234, v232
	v_and_b32_e32 v209, 7, v204
	v_mul_u32_u24_e32 v190, 0x5800, v209
	v_add_u32_e32 v235, 0xfffdf000, v190
	v_add_u32_e32 v235, v235, v234
	v_add_u32_e32 v190, v190, v234
	s_mov_b32 s46, 0x01010101
	s_mov_b32 s47, 0x01010101
	s_mov_b32 s48, 0x03030303
	s_mov_b32 s49, 0x03030303
	s_mov_b32 s50, 0xc0c0c0c0
	s_mov_b32 s51, 0xc0c0c0c0
	s_waitcnt lgkmcnt(0)
	s_add_u32 s40, s40, 0x10800
	s_addc_u32 s41, s41, 0
	s_add_u32 s42, s42, 0x5800
	s_addc_u32 s43, s43, 0
	global_load_dwordx4 v[130:133], v232, s[40:41]
	v_add_u32_e32 v213, 0x5800, v232
	global_load_dwordx4 v[134:137], v213, s[40:41]
	v_add_u32_e32 v214, 0xb000, v232
	global_load_dwordx4 v[138:141], v214, s[40:41]
	global_load_dwordx4 v[142:145], v232, s[42:43]
	v_add_u32_e32 v215, 0x2c00, v232
	global_load_dwordx4 v[146:149], v215, s[40:41]
	v_add_u32_e32 v216, 0x8400, v232
	global_load_dwordx4 v[150:153], v216, s[40:41]
	v_add_u32_e32 v217, 0xdc00, v232
	global_load_dwordx4 v[154:157], v217, s[40:41]
	v_add_u32_e32 v218, 0x2c00, v232
	global_load_dwordx4 v[158:161], v218, s[42:43]
	s_mov_b32 s4, m0
	s_mov_b32 m0, 0x23000
	s_mov_b64 exec, s[48:49]
	global_load_lds_dword v190, s[16:17]
	v_add_u32_e32 v222, 0x2c00, v190
	global_load_lds_dword v222, s[16:17]
	v_add_u32_e32 v222, 0x16000, v190
	global_load_lds_dword v222, s[16:17]
	v_add_u32_e32 v222, 0x18c00, v190
	global_load_lds_dword v222, s[16:17]
	v_add_u32_e32 v222, 0x2c000, v190
	global_load_lds_dword v222, s[16:17]
	v_add_u32_e32 v222, 0x2ec00, v190
	global_load_lds_dword v222, s[16:17]
	v_add_u32_e32 v222, 0x42000, v190
	global_load_lds_dword v222, s[16:17]
	v_add_u32_e32 v222, 0x44c00, v190
	global_load_lds_dword v222, s[16:17]
	v_add_u32_e32 v222, 0xb0000, v190
	global_load_lds_dword v222, s[16:17]
	v_add_u32_e32 v222, 0xb2c00, v190
	global_load_lds_dword v222, s[16:17]
	v_add_u32_e32 v222, 0xc6000, v190
	global_load_lds_dword v222, s[16:17]
	v_add_u32_e32 v222, 0xc8c00, v190
	global_load_lds_dword v222, s[16:17]
	v_add_u32_e32 v222, 0xdc000, v190
	global_load_lds_dword v222, s[16:17]
	v_add_u32_e32 v222, 0xdec00, v190
	global_load_lds_dword v222, s[16:17]
	v_add_u32_e32 v222, 0xf2000, v190
	global_load_lds_dword v222, s[16:17]
	v_add_u32_e32 v222, 0xf4c00, v190
	global_load_lds_dword v222, s[16:17]
	s_mov_b64 exec, -1
	s_mov_b32 m0, s4
	s_mov_b64 exec, s[48:49]
	global_load_dwordx4 v[162:165], v190, s[16:17]
	s_mov_b64 exec, -1
	s_mov_b64 exec, s[48:49]
	v_add_u32_e32 v222, 0x2c00, v190
	global_load_dwordx4 v[166:169], v222, s[16:17]
	s_mov_b64 exec, -1
	s_mov_b64 exec, s[48:49]
	v_add_u32_e32 v222, 0x16000, v190
	global_load_dwordx4 v[170:173], v222, s[16:17]
	s_mov_b64 exec, -1
	s_mov_b64 exec, s[48:49]
	v_add_u32_e32 v222, 0x18c00, v190
	global_load_dwordx4 v[174:177], v222, s[16:17]
	s_mov_b64 exec, -1
	s_mov_b32 exec_lo, 0x30003
	s_mov_b32 exec_hi, 0x30003
	v_cvt_pk_bf16_f32 v204, v126, v127
	v_cvt_pk_bf16_f32 v205, v128, v129
	global_store_dwordx2 v233, v[204:205], s[38:39]
	v_cvt_pk_bf16_f32 v206, v122, v123
	v_cvt_pk_bf16_f32 v207, v124, v125
	v_add_u32_e32 v220, 0x1600, v233
	global_store_dwordx2 v220, v[206:207], s[38:39]
	v_cvt_pk_bf16_f32 v208, v94, v95
	v_cvt_pk_bf16_f32 v209, v96, v97
	v_add_u32_e32 v221, 0x16000, v233
	global_store_dwordx2 v221, v[208:209], s[38:39]
	v_cvt_pk_bf16_f32 v210, v90, v91
	v_cvt_pk_bf16_f32 v211, v92, v93
	v_add_u32_e32 v222, 0x17600, v233
	global_store_dwordx2 v222, v[210:211], s[38:39]
	v_cvt_pk_bf16_f32 v212, v62, v63
	v_cvt_pk_bf16_f32 v213, v64, v65
	v_add_u32_e32 v223, 0x8, v233
	global_store_dwordx2 v223, v[212:213], s[38:39]
	v_cvt_pk_bf16_f32 v214, v58, v59
	v_cvt_pk_bf16_f32 v215, v60, v61
	v_add_u32_e32 v224, 0x1608, v233
	global_store_dwordx2 v224, v[214:215], s[38:39]
	v_cvt_pk_bf16_f32 v216, v30, v31
	v_cvt_pk_bf16_f32 v217, v32, v33
	v_add_u32_e32 v225, 0x16008, v233
	global_store_dwordx2 v225, v[216:217], s[38:39]
	v_cvt_pk_bf16_f32 v218, v26, v27
	v_cvt_pk_bf16_f32 v219, v28, v29
	v_add_u32_e32 v226, 0x17608, v233
	global_store_dwordx2 v226, v[218:219], s[38:39]
	s_mov_b32 exec_lo, 0xc000c000
	s_mov_b32 exec_hi, 0xc000c000
	v_cvt_pk_bf16_f32 v204, v102, v103
	v_cvt_pk_bf16_f32 v205, v104, v105
	global_store_dwordx2 v233, v[204:205], s[38:39]
	v_cvt_pk_bf16_f32 v206, v98, v99
	v_cvt_pk_bf16_f32 v207, v100, v101
	v_add_u32_e32 v220, 0x1600, v233
	global_store_dwordx2 v220, v[206:207], s[38:39]
	v_cvt_pk_bf16_f32 v208, v70, v71
	v_cvt_pk_bf16_f32 v209, v72, v73
	v_add_u32_e32 v221, 0x16000, v233
	global_store_dwordx2 v221, v[208:209], s[38:39]
	v_cvt_pk_bf16_f32 v210, v66, v67
	v_cvt_pk_bf16_f32 v211, v68, v69
	v_add_u32_e32 v222, 0x17600, v233
	global_store_dwordx2 v222, v[210:211], s[38:39]
	v_cvt_pk_bf16_f32 v212, v38, v39
	v_cvt_pk_bf16_f32 v213, v40, v41
	v_add_u32_e32 v223, 0x8, v233
	global_store_dwordx2 v223, v[212:213], s[38:39]
	v_cvt_pk_bf16_f32 v214, v34, v35
	v_cvt_pk_bf16_f32 v215, v36, v37
	v_add_u32_e32 v224, 0x1608, v233
	global_store_dwordx2 v224, v[214:215], s[38:39]
	v_cvt_pk_bf16_f32 v216, v6, v7
	v_cvt_pk_bf16_f32 v217, v8, v9
	v_add_u32_e32 v225, 0x16008, v233
	global_store_dwordx2 v225, v[216:217], s[38:39]
	v_cvt_pk_bf16_f32 v218, v2, v3
	v_cvt_pk_bf16_f32 v219, v4, v5
	v_add_u32_e32 v226, 0x17608, v233
	global_store_dwordx2 v226, v[218:219], s[38:39]
	s_mov_b64 exec, -1
	s_waitcnt vmcnt(36)
	s_mov_b64 exec, s[50:51]
	global_store_dwordx4 v235, v[126:129], s[44:45]
	v_add_u32_e32 v224, 0x2c00, v235
	global_store_dwordx4 v224, v[122:125], s[44:45]
	v_add_u32_e32 v225, 0x16000, v235
	global_store_dwordx4 v225, v[118:121], s[44:45]
	v_add_u32_e32 v226, 0x18c00, v235
	global_store_dwordx4 v226, v[114:117], s[44:45]
	v_add_u32_e32 v223, 0x2c000, v235
	global_store_dwordx4 v223, v[110:113], s[44:45]
	v_add_u32_e32 v224, 0x2ec00, v235
	global_store_dwordx4 v224, v[106:109], s[44:45]
	v_add_u32_e32 v225, 0x42000, v235
	global_store_dwordx4 v225, v[102:105], s[44:45]
	v_add_u32_e32 v226, 0x44c00, v235
	global_store_dwordx4 v226, v[98:101], s[44:45]
	v_add_u32_e32 v223, 0xb0000, v235
	global_store_dwordx4 v223, v[94:97], s[44:45]
	v_add_u32_e32 v224, 0xb2c00, v235
	global_store_dwordx4 v224, v[90:93], s[44:45]
	v_add_u32_e32 v225, 0xc6000, v235
	global_store_dwordx4 v225, v[86:89], s[44:45]
	v_add_u32_e32 v226, 0xc8c00, v235
	global_store_dwordx4 v226, v[82:85], s[44:45]
	v_add_u32_e32 v223, 0xdc000, v235
	global_store_dwordx4 v223, v[78:81], s[44:45]
	v_add_u32_e32 v224, 0xdec00, v235
	global_store_dwordx4 v224, v[74:77], s[44:45]
	v_add_u32_e32 v225, 0xf2000, v235
	global_store_dwordx4 v225, v[70:73], s[44:45]
	v_add_u32_e32 v226, 0xf4c00, v235
	global_store_dwordx4 v226, v[66:69], s[44:45]
	s_mov_b64 exec, -1
	v_pk_fma_f32 v[212:213], v[138:139], v[126:127], v[142:143]
	v_pk_fma_f32 v[214:215], v[140:141], v[128:129], v[144:145]
	s_nop 2
	v_mov_b32_dpp v204, v126 row_shr:1 row_mask:0xf bank_mask:0xf
	v_mov_b32_dpp v208, v126 row_shr:2 row_mask:0xf bank_mask:0xf
	v_mov_b32_dpp v205, v127 row_shr:1 row_mask:0xf bank_mask:0xf
	v_mov_b32_dpp v209, v127 row_shr:2 row_mask:0xf bank_mask:0xf
	v_mov_b32_dpp v206, v128 row_shr:1 row_mask:0xf bank_mask:0xf
	v_mov_b32_dpp v210, v128 row_shr:2 row_mask:0xf bank_mask:0xf
	v_mov_b32_dpp v207, v129 row_shr:1 row_mask:0xf bank_mask:0xf
	v_mov_b32_dpp v211, v129 row_shr:2 row_mask:0xf bank_mask:0xf
	s_waitcnt vmcnt(35)
	v_mov_b32_dpp v223, v162 row_shl:1 row_mask:0xf bank_mask:0xf
	v_mov_b32_dpp v224, v163 row_shl:1 row_mask:0xf bank_mask:0xf
	v_mov_b32_dpp v225, v164 row_shl:1 row_mask:0xf bank_mask:0xf
	v_mov_b32_dpp v226, v165 row_shl:1 row_mask:0xf bank_mask:0xf
	v_cndmask_b32_e64 v208, v208, v162, s[48:49]
	v_cndmask_b32_e64 v209, v209, v163, s[48:49]
	v_cndmask_b32_e64 v210, v210, v164, s[48:49]
	v_cndmask_b32_e64 v211, v211, v165, s[48:49]
	v_cndmask_b32_e64 v204, v204, v223, s[46:47]
	v_cndmask_b32_e64 v205, v205, v224, s[46:47]
	v_cndmask_b32_e64 v206, v206, v225, s[46:47]
	v_cndmask_b32_e64 v207, v207, v226, s[46:47]
	s_mov_b64 exec, s[48:49]
	v_add_u32_e32 v222, 0x2c000, v190
	global_load_dwordx4 v[162:165], v222, s[16:17]
	s_mov_b64 exec, -1
	v_pk_fma_f32 v[212:213], v[134:135], v[204:205], v[212:213]
	v_pk_fma_f32 v[214:215], v[136:137], v[206:207], v[214:215]
	v_pk_fma_f32 v[212:213], v[130:131], v[208:209], v[212:213]
	v_pk_fma_f32 v[214:215], v[132:133], v[210:211], v[214:215]
	v_pk_fma_f32 v[216:217], v[154:155], v[122:123], v[158:159]
	v_pk_fma_f32 v[218:219], v[156:157], v[124:125], v[160:161]
	s_nop 2
	v_mov_b32_dpp v204, v122 row_shr:1 row_mask:0xf bank_mask:0xf
	v_mov_b32_dpp v208, v122 row_shr:2 row_mask:0xf bank_mask:0xf
	v_mov_b32_dpp v205, v123 row_shr:1 row_mask:0xf bank_mask:0xf
	v_mov_b32_dpp v209, v123 row_shr:2 row_mask:0xf bank_mask:0xf
	v_mov_b32_dpp v206, v124 row_shr:1 row_mask:0xf bank_mask:0xf
	v_mov_b32_dpp v210, v124 row_shr:2 row_mask:0xf bank_mask:0xf
	v_mov_b32_dpp v207, v125 row_shr:1 row_mask:0xf bank_mask:0xf
	v_mov_b32_dpp v211, v125 row_shr:2 row_mask:0xf bank_mask:0xf
	s_waitcnt vmcnt(35)
	v_mov_b32_dpp v223, v166 row_shl:1 row_mask:0xf bank_mask:0xf
	v_mov_b32_dpp v224, v167 row_shl:1 row_mask:0xf bank_mask:0xf
	v_mov_b32_dpp v225, v168 row_shl:1 row_mask:0xf bank_mask:0xf
	v_mov_b32_dpp v226, v169 row_shl:1 row_mask:0xf bank_mask:0xf
	v_cndmask_b32_e64 v208, v208, v166, s[48:49]
	v_cndmask_b32_e64 v209, v209, v167, s[48:49]
	v_cndmask_b32_e64 v210, v210, v168, s[48:49]
	v_cndmask_b32_e64 v211, v211, v169, s[48:49]
	v_cndmask_b32_e64 v204, v204, v223, s[46:47]
	v_cndmask_b32_e64 v205, v205, v224, s[46:47]
	v_cndmask_b32_e64 v206, v206, v225, s[46:47]
	v_cndmask_b32_e64 v207, v207, v226, s[46:47]
	s_mov_b64 exec, s[48:49]
	v_add_u32_e32 v222, 0x2ec00, v190
	global_load_dwordx4 v[166:169], v222, s[16:17]
	s_mov_b64 exec, -1
	v_pk_fma_f32 v[216:217], v[150:151], v[204:205], v[216:217]
	v_pk_fma_f32 v[218:219], v[152:153], v[206:207], v[218:219]
	v_pk_fma_f32 v[216:217], v[146:147], v[208:209], v[216:217]
	v_pk_fma_f32 v[218:219], v[148:149], v[210:211], v[218:219]
	v_mul_f32_e32 v204, 0xbfb8aa3b, v216
	v_mul_f32_e32 v205, 0xbfb8aa3b, v217
	v_mul_f32_e32 v206, 0xbfb8aa3b, v218
	v_mul_f32_e32 v207, 0xbfb8aa3b, v219
	v_exp_f32_e32 v204, v204
	v_exp_f32_e32 v205, v205
	v_exp_f32_e32 v206, v206
	v_exp_f32_e32 v207, v207
	v_add_f32_e32 v204, 1.0, v204
	v_add_f32_e32 v205, 1.0, v205
	v_add_f32_e32 v206, 1.0, v206
	v_add_f32_e32 v207, 1.0, v207
	v_rcp_f32_e32 v204, v204
	v_rcp_f32_e32 v205, v205
	v_rcp_f32_e32 v206, v206
	v_rcp_f32_e32 v207, v207
	v_mul_f32_e32 v204, v216, v204
	v_mul_f32_e32 v205, v217, v205
	v_mul_f32_e32 v206, v218, v206
	v_mul_f32_e32 v207, v219, v207
	v_mul_f32_e32 v204, v212, v204
	v_mul_f32_e32 v205, v213, v205
	v_mul_f32_e32 v206, v214, v206
	v_mul_f32_e32 v207, v215, v207
	v_cvt_pk_bf16_f32 v220, v204, v205
	v_cvt_pk_bf16_f32 v221, v206, v207
	v_mov_b32_e32 v222, v231
	s_mov_b32 exec_lo, 0xfffcfffc
	s_mov_b32 exec_hi, 0xfffcfffc
	global_store_dwordx2 v222, v[220:221], s[36:37]
	s_mov_b64 exec, -1
	v_pk_fma_f32 v[212:213], v[138:139], v[118:119], v[142:143]
	v_pk_fma_f32 v[214:215], v[140:141], v[120:121], v[144:145]
	s_nop 2
	v_mov_b32_dpp v204, v118 row_shr:1 row_mask:0xf bank_mask:0xf
	v_mov_b32_dpp v208, v118 row_shr:2 row_mask:0xf bank_mask:0xf
	v_mov_b32_dpp v205, v119 row_shr:1 row_mask:0xf bank_mask:0xf
	v_mov_b32_dpp v209, v119 row_shr:2 row_mask:0xf bank_mask:0xf
	v_mov_b32_dpp v206, v120 row_shr:1 row_mask:0xf bank_mask:0xf
	v_mov_b32_dpp v210, v120 row_shr:2 row_mask:0xf bank_mask:0xf
	v_mov_b32_dpp v207, v121 row_shr:1 row_mask:0xf bank_mask:0xf
	v_mov_b32_dpp v211, v121 row_shr:2 row_mask:0xf bank_mask:0xf
	s_waitcnt vmcnt(36)
	v_mov_b32_dpp v223, v170 row_shl:1 row_mask:0xf bank_mask:0xf
	v_mov_b32_dpp v224, v171 row_shl:1 row_mask:0xf bank_mask:0xf
	v_mov_b32_dpp v225, v172 row_shl:1 row_mask:0xf bank_mask:0xf
	v_mov_b32_dpp v226, v173 row_shl:1 row_mask:0xf bank_mask:0xf
	v_cndmask_b32_e64 v208, v208, v170, s[48:49]
	v_cndmask_b32_e64 v209, v209, v171, s[48:49]
	v_cndmask_b32_e64 v210, v210, v172, s[48:49]
	v_cndmask_b32_e64 v211, v211, v173, s[48:49]
	v_cndmask_b32_e64 v204, v204, v223, s[46:47]
	v_cndmask_b32_e64 v205, v205, v224, s[46:47]
	v_cndmask_b32_e64 v206, v206, v225, s[46:47]
	v_cndmask_b32_e64 v207, v207, v226, s[46:47]
	s_mov_b64 exec, s[48:49]
	v_add_u32_e32 v222, 0x42000, v190
	global_load_dwordx4 v[170:173], v222, s[16:17]
	s_mov_b64 exec, -1
	v_pk_fma_f32 v[212:213], v[134:135], v[204:205], v[212:213]
	v_pk_fma_f32 v[214:215], v[136:137], v[206:207], v[214:215]
	v_pk_fma_f32 v[212:213], v[130:131], v[208:209], v[212:213]
	v_pk_fma_f32 v[214:215], v[132:133], v[210:211], v[214:215]
	v_pk_fma_f32 v[216:217], v[154:155], v[114:115], v[158:159]
	v_pk_fma_f32 v[218:219], v[156:157], v[116:117], v[160:161]
	s_nop 2
	v_mov_b32_dpp v204, v114 row_shr:1 row_mask:0xf bank_mask:0xf
	v_mov_b32_dpp v208, v114 row_shr:2 row_mask:0xf bank_mask:0xf
	v_mov_b32_dpp v205, v115 row_shr:1 row_mask:0xf bank_mask:0xf
	v_mov_b32_dpp v209, v115 row_shr:2 row_mask:0xf bank_mask:0xf
	v_mov_b32_dpp v206, v116 row_shr:1 row_mask:0xf bank_mask:0xf
	v_mov_b32_dpp v210, v116 row_shr:2 row_mask:0xf bank_mask:0xf
	v_mov_b32_dpp v207, v117 row_shr:1 row_mask:0xf bank_mask:0xf
	v_mov_b32_dpp v211, v117 row_shr:2 row_mask:0xf bank_mask:0xf
	s_waitcnt vmcnt(36)
	v_mov_b32_dpp v223, v174 row_shl:1 row_mask:0xf bank_mask:0xf
	v_mov_b32_dpp v224, v175 row_shl:1 row_mask:0xf bank_mask:0xf
	v_mov_b32_dpp v225, v176 row_shl:1 row_mask:0xf bank_mask:0xf
	v_mov_b32_dpp v226, v177 row_shl:1 row_mask:0xf bank_mask:0xf
	v_cndmask_b32_e64 v208, v208, v174, s[48:49]
	v_cndmask_b32_e64 v209, v209, v175, s[48:49]
	v_cndmask_b32_e64 v210, v210, v176, s[48:49]
	v_cndmask_b32_e64 v211, v211, v177, s[48:49]
	v_cndmask_b32_e64 v204, v204, v223, s[46:47]
	v_cndmask_b32_e64 v205, v205, v224, s[46:47]
	v_cndmask_b32_e64 v206, v206, v225, s[46:47]
	v_cndmask_b32_e64 v207, v207, v226, s[46:47]
	s_mov_b64 exec, s[48:49]
	v_add_u32_e32 v222, 0x44c00, v190
	global_load_dwordx4 v[174:177], v222, s[16:17]
	s_mov_b64 exec, -1
	v_pk_fma_f32 v[216:217], v[150:151], v[204:205], v[216:217]
	v_pk_fma_f32 v[218:219], v[152:153], v[206:207], v[218:219]
	v_pk_fma_f32 v[216:217], v[146:147], v[208:209], v[216:217]
	v_pk_fma_f32 v[218:219], v[148:149], v[210:211], v[218:219]
	v_mul_f32_e32 v204, 0xbfb8aa3b, v216
	v_mul_f32_e32 v205, 0xbfb8aa3b, v217
	v_mul_f32_e32 v206, 0xbfb8aa3b, v218
	v_mul_f32_e32 v207, 0xbfb8aa3b, v219
	v_exp_f32_e32 v204, v204
	v_exp_f32_e32 v205, v205
	v_exp_f32_e32 v206, v206
	v_exp_f32_e32 v207, v207
	v_add_f32_e32 v204, 1.0, v204
	v_add_f32_e32 v205, 1.0, v205
	v_add_f32_e32 v206, 1.0, v206
	v_add_f32_e32 v207, 1.0, v207
	v_rcp_f32_e32 v204, v204
	v_rcp_f32_e32 v205, v205
	v_rcp_f32_e32 v206, v206
	v_rcp_f32_e32 v207, v207
	v_mul_f32_e32 v204, v216, v204
	v_mul_f32_e32 v205, v217, v205
	v_mul_f32_e32 v206, v218, v206
	v_mul_f32_e32 v207, v219, v207
	v_mul_f32_e32 v204, v212, v204
	v_mul_f32_e32 v205, v213, v205
	v_mul_f32_e32 v206, v214, v206
	v_mul_f32_e32 v207, v215, v207
	v_cvt_pk_bf16_f32 v220, v204, v205
	v_cvt_pk_bf16_f32 v221, v206, v207
	v_add_u32_e32 v222, 0x16000, v231
	global_store_dwordx2 v222, v[220:221], s[36:37]
	v_pk_fma_f32 v[212:213], v[138:139], v[110:111], v[142:143]
	v_pk_fma_f32 v[214:215], v[140:141], v[112:113], v[144:145]
	s_nop 2
	v_mov_b32_dpp v204, v110 row_shr:1 row_mask:0xf bank_mask:0xf
	v_mov_b32_dpp v208, v110 row_shr:2 row_mask:0xf bank_mask:0xf
	v_mov_b32_dpp v205, v111 row_shr:1 row_mask:0xf bank_mask:0xf
	v_mov_b32_dpp v209, v111 row_shr:2 row_mask:0xf bank_mask:0xf
	v_mov_b32_dpp v206, v112 row_shr:1 row_mask:0xf bank_mask:0xf
	v_mov_b32_dpp v210, v112 row_shr:2 row_mask:0xf bank_mask:0xf
	v_mov_b32_dpp v207, v113 row_shr:1 row_mask:0xf bank_mask:0xf
	v_mov_b32_dpp v211, v113 row_shr:2 row_mask:0xf bank_mask:0xf
	s_waitcnt vmcnt(5)
	v_mov_b32_dpp v223, v162 row_shl:1 row_mask:0xf bank_mask:0xf
	v_mov_b32_dpp v224, v163 row_shl:1 row_mask:0xf bank_mask:0xf
	v_mov_b32_dpp v225, v164 row_shl:1 row_mask:0xf bank_mask:0xf
	v_mov_b32_dpp v226, v165 row_shl:1 row_mask:0xf bank_mask:0xf
	v_cndmask_b32_e64 v208, v208, v162, s[48:49]
	v_cndmask_b32_e64 v209, v209, v163, s[48:49]
	v_cndmask_b32_e64 v210, v210, v164, s[48:49]
	v_cndmask_b32_e64 v211, v211, v165, s[48:49]
	v_cndmask_b32_e64 v204, v204, v223, s[46:47]
	v_cndmask_b32_e64 v205, v205, v224, s[46:47]
	v_cndmask_b32_e64 v206, v206, v225, s[46:47]
	v_cndmask_b32_e64 v207, v207, v226, s[46:47]
	s_mov_b64 exec, s[48:49]
	v_add_u32_e32 v222, 0xb0000, v190
	global_load_dwordx4 v[162:165], v222, s[16:17]
	s_mov_b64 exec, -1
	v_pk_fma_f32 v[212:213], v[134:135], v[204:205], v[212:213]
	v_pk_fma_f32 v[214:215], v[136:137], v[206:207], v[214:215]
	v_pk_fma_f32 v[212:213], v[130:131], v[208:209], v[212:213]
	v_pk_fma_f32 v[214:215], v[132:133], v[210:211], v[214:215]
	v_pk_fma_f32 v[216:217], v[154:155], v[106:107], v[158:159]
	v_pk_fma_f32 v[218:219], v[156:157], v[108:109], v[160:161]
	s_nop 2
	v_mov_b32_dpp v204, v106 row_shr:1 row_mask:0xf bank_mask:0xf
	v_mov_b32_dpp v208, v106 row_shr:2 row_mask:0xf bank_mask:0xf
	v_mov_b32_dpp v205, v107 row_shr:1 row_mask:0xf bank_mask:0xf
	v_mov_b32_dpp v209, v107 row_shr:2 row_mask:0xf bank_mask:0xf
	v_mov_b32_dpp v206, v108 row_shr:1 row_mask:0xf bank_mask:0xf
	v_mov_b32_dpp v210, v108 row_shr:2 row_mask:0xf bank_mask:0xf
	v_mov_b32_dpp v207, v109 row_shr:1 row_mask:0xf bank_mask:0xf
	v_mov_b32_dpp v211, v109 row_shr:2 row_mask:0xf bank_mask:0xf
	s_waitcnt vmcnt(5)
	v_mov_b32_dpp v223, v166 row_shl:1 row_mask:0xf bank_mask:0xf
	v_mov_b32_dpp v224, v167 row_shl:1 row_mask:0xf bank_mask:0xf
	v_mov_b32_dpp v225, v168 row_shl:1 row_mask:0xf bank_mask:0xf
	v_mov_b32_dpp v226, v169 row_shl:1 row_mask:0xf bank_mask:0xf
	v_cndmask_b32_e64 v208, v208, v166, s[48:49]
	v_cndmask_b32_e64 v209, v209, v167, s[48:49]
	v_cndmask_b32_e64 v210, v210, v168, s[48:49]
	v_cndmask_b32_e64 v211, v211, v169, s[48:49]
	v_cndmask_b32_e64 v204, v204, v223, s[46:47]
	v_cndmask_b32_e64 v205, v205, v224, s[46:47]
	v_cndmask_b32_e64 v206, v206, v225, s[46:47]
	v_cndmask_b32_e64 v207, v207, v226, s[46:47]
	s_mov_b64 exec, s[48:49]
	v_add_u32_e32 v222, 0xb2c00, v190
	global_load_dwordx4 v[166:169], v222, s[16:17]
	s_mov_b64 exec, -1
	v_pk_fma_f32 v[216:217], v[150:151], v[204:205], v[216:217]
	v_pk_fma_f32 v[218:219], v[152:153], v[206:207], v[218:219]
	v_pk_fma_f32 v[216:217], v[146:147], v[208:209], v[216:217]
	v_pk_fma_f32 v[218:219], v[148:149], v[210:211], v[218:219]
	v_mul_f32_e32 v204, 0xbfb8aa3b, v216
	v_mul_f32_e32 v205, 0xbfb8aa3b, v217
	v_mul_f32_e32 v206, 0xbfb8aa3b, v218
	v_mul_f32_e32 v207, 0xbfb8aa3b, v219
	v_exp_f32_e32 v204, v204
	v_exp_f32_e32 v205, v205
	v_exp_f32_e32 v206, v206
	v_exp_f32_e32 v207, v207
	v_add_f32_e32 v204, 1.0, v204
	v_add_f32_e32 v205, 1.0, v205
	v_add_f32_e32 v206, 1.0, v206
	v_add_f32_e32 v207, 1.0, v207
	v_rcp_f32_e32 v204, v204
	v_rcp_f32_e32 v205, v205
	v_rcp_f32_e32 v206, v206
	v_rcp_f32_e32 v207, v207
	v_mul_f32_e32 v204, v216, v204
	v_mul_f32_e32 v205, v217, v205
	v_mul_f32_e32 v206, v218, v206
	v_mul_f32_e32 v207, v219, v207
	v_mul_f32_e32 v204, v212, v204
	v_mul_f32_e32 v205, v213, v205
	v_mul_f32_e32 v206, v214, v206
	v_mul_f32_e32 v207, v215, v207
	v_cvt_pk_bf16_f32 v220, v204, v205
	v_cvt_pk_bf16_f32 v221, v206, v207
	v_add_u32_e32 v222, 0x2c000, v231
	global_store_dwordx2 v222, v[220:221], s[36:37]
	v_pk_fma_f32 v[212:213], v[138:139], v[102:103], v[142:143]
	v_pk_fma_f32 v[214:215], v[140:141], v[104:105], v[144:145]
	s_nop 2
	v_mov_b32_dpp v204, v102 row_shr:1 row_mask:0xf bank_mask:0xf
	v_mov_b32_dpp v208, v102 row_shr:2 row_mask:0xf bank_mask:0xf
	v_mov_b32_dpp v205, v103 row_shr:1 row_mask:0xf bank_mask:0xf
	v_mov_b32_dpp v209, v103 row_shr:2 row_mask:0xf bank_mask:0xf
	v_mov_b32_dpp v206, v104 row_shr:1 row_mask:0xf bank_mask:0xf
	v_mov_b32_dpp v210, v104 row_shr:2 row_mask:0xf bank_mask:0xf
	v_mov_b32_dpp v207, v105 row_shr:1 row_mask:0xf bank_mask:0xf
	v_mov_b32_dpp v211, v105 row_shr:2 row_mask:0xf bank_mask:0xf
	s_waitcnt vmcnt(5)
	v_mov_b32_dpp v223, v170 row_shl:1 row_mask:0xf bank_mask:0xf
	v_mov_b32_dpp v224, v171 row_shl:1 row_mask:0xf bank_mask:0xf
	v_mov_b32_dpp v225, v172 row_shl:1 row_mask:0xf bank_mask:0xf
	v_mov_b32_dpp v226, v173 row_shl:1 row_mask:0xf bank_mask:0xf
	v_cndmask_b32_e64 v208, v208, v170, s[48:49]
	v_cndmask_b32_e64 v209, v209, v171, s[48:49]
	v_cndmask_b32_e64 v210, v210, v172, s[48:49]
	v_cndmask_b32_e64 v211, v211, v173, s[48:49]
	v_cndmask_b32_e64 v204, v204, v223, s[46:47]
	v_cndmask_b32_e64 v205, v205, v224, s[46:47]
	v_cndmask_b32_e64 v206, v206, v225, s[46:47]
	v_cndmask_b32_e64 v207, v207, v226, s[46:47]
	s_mov_b64 exec, s[48:49]
	v_add_u32_e32 v222, 0xc6000, v190
	global_load_dwordx4 v[170:173], v222, s[16:17]
	s_mov_b64 exec, -1
	v_pk_fma_f32 v[212:213], v[134:135], v[204:205], v[212:213]
	v_pk_fma_f32 v[214:215], v[136:137], v[206:207], v[214:215]
	v_pk_fma_f32 v[212:213], v[130:131], v[208:209], v[212:213]
	v_pk_fma_f32 v[214:215], v[132:133], v[210:211], v[214:215]
	v_pk_fma_f32 v[216:217], v[154:155], v[98:99], v[158:159]
	v_pk_fma_f32 v[218:219], v[156:157], v[100:101], v[160:161]
	s_nop 2
	v_mov_b32_dpp v204, v98 row_shr:1 row_mask:0xf bank_mask:0xf
	v_mov_b32_dpp v208, v98 row_shr:2 row_mask:0xf bank_mask:0xf
	v_mov_b32_dpp v205, v99 row_shr:1 row_mask:0xf bank_mask:0xf
	v_mov_b32_dpp v209, v99 row_shr:2 row_mask:0xf bank_mask:0xf
	v_mov_b32_dpp v206, v100 row_shr:1 row_mask:0xf bank_mask:0xf
	v_mov_b32_dpp v210, v100 row_shr:2 row_mask:0xf bank_mask:0xf
	v_mov_b32_dpp v207, v101 row_shr:1 row_mask:0xf bank_mask:0xf
	v_mov_b32_dpp v211, v101 row_shr:2 row_mask:0xf bank_mask:0xf
	s_waitcnt vmcnt(5)
	v_mov_b32_dpp v223, v174 row_shl:1 row_mask:0xf bank_mask:0xf
	v_mov_b32_dpp v224, v175 row_shl:1 row_mask:0xf bank_mask:0xf
	v_mov_b32_dpp v225, v176 row_shl:1 row_mask:0xf bank_mask:0xf
	v_mov_b32_dpp v226, v177 row_shl:1 row_mask:0xf bank_mask:0xf
	v_cndmask_b32_e64 v208, v208, v174, s[48:49]
	v_cndmask_b32_e64 v209, v209, v175, s[48:49]
	v_cndmask_b32_e64 v210, v210, v176, s[48:49]
	v_cndmask_b32_e64 v211, v211, v177, s[48:49]
	v_cndmask_b32_e64 v204, v204, v223, s[46:47]
	v_cndmask_b32_e64 v205, v205, v224, s[46:47]
	v_cndmask_b32_e64 v206, v206, v225, s[46:47]
	v_cndmask_b32_e64 v207, v207, v226, s[46:47]
	s_mov_b64 exec, s[48:49]
	v_add_u32_e32 v222, 0xc8c00, v190
	global_load_dwordx4 v[174:177], v222, s[16:17]
	s_mov_b64 exec, -1
	v_pk_fma_f32 v[216:217], v[150:151], v[204:205], v[216:217]
	v_pk_fma_f32 v[218:219], v[152:153], v[206:207], v[218:219]
	v_pk_fma_f32 v[216:217], v[146:147], v[208:209], v[216:217]
	v_pk_fma_f32 v[218:219], v[148:149], v[210:211], v[218:219]
	v_mul_f32_e32 v204, 0xbfb8aa3b, v216
	v_mul_f32_e32 v205, 0xbfb8aa3b, v217
	v_mul_f32_e32 v206, 0xbfb8aa3b, v218
	v_mul_f32_e32 v207, 0xbfb8aa3b, v219
	v_exp_f32_e32 v204, v204
	v_exp_f32_e32 v205, v205
	v_exp_f32_e32 v206, v206
	v_exp_f32_e32 v207, v207
	v_add_f32_e32 v204, 1.0, v204
	v_add_f32_e32 v205, 1.0, v205
	v_add_f32_e32 v206, 1.0, v206
	v_add_f32_e32 v207, 1.0, v207
	v_rcp_f32_e32 v204, v204
	v_rcp_f32_e32 v205, v205
	v_rcp_f32_e32 v206, v206
	v_rcp_f32_e32 v207, v207
	v_mul_f32_e32 v204, v216, v204
	v_mul_f32_e32 v205, v217, v205
	v_mul_f32_e32 v206, v218, v206
	v_mul_f32_e32 v207, v219, v207
	v_mul_f32_e32 v204, v212, v204
	v_mul_f32_e32 v205, v213, v205
	v_mul_f32_e32 v206, v214, v206
	v_mul_f32_e32 v207, v215, v207
	v_cvt_pk_bf16_f32 v220, v204, v205
	v_cvt_pk_bf16_f32 v221, v206, v207
	v_add_u32_e32 v222, 0x42000, v231
	global_store_dwordx2 v222, v[220:221], s[36:37]
	global_load_dwordx4 v[98:101], v232, s[40:41] offset:16
	v_add_u32_e32 v204, 0x5800, v232
	global_load_dwordx4 v[102:105], v204, s[40:41] offset:16
	v_add_u32_e32 v205, 0xb000, v232
	global_load_dwordx4 v[106:109], v205, s[40:41] offset:16
	global_load_dwordx4 v[110:113], v232, s[42:43] offset:16
	v_add_u32_e32 v206, 0x2c00, v232
	global_load_dwordx4 v[114:117], v206, s[40:41] offset:16
	v_add_u32_e32 v207, 0x8400, v232
	global_load_dwordx4 v[118:121], v207, s[40:41] offset:16
	v_add_u32_e32 v208, 0xdc00, v232
	global_load_dwordx4 v[122:125], v208, s[40:41] offset:16
	v_add_u32_e32 v209, 0x2c00, v232
	global_load_dwordx4 v[126:129], v209, s[42:43] offset:16
	s_mov_b64 exec, s[50:51]
	v_add_u32_e32 v223, 0x10, v235
	global_store_dwordx4 v223, v[62:65], s[44:45]
	v_add_u32_e32 v224, 0x2c10, v235
	global_store_dwordx4 v224, v[58:61], s[44:45]
	v_add_u32_e32 v225, 0x16010, v235
	global_store_dwordx4 v225, v[54:57], s[44:45]
	v_add_u32_e32 v226, 0x18c10, v235
	global_store_dwordx4 v226, v[50:53], s[44:45]
	v_add_u32_e32 v223, 0x2c010, v235
	global_store_dwordx4 v223, v[46:49], s[44:45]
	v_add_u32_e32 v224, 0x2ec10, v235
	global_store_dwordx4 v224, v[42:45], s[44:45]
	v_add_u32_e32 v225, 0x42010, v235
	global_store_dwordx4 v225, v[38:41], s[44:45]
	v_add_u32_e32 v226, 0x44c10, v235
	global_store_dwordx4 v226, v[34:37], s[44:45]
	v_add_u32_e32 v223, 0xb0010, v235
	global_store_dwordx4 v223, v[30:33], s[44:45]
	v_add_u32_e32 v224, 0xb2c10, v235
	global_store_dwordx4 v224, v[26:29], s[44:45]
	v_add_u32_e32 v225, 0xc6010, v235
	global_store_dwordx4 v225, v[22:25], s[44:45]
	v_add_u32_e32 v226, 0xc8c10, v235
	global_store_dwordx4 v226, v[18:21], s[44:45]
	v_add_u32_e32 v223, 0xdc010, v235
	global_store_dwordx4 v223, v[14:17], s[44:45]
	v_add_u32_e32 v224, 0xdec10, v235
	global_store_dwordx4 v224, v[10:13], s[44:45]
	v_add_u32_e32 v225, 0xf2010, v235
	global_store_dwordx4 v225, v[6:9], s[44:45]
	v_add_u32_e32 v226, 0xf4c10, v235
	global_store_dwordx4 v226, v[2:5], s[44:45]
	s_mov_b64 exec, -1
	v_pk_fma_f32 v[212:213], v[138:139], v[94:95], v[142:143]
	v_pk_fma_f32 v[214:215], v[140:141], v[96:97], v[144:145]
	s_nop 2
	v_mov_b32_dpp v204, v94 row_shr:1 row_mask:0xf bank_mask:0xf
	v_mov_b32_dpp v208, v94 row_shr:2 row_mask:0xf bank_mask:0xf
	v_mov_b32_dpp v205, v95 row_shr:1 row_mask:0xf bank_mask:0xf
	v_mov_b32_dpp v209, v95 row_shr:2 row_mask:0xf bank_mask:0xf
	v_mov_b32_dpp v206, v96 row_shr:1 row_mask:0xf bank_mask:0xf
	v_mov_b32_dpp v210, v96 row_shr:2 row_mask:0xf bank_mask:0xf
	v_mov_b32_dpp v207, v97 row_shr:1 row_mask:0xf bank_mask:0xf
	v_mov_b32_dpp v211, v97 row_shr:2 row_mask:0xf bank_mask:0xf
	s_waitcnt vmcnt(29)
	v_mov_b32_dpp v223, v162 row_shl:1 row_mask:0xf bank_mask:0xf
	v_mov_b32_dpp v224, v163 row_shl:1 row_mask:0xf bank_mask:0xf
	v_mov_b32_dpp v225, v164 row_shl:1 row_mask:0xf bank_mask:0xf
	v_mov_b32_dpp v226, v165 row_shl:1 row_mask:0xf bank_mask:0xf
	v_cndmask_b32_e64 v208, v208, v162, s[48:49]
	v_cndmask_b32_e64 v209, v209, v163, s[48:49]
	v_cndmask_b32_e64 v210, v210, v164, s[48:49]
	v_cndmask_b32_e64 v211, v211, v165, s[48:49]
	v_cndmask_b32_e64 v204, v204, v223, s[46:47]
	v_cndmask_b32_e64 v205, v205, v224, s[46:47]
	v_cndmask_b32_e64 v206, v206, v225, s[46:47]
	v_cndmask_b32_e64 v207, v207, v226, s[46:47]
	s_mov_b64 exec, s[48:49]
	v_add_u32_e32 v222, 0xdc000, v190
	global_load_dwordx4 v[162:165], v222, s[16:17]
	s_mov_b64 exec, -1
	v_pk_fma_f32 v[212:213], v[134:135], v[204:205], v[212:213]
	v_pk_fma_f32 v[214:215], v[136:137], v[206:207], v[214:215]
	v_pk_fma_f32 v[212:213], v[130:131], v[208:209], v[212:213]
	v_pk_fma_f32 v[214:215], v[132:133], v[210:211], v[214:215]
	v_pk_fma_f32 v[216:217], v[154:155], v[90:91], v[158:159]
	v_pk_fma_f32 v[218:219], v[156:157], v[92:93], v[160:161]
	s_nop 2
	v_mov_b32_dpp v204, v90 row_shr:1 row_mask:0xf bank_mask:0xf
	v_mov_b32_dpp v208, v90 row_shr:2 row_mask:0xf bank_mask:0xf
	v_mov_b32_dpp v205, v91 row_shr:1 row_mask:0xf bank_mask:0xf
	v_mov_b32_dpp v209, v91 row_shr:2 row_mask:0xf bank_mask:0xf
	v_mov_b32_dpp v206, v92 row_shr:1 row_mask:0xf bank_mask:0xf
	v_mov_b32_dpp v210, v92 row_shr:2 row_mask:0xf bank_mask:0xf
	v_mov_b32_dpp v207, v93 row_shr:1 row_mask:0xf bank_mask:0xf
	v_mov_b32_dpp v211, v93 row_shr:2 row_mask:0xf bank_mask:0xf
	s_waitcnt vmcnt(29)
	v_mov_b32_dpp v223, v166 row_shl:1 row_mask:0xf bank_mask:0xf
	v_mov_b32_dpp v224, v167 row_shl:1 row_mask:0xf bank_mask:0xf
	v_mov_b32_dpp v225, v168 row_shl:1 row_mask:0xf bank_mask:0xf
	v_mov_b32_dpp v226, v169 row_shl:1 row_mask:0xf bank_mask:0xf
	v_cndmask_b32_e64 v208, v208, v166, s[48:49]
	v_cndmask_b32_e64 v209, v209, v167, s[48:49]
	v_cndmask_b32_e64 v210, v210, v168, s[48:49]
	v_cndmask_b32_e64 v211, v211, v169, s[48:49]
	v_cndmask_b32_e64 v204, v204, v223, s[46:47]
	v_cndmask_b32_e64 v205, v205, v224, s[46:47]
	v_cndmask_b32_e64 v206, v206, v225, s[46:47]
	v_cndmask_b32_e64 v207, v207, v226, s[46:47]
	s_mov_b64 exec, s[48:49]
	v_add_u32_e32 v222, 0xdec00, v190
	global_load_dwordx4 v[166:169], v222, s[16:17]
	s_mov_b64 exec, -1
	v_pk_fma_f32 v[216:217], v[150:151], v[204:205], v[216:217]
	v_pk_fma_f32 v[218:219], v[152:153], v[206:207], v[218:219]
	v_pk_fma_f32 v[216:217], v[146:147], v[208:209], v[216:217]
	v_pk_fma_f32 v[218:219], v[148:149], v[210:211], v[218:219]
	v_mul_f32_e32 v204, 0xbfb8aa3b, v216
	v_mul_f32_e32 v205, 0xbfb8aa3b, v217
	v_mul_f32_e32 v206, 0xbfb8aa3b, v218
	v_mul_f32_e32 v207, 0xbfb8aa3b, v219
	v_exp_f32_e32 v204, v204
	v_exp_f32_e32 v205, v205
	v_exp_f32_e32 v206, v206
	v_exp_f32_e32 v207, v207
	v_add_f32_e32 v204, 1.0, v204
	v_add_f32_e32 v205, 1.0, v205
	v_add_f32_e32 v206, 1.0, v206
	v_add_f32_e32 v207, 1.0, v207
	v_rcp_f32_e32 v204, v204
	v_rcp_f32_e32 v205, v205
	v_rcp_f32_e32 v206, v206
	v_rcp_f32_e32 v207, v207
	v_mul_f32_e32 v204, v216, v204
	v_mul_f32_e32 v205, v217, v205
	v_mul_f32_e32 v206, v218, v206
	v_mul_f32_e32 v207, v219, v207
	v_mul_f32_e32 v204, v212, v204
	v_mul_f32_e32 v205, v213, v205
	v_mul_f32_e32 v206, v214, v206
	v_mul_f32_e32 v207, v215, v207
	v_cvt_pk_bf16_f32 v94, v204, v205
	v_cvt_pk_bf16_f32 v95, v206, v207
	v_pk_fma_f32 v[212:213], v[138:139], v[86:87], v[142:143]
	v_pk_fma_f32 v[214:215], v[140:141], v[88:89], v[144:145]
	s_nop 2
	v_mov_b32_dpp v204, v86 row_shr:1 row_mask:0xf bank_mask:0xf
	v_mov_b32_dpp v208, v86 row_shr:2 row_mask:0xf bank_mask:0xf
	v_mov_b32_dpp v205, v87 row_shr:1 row_mask:0xf bank_mask:0xf
	v_mov_b32_dpp v209, v87 row_shr:2 row_mask:0xf bank_mask:0xf
	v_mov_b32_dpp v206, v88 row_shr:1 row_mask:0xf bank_mask:0xf
	v_mov_b32_dpp v210, v88 row_shr:2 row_mask:0xf bank_mask:0xf
	v_mov_b32_dpp v207, v89 row_shr:1 row_mask:0xf bank_mask:0xf
	v_mov_b32_dpp v211, v89 row_shr:2 row_mask:0xf bank_mask:0xf
	s_waitcnt vmcnt(28)
	v_mov_b32_dpp v223, v170 row_shl:1 row_mask:0xf bank_mask:0xf
	v_mov_b32_dpp v224, v171 row_shl:1 row_mask:0xf bank_mask:0xf
	v_mov_b32_dpp v225, v172 row_shl:1 row_mask:0xf bank_mask:0xf
	v_mov_b32_dpp v226, v173 row_shl:1 row_mask:0xf bank_mask:0xf
	v_cndmask_b32_e64 v208, v208, v170, s[48:49]
	v_cndmask_b32_e64 v209, v209, v171, s[48:49]
	v_cndmask_b32_e64 v210, v210, v172, s[48:49]
	v_cndmask_b32_e64 v211, v211, v173, s[48:49]
	v_cndmask_b32_e64 v204, v204, v223, s[46:47]
	v_cndmask_b32_e64 v205, v205, v224, s[46:47]
	v_cndmask_b32_e64 v206, v206, v225, s[46:47]
	v_cndmask_b32_e64 v207, v207, v226, s[46:47]
	s_mov_b64 exec, s[48:49]
	v_add_u32_e32 v222, 0xf2000, v190
	global_load_dwordx4 v[170:173], v222, s[16:17]
	s_mov_b64 exec, -1
	v_pk_fma_f32 v[212:213], v[134:135], v[204:205], v[212:213]
	v_pk_fma_f32 v[214:215], v[136:137], v[206:207], v[214:215]
	v_pk_fma_f32 v[212:213], v[130:131], v[208:209], v[212:213]
	v_pk_fma_f32 v[214:215], v[132:133], v[210:211], v[214:215]
	v_pk_fma_f32 v[216:217], v[154:155], v[82:83], v[158:159]
	v_pk_fma_f32 v[218:219], v[156:157], v[84:85], v[160:161]
	s_nop 2
	v_mov_b32_dpp v204, v82 row_shr:1 row_mask:0xf bank_mask:0xf
	v_mov_b32_dpp v208, v82 row_shr:2 row_mask:0xf bank_mask:0xf
	v_mov_b32_dpp v205, v83 row_shr:1 row_mask:0xf bank_mask:0xf
	v_mov_b32_dpp v209, v83 row_shr:2 row_mask:0xf bank_mask:0xf
	v_mov_b32_dpp v206, v84 row_shr:1 row_mask:0xf bank_mask:0xf
	v_mov_b32_dpp v210, v84 row_shr:2 row_mask:0xf bank_mask:0xf
	v_mov_b32_dpp v207, v85 row_shr:1 row_mask:0xf bank_mask:0xf
	v_mov_b32_dpp v211, v85 row_shr:2 row_mask:0xf bank_mask:0xf
	s_waitcnt vmcnt(28)
	v_mov_b32_dpp v223, v174 row_shl:1 row_mask:0xf bank_mask:0xf
	v_mov_b32_dpp v224, v175 row_shl:1 row_mask:0xf bank_mask:0xf
	v_mov_b32_dpp v225, v176 row_shl:1 row_mask:0xf bank_mask:0xf
	v_mov_b32_dpp v226, v177 row_shl:1 row_mask:0xf bank_mask:0xf
	v_cndmask_b32_e64 v208, v208, v174, s[48:49]
	v_cndmask_b32_e64 v209, v209, v175, s[48:49]
	v_cndmask_b32_e64 v210, v210, v176, s[48:49]
	v_cndmask_b32_e64 v211, v211, v177, s[48:49]
	v_cndmask_b32_e64 v204, v204, v223, s[46:47]
	v_cndmask_b32_e64 v205, v205, v224, s[46:47]
	v_cndmask_b32_e64 v206, v206, v225, s[46:47]
	v_cndmask_b32_e64 v207, v207, v226, s[46:47]
	s_mov_b64 exec, s[48:49]
	v_add_u32_e32 v222, 0xf4c00, v190
	global_load_dwordx4 v[174:177], v222, s[16:17]
	s_mov_b64 exec, -1
	v_pk_fma_f32 v[216:217], v[150:151], v[204:205], v[216:217]
	v_pk_fma_f32 v[218:219], v[152:153], v[206:207], v[218:219]
	v_pk_fma_f32 v[216:217], v[146:147], v[208:209], v[216:217]
	v_pk_fma_f32 v[218:219], v[148:149], v[210:211], v[218:219]
	v_mul_f32_e32 v204, 0xbfb8aa3b, v216
	v_mul_f32_e32 v205, 0xbfb8aa3b, v217
	v_mul_f32_e32 v206, 0xbfb8aa3b, v218
	v_mul_f32_e32 v207, 0xbfb8aa3b, v219
	v_exp_f32_e32 v204, v204
	v_exp_f32_e32 v205, v205
	v_exp_f32_e32 v206, v206
	v_exp_f32_e32 v207, v207
	v_add_f32_e32 v204, 1.0, v204
	v_add_f32_e32 v205, 1.0, v205
	v_add_f32_e32 v206, 1.0, v206
	v_add_f32_e32 v207, 1.0, v207
	v_rcp_f32_e32 v204, v204
	v_rcp_f32_e32 v205, v205
	v_rcp_f32_e32 v206, v206
	v_rcp_f32_e32 v207, v207
	v_mul_f32_e32 v204, v216, v204
	v_mul_f32_e32 v205, v217, v205
	v_mul_f32_e32 v206, v218, v206
	v_mul_f32_e32 v207, v219, v207
	v_mul_f32_e32 v204, v212, v204
	v_mul_f32_e32 v205, v213, v205
	v_mul_f32_e32 v206, v214, v206
	v_mul_f32_e32 v207, v215, v207
	v_cvt_pk_bf16_f32 v86, v204, v205
	v_cvt_pk_bf16_f32 v87, v206, v207
	v_pk_fma_f32 v[212:213], v[138:139], v[78:79], v[142:143]
	v_pk_fma_f32 v[214:215], v[140:141], v[80:81], v[144:145]
	s_nop 2
	v_mov_b32_dpp v204, v78 row_shr:1 row_mask:0xf bank_mask:0xf
	v_mov_b32_dpp v208, v78 row_shr:2 row_mask:0xf bank_mask:0xf
	v_mov_b32_dpp v205, v79 row_shr:1 row_mask:0xf bank_mask:0xf
	v_mov_b32_dpp v209, v79 row_shr:2 row_mask:0xf bank_mask:0xf
	v_mov_b32_dpp v206, v80 row_shr:1 row_mask:0xf bank_mask:0xf
	v_mov_b32_dpp v210, v80 row_shr:2 row_mask:0xf bank_mask:0xf
	v_mov_b32_dpp v207, v81 row_shr:1 row_mask:0xf bank_mask:0xf
	v_mov_b32_dpp v211, v81 row_shr:2 row_mask:0xf bank_mask:0xf
	s_waitcnt vmcnt(3)
	v_mov_b32_dpp v223, v162 row_shl:1 row_mask:0xf bank_mask:0xf
	v_mov_b32_dpp v224, v163 row_shl:1 row_mask:0xf bank_mask:0xf
	v_mov_b32_dpp v225, v164 row_shl:1 row_mask:0xf bank_mask:0xf
	v_mov_b32_dpp v226, v165 row_shl:1 row_mask:0xf bank_mask:0xf
	v_cndmask_b32_e64 v208, v208, v162, s[48:49]
	v_cndmask_b32_e64 v209, v209, v163, s[48:49]
	v_cndmask_b32_e64 v210, v210, v164, s[48:49]
	v_cndmask_b32_e64 v211, v211, v165, s[48:49]
	v_cndmask_b32_e64 v204, v204, v223, s[46:47]
	v_cndmask_b32_e64 v205, v205, v224, s[46:47]
	v_cndmask_b32_e64 v206, v206, v225, s[46:47]
	v_cndmask_b32_e64 v207, v207, v226, s[46:47]
	s_mov_b64 exec, s[48:49]
	global_load_dwordx4 v[162:165], v190, s[16:17] offset:16
	s_mov_b64 exec, -1
	v_pk_fma_f32 v[212:213], v[134:135], v[204:205], v[212:213]
	v_pk_fma_f32 v[214:215], v[136:137], v[206:207], v[214:215]
	v_pk_fma_f32 v[212:213], v[130:131], v[208:209], v[212:213]
	v_pk_fma_f32 v[214:215], v[132:133], v[210:211], v[214:215]
	v_pk_fma_f32 v[216:217], v[154:155], v[74:75], v[158:159]
	v_pk_fma_f32 v[218:219], v[156:157], v[76:77], v[160:161]
	s_nop 2
	v_mov_b32_dpp v204, v74 row_shr:1 row_mask:0xf bank_mask:0xf
	v_mov_b32_dpp v208, v74 row_shr:2 row_mask:0xf bank_mask:0xf
	v_mov_b32_dpp v205, v75 row_shr:1 row_mask:0xf bank_mask:0xf
	v_mov_b32_dpp v209, v75 row_shr:2 row_mask:0xf bank_mask:0xf
	v_mov_b32_dpp v206, v76 row_shr:1 row_mask:0xf bank_mask:0xf
	v_mov_b32_dpp v210, v76 row_shr:2 row_mask:0xf bank_mask:0xf
	v_mov_b32_dpp v207, v77 row_shr:1 row_mask:0xf bank_mask:0xf
	v_mov_b32_dpp v211, v77 row_shr:2 row_mask:0xf bank_mask:0xf
	s_waitcnt vmcnt(3)
	v_mov_b32_dpp v223, v166 row_shl:1 row_mask:0xf bank_mask:0xf
	v_mov_b32_dpp v224, v167 row_shl:1 row_mask:0xf bank_mask:0xf
	v_mov_b32_dpp v225, v168 row_shl:1 row_mask:0xf bank_mask:0xf
	v_mov_b32_dpp v226, v169 row_shl:1 row_mask:0xf bank_mask:0xf
	v_cndmask_b32_e64 v208, v208, v166, s[48:49]
	v_cndmask_b32_e64 v209, v209, v167, s[48:49]
	v_cndmask_b32_e64 v210, v210, v168, s[48:49]
	v_cndmask_b32_e64 v211, v211, v169, s[48:49]
	v_cndmask_b32_e64 v204, v204, v223, s[46:47]
	v_cndmask_b32_e64 v205, v205, v224, s[46:47]
	v_cndmask_b32_e64 v206, v206, v225, s[46:47]
	v_cndmask_b32_e64 v207, v207, v226, s[46:47]
	s_mov_b64 exec, s[48:49]
	v_add_u32_e32 v222, 0x2c00, v190
	global_load_dwordx4 v[166:169], v222, s[16:17] offset:16
	s_mov_b64 exec, -1
	v_pk_fma_f32 v[216:217], v[150:151], v[204:205], v[216:217]
	v_pk_fma_f32 v[218:219], v[152:153], v[206:207], v[218:219]
	v_pk_fma_f32 v[216:217], v[146:147], v[208:209], v[216:217]
	v_pk_fma_f32 v[218:219], v[148:149], v[210:211], v[218:219]
	v_mul_f32_e32 v204, 0xbfb8aa3b, v216
	v_mul_f32_e32 v205, 0xbfb8aa3b, v217
	v_mul_f32_e32 v206, 0xbfb8aa3b, v218
	v_mul_f32_e32 v207, 0xbfb8aa3b, v219
	v_exp_f32_e32 v204, v204
	v_exp_f32_e32 v205, v205
	v_exp_f32_e32 v206, v206
	v_exp_f32_e32 v207, v207
	v_add_f32_e32 v204, 1.0, v204
	v_add_f32_e32 v205, 1.0, v205
	v_add_f32_e32 v206, 1.0, v206
	v_add_f32_e32 v207, 1.0, v207
	v_rcp_f32_e32 v204, v204
	v_rcp_f32_e32 v205, v205
	v_rcp_f32_e32 v206, v206
	v_rcp_f32_e32 v207, v207
	v_mul_f32_e32 v204, v216, v204
	v_mul_f32_e32 v205, v217, v205
	v_mul_f32_e32 v206, v218, v206
	v_mul_f32_e32 v207, v219, v207
	v_mul_f32_e32 v204, v212, v204
	v_mul_f32_e32 v205, v213, v205
	v_mul_f32_e32 v206, v214, v206
	v_mul_f32_e32 v207, v215, v207
	v_cvt_pk_bf16_f32 v78, v204, v205
	v_cvt_pk_bf16_f32 v79, v206, v207
	v_pk_fma_f32 v[212:213], v[138:139], v[70:71], v[142:143]
	v_pk_fma_f32 v[214:215], v[140:141], v[72:73], v[144:145]
	s_nop 2
	v_mov_b32_dpp v204, v70 row_shr:1 row_mask:0xf bank_mask:0xf
	v_mov_b32_dpp v208, v70 row_shr:2 row_mask:0xf bank_mask:0xf
	v_mov_b32_dpp v205, v71 row_shr:1 row_mask:0xf bank_mask:0xf
	v_mov_b32_dpp v209, v71 row_shr:2 row_mask:0xf bank_mask:0xf
	v_mov_b32_dpp v206, v72 row_shr:1 row_mask:0xf bank_mask:0xf
	v_mov_b32_dpp v210, v72 row_shr:2 row_mask:0xf bank_mask:0xf
	v_mov_b32_dpp v207, v73 row_shr:1 row_mask:0xf bank_mask:0xf
	v_mov_b32_dpp v211, v73 row_shr:2 row_mask:0xf bank_mask:0xf
	s_waitcnt vmcnt(3)
	v_mov_b32_dpp v223, v170 row_shl:1 row_mask:0xf bank_mask:0xf
	v_mov_b32_dpp v224, v171 row_shl:1 row_mask:0xf bank_mask:0xf
	v_mov_b32_dpp v225, v172 row_shl:1 row_mask:0xf bank_mask:0xf
	v_mov_b32_dpp v226, v173 row_shl:1 row_mask:0xf bank_mask:0xf
	v_cndmask_b32_e64 v208, v208, v170, s[48:49]
	v_cndmask_b32_e64 v209, v209, v171, s[48:49]
	v_cndmask_b32_e64 v210, v210, v172, s[48:49]
	v_cndmask_b32_e64 v211, v211, v173, s[48:49]
	v_cndmask_b32_e64 v204, v204, v223, s[46:47]
	v_cndmask_b32_e64 v205, v205, v224, s[46:47]
	v_cndmask_b32_e64 v206, v206, v225, s[46:47]
	v_cndmask_b32_e64 v207, v207, v226, s[46:47]
	s_mov_b64 exec, s[48:49]
	v_add_u32_e32 v222, 0x16000, v190
	global_load_dwordx4 v[170:173], v222, s[16:17] offset:16
	s_mov_b64 exec, -1
	v_pk_fma_f32 v[212:213], v[134:135], v[204:205], v[212:213]
	v_pk_fma_f32 v[214:215], v[136:137], v[206:207], v[214:215]
	v_pk_fma_f32 v[212:213], v[130:131], v[208:209], v[212:213]
	v_pk_fma_f32 v[214:215], v[132:133], v[210:211], v[214:215]
	v_pk_fma_f32 v[216:217], v[154:155], v[66:67], v[158:159]
	v_pk_fma_f32 v[218:219], v[156:157], v[68:69], v[160:161]
	s_nop 2
	v_mov_b32_dpp v204, v66 row_shr:1 row_mask:0xf bank_mask:0xf
	v_mov_b32_dpp v208, v66 row_shr:2 row_mask:0xf bank_mask:0xf
	v_mov_b32_dpp v205, v67 row_shr:1 row_mask:0xf bank_mask:0xf
	v_mov_b32_dpp v209, v67 row_shr:2 row_mask:0xf bank_mask:0xf
	v_mov_b32_dpp v206, v68 row_shr:1 row_mask:0xf bank_mask:0xf
	v_mov_b32_dpp v210, v68 row_shr:2 row_mask:0xf bank_mask:0xf
	v_mov_b32_dpp v207, v69 row_shr:1 row_mask:0xf bank_mask:0xf
	v_mov_b32_dpp v211, v69 row_shr:2 row_mask:0xf bank_mask:0xf
	s_waitcnt vmcnt(3)
	v_mov_b32_dpp v223, v174 row_shl:1 row_mask:0xf bank_mask:0xf
	v_mov_b32_dpp v224, v175 row_shl:1 row_mask:0xf bank_mask:0xf
	v_mov_b32_dpp v225, v176 row_shl:1 row_mask:0xf bank_mask:0xf
	v_mov_b32_dpp v226, v177 row_shl:1 row_mask:0xf bank_mask:0xf
	v_cndmask_b32_e64 v208, v208, v174, s[48:49]
	v_cndmask_b32_e64 v209, v209, v175, s[48:49]
	v_cndmask_b32_e64 v210, v210, v176, s[48:49]
	v_cndmask_b32_e64 v211, v211, v177, s[48:49]
	v_cndmask_b32_e64 v204, v204, v223, s[46:47]
	v_cndmask_b32_e64 v205, v205, v224, s[46:47]
	v_cndmask_b32_e64 v206, v206, v225, s[46:47]
	v_cndmask_b32_e64 v207, v207, v226, s[46:47]
	s_mov_b64 exec, s[48:49]
	v_add_u32_e32 v222, 0x18c00, v190
	global_load_dwordx4 v[174:177], v222, s[16:17] offset:16
	s_mov_b64 exec, -1
	v_pk_fma_f32 v[216:217], v[150:151], v[204:205], v[216:217]
	v_pk_fma_f32 v[218:219], v[152:153], v[206:207], v[218:219]
	v_pk_fma_f32 v[216:217], v[146:147], v[208:209], v[216:217]
	v_pk_fma_f32 v[218:219], v[148:149], v[210:211], v[218:219]
	v_mul_f32_e32 v204, 0xbfb8aa3b, v216
	v_mul_f32_e32 v205, 0xbfb8aa3b, v217
	v_mul_f32_e32 v206, 0xbfb8aa3b, v218
	v_mul_f32_e32 v207, 0xbfb8aa3b, v219
	v_exp_f32_e32 v204, v204
	v_exp_f32_e32 v205, v205
	v_exp_f32_e32 v206, v206
	v_exp_f32_e32 v207, v207
	v_add_f32_e32 v204, 1.0, v204
	v_add_f32_e32 v205, 1.0, v205
	v_add_f32_e32 v206, 1.0, v206
	v_add_f32_e32 v207, 1.0, v207
	v_rcp_f32_e32 v204, v204
	v_rcp_f32_e32 v205, v205
	v_rcp_f32_e32 v206, v206
	v_rcp_f32_e32 v207, v207
	v_mul_f32_e32 v204, v216, v204
	v_mul_f32_e32 v205, v217, v205
	v_mul_f32_e32 v206, v218, v206
	v_mul_f32_e32 v207, v219, v207
	v_mul_f32_e32 v204, v212, v204
	v_mul_f32_e32 v205, v213, v205
	v_mul_f32_e32 v206, v214, v206
	v_mul_f32_e32 v207, v215, v207
	v_cvt_pk_bf16_f32 v70, v204, v205
	v_cvt_pk_bf16_f32 v71, v206, v207
	s_waitcnt vmcnt(24)
	v_pk_fma_f32 v[212:213], v[106:107], v[62:63], v[110:111]
	v_pk_fma_f32 v[214:215], v[108:109], v[64:65], v[112:113]
	s_nop 2
	v_mov_b32_dpp v204, v62 row_shr:1 row_mask:0xf bank_mask:0xf
	v_mov_b32_dpp v208, v62 row_shr:2 row_mask:0xf bank_mask:0xf
	v_mov_b32_dpp v205, v63 row_shr:1 row_mask:0xf bank_mask:0xf
	v_mov_b32_dpp v209, v63 row_shr:2 row_mask:0xf bank_mask:0xf
	v_mov_b32_dpp v206, v64 row_shr:1 row_mask:0xf bank_mask:0xf
	v_mov_b32_dpp v210, v64 row_shr:2 row_mask:0xf bank_mask:0xf
	v_mov_b32_dpp v207, v65 row_shr:1 row_mask:0xf bank_mask:0xf
	v_mov_b32_dpp v211, v65 row_shr:2 row_mask:0xf bank_mask:0xf
	s_waitcnt vmcnt(3)
	v_mov_b32_dpp v223, v162 row_shl:1 row_mask:0xf bank_mask:0xf
	v_mov_b32_dpp v224, v163 row_shl:1 row_mask:0xf bank_mask:0xf
	v_mov_b32_dpp v225, v164 row_shl:1 row_mask:0xf bank_mask:0xf
	v_mov_b32_dpp v226, v165 row_shl:1 row_mask:0xf bank_mask:0xf
	v_cndmask_b32_e64 v208, v208, v162, s[48:49]
	v_cndmask_b32_e64 v209, v209, v163, s[48:49]
	v_cndmask_b32_e64 v210, v210, v164, s[48:49]
	v_cndmask_b32_e64 v211, v211, v165, s[48:49]
	v_cndmask_b32_e64 v204, v204, v223, s[46:47]
	v_cndmask_b32_e64 v205, v205, v224, s[46:47]
	v_cndmask_b32_e64 v206, v206, v225, s[46:47]
	v_cndmask_b32_e64 v207, v207, v226, s[46:47]
	s_mov_b64 exec, s[48:49]
	v_add_u32_e32 v222, 0x2c000, v190
	global_load_dwordx4 v[162:165], v222, s[16:17] offset:16
	s_mov_b64 exec, -1
	v_pk_fma_f32 v[212:213], v[102:103], v[204:205], v[212:213]
	v_pk_fma_f32 v[214:215], v[104:105], v[206:207], v[214:215]
	v_pk_fma_f32 v[212:213], v[98:99], v[208:209], v[212:213]
	v_pk_fma_f32 v[214:215], v[100:101], v[210:211], v[214:215]
	v_pk_fma_f32 v[216:217], v[122:123], v[58:59], v[126:127]
	v_pk_fma_f32 v[218:219], v[124:125], v[60:61], v[128:129]
	s_nop 2
	v_mov_b32_dpp v204, v58 row_shr:1 row_mask:0xf bank_mask:0xf
	v_mov_b32_dpp v208, v58 row_shr:2 row_mask:0xf bank_mask:0xf
	v_mov_b32_dpp v205, v59 row_shr:1 row_mask:0xf bank_mask:0xf
	v_mov_b32_dpp v209, v59 row_shr:2 row_mask:0xf bank_mask:0xf
	v_mov_b32_dpp v206, v60 row_shr:1 row_mask:0xf bank_mask:0xf
	v_mov_b32_dpp v210, v60 row_shr:2 row_mask:0xf bank_mask:0xf
	v_mov_b32_dpp v207, v61 row_shr:1 row_mask:0xf bank_mask:0xf
	v_mov_b32_dpp v211, v61 row_shr:2 row_mask:0xf bank_mask:0xf
	s_waitcnt vmcnt(3)
	v_mov_b32_dpp v223, v166 row_shl:1 row_mask:0xf bank_mask:0xf
	v_mov_b32_dpp v224, v167 row_shl:1 row_mask:0xf bank_mask:0xf
	v_mov_b32_dpp v225, v168 row_shl:1 row_mask:0xf bank_mask:0xf
	v_mov_b32_dpp v226, v169 row_shl:1 row_mask:0xf bank_mask:0xf
	v_cndmask_b32_e64 v208, v208, v166, s[48:49]
	v_cndmask_b32_e64 v209, v209, v167, s[48:49]
	v_cndmask_b32_e64 v210, v210, v168, s[48:49]
	v_cndmask_b32_e64 v211, v211, v169, s[48:49]
	v_cndmask_b32_e64 v204, v204, v223, s[46:47]
	v_cndmask_b32_e64 v205, v205, v224, s[46:47]
	v_cndmask_b32_e64 v206, v206, v225, s[46:47]
	v_cndmask_b32_e64 v207, v207, v226, s[46:47]
	s_mov_b64 exec, s[48:49]
	v_add_u32_e32 v222, 0x2ec00, v190
	global_load_dwordx4 v[166:169], v222, s[16:17] offset:16
	s_mov_b64 exec, -1
	v_pk_fma_f32 v[216:217], v[118:119], v[204:205], v[216:217]
	v_pk_fma_f32 v[218:219], v[120:121], v[206:207], v[218:219]
	v_pk_fma_f32 v[216:217], v[114:115], v[208:209], v[216:217]
	v_pk_fma_f32 v[218:219], v[116:117], v[210:211], v[218:219]
	v_mul_f32_e32 v204, 0xbfb8aa3b, v216
	v_mul_f32_e32 v205, 0xbfb8aa3b, v217
	v_mul_f32_e32 v206, 0xbfb8aa3b, v218
	v_mul_f32_e32 v207, 0xbfb8aa3b, v219
	v_exp_f32_e32 v204, v204
	v_exp_f32_e32 v205, v205
	v_exp_f32_e32 v206, v206
	v_exp_f32_e32 v207, v207
	v_add_f32_e32 v204, 1.0, v204
	v_add_f32_e32 v205, 1.0, v205
	v_add_f32_e32 v206, 1.0, v206
	v_add_f32_e32 v207, 1.0, v207
	v_rcp_f32_e32 v204, v204
	v_rcp_f32_e32 v205, v205
	v_rcp_f32_e32 v206, v206
	v_rcp_f32_e32 v207, v207
	v_mul_f32_e32 v204, v216, v204
	v_mul_f32_e32 v205, v217, v205
	v_mul_f32_e32 v206, v218, v206
	v_mul_f32_e32 v207, v219, v207
	v_mul_f32_e32 v204, v212, v204
	v_mul_f32_e32 v205, v213, v205
	v_mul_f32_e32 v206, v214, v206
	v_mul_f32_e32 v207, v215, v207
	v_cvt_pk_bf16_f32 v62, v204, v205
	v_cvt_pk_bf16_f32 v63, v206, v207
	v_pk_fma_f32 v[212:213], v[106:107], v[54:55], v[110:111]
	v_pk_fma_f32 v[214:215], v[108:109], v[56:57], v[112:113]
	s_nop 2
	v_mov_b32_dpp v204, v54 row_shr:1 row_mask:0xf bank_mask:0xf
	v_mov_b32_dpp v208, v54 row_shr:2 row_mask:0xf bank_mask:0xf
	v_mov_b32_dpp v205, v55 row_shr:1 row_mask:0xf bank_mask:0xf
	v_mov_b32_dpp v209, v55 row_shr:2 row_mask:0xf bank_mask:0xf
	v_mov_b32_dpp v206, v56 row_shr:1 row_mask:0xf bank_mask:0xf
	v_mov_b32_dpp v210, v56 row_shr:2 row_mask:0xf bank_mask:0xf
	v_mov_b32_dpp v207, v57 row_shr:1 row_mask:0xf bank_mask:0xf
	v_mov_b32_dpp v211, v57 row_shr:2 row_mask:0xf bank_mask:0xf
	s_waitcnt vmcnt(3)
	v_mov_b32_dpp v223, v170 row_shl:1 row_mask:0xf bank_mask:0xf
	v_mov_b32_dpp v224, v171 row_shl:1 row_mask:0xf bank_mask:0xf
	v_mov_b32_dpp v225, v172 row_shl:1 row_mask:0xf bank_mask:0xf
	v_mov_b32_dpp v226, v173 row_shl:1 row_mask:0xf bank_mask:0xf
	v_cndmask_b32_e64 v208, v208, v170, s[48:49]
	v_cndmask_b32_e64 v209, v209, v171, s[48:49]
	v_cndmask_b32_e64 v210, v210, v172, s[48:49]
	v_cndmask_b32_e64 v211, v211, v173, s[48:49]
	v_cndmask_b32_e64 v204, v204, v223, s[46:47]
	v_cndmask_b32_e64 v205, v205, v224, s[46:47]
	v_cndmask_b32_e64 v206, v206, v225, s[46:47]
	v_cndmask_b32_e64 v207, v207, v226, s[46:47]
	s_mov_b64 exec, s[48:49]
	v_add_u32_e32 v222, 0x42000, v190
	global_load_dwordx4 v[170:173], v222, s[16:17] offset:16
	s_mov_b64 exec, -1
	v_pk_fma_f32 v[212:213], v[102:103], v[204:205], v[212:213]
	v_pk_fma_f32 v[214:215], v[104:105], v[206:207], v[214:215]
	v_pk_fma_f32 v[212:213], v[98:99], v[208:209], v[212:213]
	v_pk_fma_f32 v[214:215], v[100:101], v[210:211], v[214:215]
	v_pk_fma_f32 v[216:217], v[122:123], v[50:51], v[126:127]
	v_pk_fma_f32 v[218:219], v[124:125], v[52:53], v[128:129]
	s_nop 2
	v_mov_b32_dpp v204, v50 row_shr:1 row_mask:0xf bank_mask:0xf
	v_mov_b32_dpp v208, v50 row_shr:2 row_mask:0xf bank_mask:0xf
	v_mov_b32_dpp v205, v51 row_shr:1 row_mask:0xf bank_mask:0xf
	v_mov_b32_dpp v209, v51 row_shr:2 row_mask:0xf bank_mask:0xf
	v_mov_b32_dpp v206, v52 row_shr:1 row_mask:0xf bank_mask:0xf
	v_mov_b32_dpp v210, v52 row_shr:2 row_mask:0xf bank_mask:0xf
	v_mov_b32_dpp v207, v53 row_shr:1 row_mask:0xf bank_mask:0xf
	v_mov_b32_dpp v211, v53 row_shr:2 row_mask:0xf bank_mask:0xf
	s_waitcnt vmcnt(3)
	v_mov_b32_dpp v223, v174 row_shl:1 row_mask:0xf bank_mask:0xf
	v_mov_b32_dpp v224, v175 row_shl:1 row_mask:0xf bank_mask:0xf
	v_mov_b32_dpp v225, v176 row_shl:1 row_mask:0xf bank_mask:0xf
	v_mov_b32_dpp v226, v177 row_shl:1 row_mask:0xf bank_mask:0xf
	v_cndmask_b32_e64 v208, v208, v174, s[48:49]
	v_cndmask_b32_e64 v209, v209, v175, s[48:49]
	v_cndmask_b32_e64 v210, v210, v176, s[48:49]
	v_cndmask_b32_e64 v211, v211, v177, s[48:49]
	v_cndmask_b32_e64 v204, v204, v223, s[46:47]
	v_cndmask_b32_e64 v205, v205, v224, s[46:47]
	v_cndmask_b32_e64 v206, v206, v225, s[46:47]
	v_cndmask_b32_e64 v207, v207, v226, s[46:47]
	s_mov_b64 exec, s[48:49]
	v_add_u32_e32 v222, 0x44c00, v190
	global_load_dwordx4 v[174:177], v222, s[16:17] offset:16
	s_mov_b64 exec, -1
	v_pk_fma_f32 v[216:217], v[118:119], v[204:205], v[216:217]
	v_pk_fma_f32 v[218:219], v[120:121], v[206:207], v[218:219]
	v_pk_fma_f32 v[216:217], v[114:115], v[208:209], v[216:217]
	v_pk_fma_f32 v[218:219], v[116:117], v[210:211], v[218:219]
	v_mul_f32_e32 v204, 0xbfb8aa3b, v216
	v_mul_f32_e32 v205, 0xbfb8aa3b, v217
	v_mul_f32_e32 v206, 0xbfb8aa3b, v218
	v_mul_f32_e32 v207, 0xbfb8aa3b, v219
	v_exp_f32_e32 v204, v204
	v_exp_f32_e32 v205, v205
	v_exp_f32_e32 v206, v206
	v_exp_f32_e32 v207, v207
	v_add_f32_e32 v204, 1.0, v204
	v_add_f32_e32 v205, 1.0, v205
	v_add_f32_e32 v206, 1.0, v206
	v_add_f32_e32 v207, 1.0, v207
	v_rcp_f32_e32 v204, v204
	v_rcp_f32_e32 v205, v205
	v_rcp_f32_e32 v206, v206
	v_rcp_f32_e32 v207, v207
	v_mul_f32_e32 v204, v216, v204
	v_mul_f32_e32 v205, v217, v205
	v_mul_f32_e32 v206, v218, v206
	v_mul_f32_e32 v207, v219, v207
	v_mul_f32_e32 v204, v212, v204
	v_mul_f32_e32 v205, v213, v205
	v_mul_f32_e32 v206, v214, v206
	v_mul_f32_e32 v207, v215, v207
	v_cvt_pk_bf16_f32 v54, v204, v205
	v_cvt_pk_bf16_f32 v55, v206, v207
	v_pk_fma_f32 v[212:213], v[106:107], v[46:47], v[110:111]
	v_pk_fma_f32 v[214:215], v[108:109], v[48:49], v[112:113]
	s_nop 2
	v_mov_b32_dpp v204, v46 row_shr:1 row_mask:0xf bank_mask:0xf
	v_mov_b32_dpp v208, v46 row_shr:2 row_mask:0xf bank_mask:0xf
	v_mov_b32_dpp v205, v47 row_shr:1 row_mask:0xf bank_mask:0xf
	v_mov_b32_dpp v209, v47 row_shr:2 row_mask:0xf bank_mask:0xf
	v_mov_b32_dpp v206, v48 row_shr:1 row_mask:0xf bank_mask:0xf
	v_mov_b32_dpp v210, v48 row_shr:2 row_mask:0xf bank_mask:0xf
	v_mov_b32_dpp v207, v49 row_shr:1 row_mask:0xf bank_mask:0xf
	v_mov_b32_dpp v211, v49 row_shr:2 row_mask:0xf bank_mask:0xf
	s_waitcnt vmcnt(3)
	v_mov_b32_dpp v223, v162 row_shl:1 row_mask:0xf bank_mask:0xf
	v_mov_b32_dpp v224, v163 row_shl:1 row_mask:0xf bank_mask:0xf
	v_mov_b32_dpp v225, v164 row_shl:1 row_mask:0xf bank_mask:0xf
	v_mov_b32_dpp v226, v165 row_shl:1 row_mask:0xf bank_mask:0xf
	v_cndmask_b32_e64 v208, v208, v162, s[48:49]
	v_cndmask_b32_e64 v209, v209, v163, s[48:49]
	v_cndmask_b32_e64 v210, v210, v164, s[48:49]
	v_cndmask_b32_e64 v211, v211, v165, s[48:49]
	v_cndmask_b32_e64 v204, v204, v223, s[46:47]
	v_cndmask_b32_e64 v205, v205, v224, s[46:47]
	v_cndmask_b32_e64 v206, v206, v225, s[46:47]
	v_cndmask_b32_e64 v207, v207, v226, s[46:47]
	s_mov_b64 exec, s[48:49]
	v_add_u32_e32 v222, 0xb0000, v190
	global_load_dwordx4 v[162:165], v222, s[16:17] offset:16
	s_mov_b64 exec, -1
	v_pk_fma_f32 v[212:213], v[102:103], v[204:205], v[212:213]
	v_pk_fma_f32 v[214:215], v[104:105], v[206:207], v[214:215]
	v_pk_fma_f32 v[212:213], v[98:99], v[208:209], v[212:213]
	v_pk_fma_f32 v[214:215], v[100:101], v[210:211], v[214:215]
	v_pk_fma_f32 v[216:217], v[122:123], v[42:43], v[126:127]
	v_pk_fma_f32 v[218:219], v[124:125], v[44:45], v[128:129]
	s_nop 2
	v_mov_b32_dpp v204, v42 row_shr:1 row_mask:0xf bank_mask:0xf
	v_mov_b32_dpp v208, v42 row_shr:2 row_mask:0xf bank_mask:0xf
	v_mov_b32_dpp v205, v43 row_shr:1 row_mask:0xf bank_mask:0xf
	v_mov_b32_dpp v209, v43 row_shr:2 row_mask:0xf bank_mask:0xf
	v_mov_b32_dpp v206, v44 row_shr:1 row_mask:0xf bank_mask:0xf
	v_mov_b32_dpp v210, v44 row_shr:2 row_mask:0xf bank_mask:0xf
	v_mov_b32_dpp v207, v45 row_shr:1 row_mask:0xf bank_mask:0xf
	v_mov_b32_dpp v211, v45 row_shr:2 row_mask:0xf bank_mask:0xf
	s_waitcnt vmcnt(3)
	v_mov_b32_dpp v223, v166 row_shl:1 row_mask:0xf bank_mask:0xf
	v_mov_b32_dpp v224, v167 row_shl:1 row_mask:0xf bank_mask:0xf
	v_mov_b32_dpp v225, v168 row_shl:1 row_mask:0xf bank_mask:0xf
	v_mov_b32_dpp v226, v169 row_shl:1 row_mask:0xf bank_mask:0xf
	v_cndmask_b32_e64 v208, v208, v166, s[48:49]
	v_cndmask_b32_e64 v209, v209, v167, s[48:49]
	v_cndmask_b32_e64 v210, v210, v168, s[48:49]
	v_cndmask_b32_e64 v211, v211, v169, s[48:49]
	v_cndmask_b32_e64 v204, v204, v223, s[46:47]
	v_cndmask_b32_e64 v205, v205, v224, s[46:47]
	v_cndmask_b32_e64 v206, v206, v225, s[46:47]
	v_cndmask_b32_e64 v207, v207, v226, s[46:47]
	s_mov_b64 exec, s[48:49]
	v_add_u32_e32 v222, 0xb2c00, v190
	global_load_dwordx4 v[166:169], v222, s[16:17] offset:16
	s_mov_b64 exec, -1
	v_pk_fma_f32 v[216:217], v[118:119], v[204:205], v[216:217]
	v_pk_fma_f32 v[218:219], v[120:121], v[206:207], v[218:219]
	v_pk_fma_f32 v[216:217], v[114:115], v[208:209], v[216:217]
	v_pk_fma_f32 v[218:219], v[116:117], v[210:211], v[218:219]
	v_mul_f32_e32 v204, 0xbfb8aa3b, v216
	v_mul_f32_e32 v205, 0xbfb8aa3b, v217
	v_mul_f32_e32 v206, 0xbfb8aa3b, v218
	v_mul_f32_e32 v207, 0xbfb8aa3b, v219
	v_exp_f32_e32 v204, v204
	v_exp_f32_e32 v205, v205
	v_exp_f32_e32 v206, v206
	v_exp_f32_e32 v207, v207
	v_add_f32_e32 v204, 1.0, v204
	v_add_f32_e32 v205, 1.0, v205
	v_add_f32_e32 v206, 1.0, v206
	v_add_f32_e32 v207, 1.0, v207
	v_rcp_f32_e32 v204, v204
	v_rcp_f32_e32 v205, v205
	v_rcp_f32_e32 v206, v206
	v_rcp_f32_e32 v207, v207
	v_mul_f32_e32 v204, v216, v204
	v_mul_f32_e32 v205, v217, v205
	v_mul_f32_e32 v206, v218, v206
	v_mul_f32_e32 v207, v219, v207
	v_mul_f32_e32 v204, v212, v204
	v_mul_f32_e32 v205, v213, v205
	v_mul_f32_e32 v206, v214, v206
	v_mul_f32_e32 v207, v215, v207
	v_cvt_pk_bf16_f32 v46, v204, v205
	v_cvt_pk_bf16_f32 v47, v206, v207
	v_pk_fma_f32 v[212:213], v[106:107], v[38:39], v[110:111]
	v_pk_fma_f32 v[214:215], v[108:109], v[40:41], v[112:113]
	s_nop 2
	v_mov_b32_dpp v204, v38 row_shr:1 row_mask:0xf bank_mask:0xf
	v_mov_b32_dpp v208, v38 row_shr:2 row_mask:0xf bank_mask:0xf
	v_mov_b32_dpp v205, v39 row_shr:1 row_mask:0xf bank_mask:0xf
	v_mov_b32_dpp v209, v39 row_shr:2 row_mask:0xf bank_mask:0xf
	v_mov_b32_dpp v206, v40 row_shr:1 row_mask:0xf bank_mask:0xf
	v_mov_b32_dpp v210, v40 row_shr:2 row_mask:0xf bank_mask:0xf
	v_mov_b32_dpp v207, v41 row_shr:1 row_mask:0xf bank_mask:0xf
	v_mov_b32_dpp v211, v41 row_shr:2 row_mask:0xf bank_mask:0xf
	s_waitcnt vmcnt(3)
	v_mov_b32_dpp v223, v170 row_shl:1 row_mask:0xf bank_mask:0xf
	v_mov_b32_dpp v224, v171 row_shl:1 row_mask:0xf bank_mask:0xf
	v_mov_b32_dpp v225, v172 row_shl:1 row_mask:0xf bank_mask:0xf
	v_mov_b32_dpp v226, v173 row_shl:1 row_mask:0xf bank_mask:0xf
	v_cndmask_b32_e64 v208, v208, v170, s[48:49]
	v_cndmask_b32_e64 v209, v209, v171, s[48:49]
	v_cndmask_b32_e64 v210, v210, v172, s[48:49]
	v_cndmask_b32_e64 v211, v211, v173, s[48:49]
	v_cndmask_b32_e64 v204, v204, v223, s[46:47]
	v_cndmask_b32_e64 v205, v205, v224, s[46:47]
	v_cndmask_b32_e64 v206, v206, v225, s[46:47]
	v_cndmask_b32_e64 v207, v207, v226, s[46:47]
	s_mov_b64 exec, s[48:49]
	v_add_u32_e32 v222, 0xc6000, v190
	global_load_dwordx4 v[170:173], v222, s[16:17] offset:16
	s_mov_b64 exec, -1
	v_pk_fma_f32 v[212:213], v[102:103], v[204:205], v[212:213]
	v_pk_fma_f32 v[214:215], v[104:105], v[206:207], v[214:215]
	v_pk_fma_f32 v[212:213], v[98:99], v[208:209], v[212:213]
	v_pk_fma_f32 v[214:215], v[100:101], v[210:211], v[214:215]
	v_pk_fma_f32 v[216:217], v[122:123], v[34:35], v[126:127]
	v_pk_fma_f32 v[218:219], v[124:125], v[36:37], v[128:129]
	s_nop 2
	v_mov_b32_dpp v204, v34 row_shr:1 row_mask:0xf bank_mask:0xf
	v_mov_b32_dpp v208, v34 row_shr:2 row_mask:0xf bank_mask:0xf
	v_mov_b32_dpp v205, v35 row_shr:1 row_mask:0xf bank_mask:0xf
	v_mov_b32_dpp v209, v35 row_shr:2 row_mask:0xf bank_mask:0xf
	v_mov_b32_dpp v206, v36 row_shr:1 row_mask:0xf bank_mask:0xf
	v_mov_b32_dpp v210, v36 row_shr:2 row_mask:0xf bank_mask:0xf
	v_mov_b32_dpp v207, v37 row_shr:1 row_mask:0xf bank_mask:0xf
	v_mov_b32_dpp v211, v37 row_shr:2 row_mask:0xf bank_mask:0xf
	s_waitcnt vmcnt(3)
	v_mov_b32_dpp v223, v174 row_shl:1 row_mask:0xf bank_mask:0xf
	v_mov_b32_dpp v224, v175 row_shl:1 row_mask:0xf bank_mask:0xf
	v_mov_b32_dpp v225, v176 row_shl:1 row_mask:0xf bank_mask:0xf
	v_mov_b32_dpp v226, v177 row_shl:1 row_mask:0xf bank_mask:0xf
	v_cndmask_b32_e64 v208, v208, v174, s[48:49]
	v_cndmask_b32_e64 v209, v209, v175, s[48:49]
	v_cndmask_b32_e64 v210, v210, v176, s[48:49]
	v_cndmask_b32_e64 v211, v211, v177, s[48:49]
	v_cndmask_b32_e64 v204, v204, v223, s[46:47]
	v_cndmask_b32_e64 v205, v205, v224, s[46:47]
	v_cndmask_b32_e64 v206, v206, v225, s[46:47]
	v_cndmask_b32_e64 v207, v207, v226, s[46:47]
	s_mov_b64 exec, s[48:49]
	v_add_u32_e32 v222, 0xc8c00, v190
	global_load_dwordx4 v[174:177], v222, s[16:17] offset:16
	s_mov_b64 exec, -1
	v_pk_fma_f32 v[216:217], v[118:119], v[204:205], v[216:217]
	v_pk_fma_f32 v[218:219], v[120:121], v[206:207], v[218:219]
	v_pk_fma_f32 v[216:217], v[114:115], v[208:209], v[216:217]
	v_pk_fma_f32 v[218:219], v[116:117], v[210:211], v[218:219]
	v_mul_f32_e32 v204, 0xbfb8aa3b, v216
	v_mul_f32_e32 v205, 0xbfb8aa3b, v217
	v_mul_f32_e32 v206, 0xbfb8aa3b, v218
	v_mul_f32_e32 v207, 0xbfb8aa3b, v219
	v_exp_f32_e32 v204, v204
	v_exp_f32_e32 v205, v205
	v_exp_f32_e32 v206, v206
	v_exp_f32_e32 v207, v207
	v_add_f32_e32 v204, 1.0, v204
	v_add_f32_e32 v205, 1.0, v205
	v_add_f32_e32 v206, 1.0, v206
	v_add_f32_e32 v207, 1.0, v207
	v_rcp_f32_e32 v204, v204
	v_rcp_f32_e32 v205, v205
	v_rcp_f32_e32 v206, v206
	v_rcp_f32_e32 v207, v207
	v_mul_f32_e32 v204, v216, v204
	v_mul_f32_e32 v205, v217, v205
	v_mul_f32_e32 v206, v218, v206
	v_mul_f32_e32 v207, v219, v207
	v_mul_f32_e32 v204, v212, v204
	v_mul_f32_e32 v205, v213, v205
	v_mul_f32_e32 v206, v214, v206
	v_mul_f32_e32 v207, v215, v207
	v_cvt_pk_bf16_f32 v38, v204, v205
	v_cvt_pk_bf16_f32 v39, v206, v207
	v_pk_fma_f32 v[212:213], v[106:107], v[30:31], v[110:111]
	v_pk_fma_f32 v[214:215], v[108:109], v[32:33], v[112:113]
	s_nop 2
	v_mov_b32_dpp v204, v30 row_shr:1 row_mask:0xf bank_mask:0xf
	v_mov_b32_dpp v208, v30 row_shr:2 row_mask:0xf bank_mask:0xf
	v_mov_b32_dpp v205, v31 row_shr:1 row_mask:0xf bank_mask:0xf
	v_mov_b32_dpp v209, v31 row_shr:2 row_mask:0xf bank_mask:0xf
	v_mov_b32_dpp v206, v32 row_shr:1 row_mask:0xf bank_mask:0xf
	v_mov_b32_dpp v210, v32 row_shr:2 row_mask:0xf bank_mask:0xf
	v_mov_b32_dpp v207, v33 row_shr:1 row_mask:0xf bank_mask:0xf
	v_mov_b32_dpp v211, v33 row_shr:2 row_mask:0xf bank_mask:0xf
	s_waitcnt vmcnt(3)
	v_mov_b32_dpp v223, v162 row_shl:1 row_mask:0xf bank_mask:0xf
	v_mov_b32_dpp v224, v163 row_shl:1 row_mask:0xf bank_mask:0xf
	v_mov_b32_dpp v225, v164 row_shl:1 row_mask:0xf bank_mask:0xf
	v_mov_b32_dpp v226, v165 row_shl:1 row_mask:0xf bank_mask:0xf
	v_cndmask_b32_e64 v208, v208, v162, s[48:49]
	v_cndmask_b32_e64 v209, v209, v163, s[48:49]
	v_cndmask_b32_e64 v210, v210, v164, s[48:49]
	v_cndmask_b32_e64 v211, v211, v165, s[48:49]
	v_cndmask_b32_e64 v204, v204, v223, s[46:47]
	v_cndmask_b32_e64 v205, v205, v224, s[46:47]
	v_cndmask_b32_e64 v206, v206, v225, s[46:47]
	v_cndmask_b32_e64 v207, v207, v226, s[46:47]
	s_mov_b64 exec, s[48:49]
	v_add_u32_e32 v222, 0xdc000, v190
	global_load_dwordx4 v[162:165], v222, s[16:17] offset:16
	s_mov_b64 exec, -1
	v_pk_fma_f32 v[212:213], v[102:103], v[204:205], v[212:213]
	v_pk_fma_f32 v[214:215], v[104:105], v[206:207], v[214:215]
	v_pk_fma_f32 v[212:213], v[98:99], v[208:209], v[212:213]
	v_pk_fma_f32 v[214:215], v[100:101], v[210:211], v[214:215]
	v_pk_fma_f32 v[216:217], v[122:123], v[26:27], v[126:127]
	v_pk_fma_f32 v[218:219], v[124:125], v[28:29], v[128:129]
	s_nop 2
	v_mov_b32_dpp v204, v26 row_shr:1 row_mask:0xf bank_mask:0xf
	v_mov_b32_dpp v208, v26 row_shr:2 row_mask:0xf bank_mask:0xf
	v_mov_b32_dpp v205, v27 row_shr:1 row_mask:0xf bank_mask:0xf
	v_mov_b32_dpp v209, v27 row_shr:2 row_mask:0xf bank_mask:0xf
	v_mov_b32_dpp v206, v28 row_shr:1 row_mask:0xf bank_mask:0xf
	v_mov_b32_dpp v210, v28 row_shr:2 row_mask:0xf bank_mask:0xf
	v_mov_b32_dpp v207, v29 row_shr:1 row_mask:0xf bank_mask:0xf
	v_mov_b32_dpp v211, v29 row_shr:2 row_mask:0xf bank_mask:0xf
	s_waitcnt vmcnt(3)
	v_mov_b32_dpp v223, v166 row_shl:1 row_mask:0xf bank_mask:0xf
	v_mov_b32_dpp v224, v167 row_shl:1 row_mask:0xf bank_mask:0xf
	v_mov_b32_dpp v225, v168 row_shl:1 row_mask:0xf bank_mask:0xf
	v_mov_b32_dpp v226, v169 row_shl:1 row_mask:0xf bank_mask:0xf
	v_cndmask_b32_e64 v208, v208, v166, s[48:49]
	v_cndmask_b32_e64 v209, v209, v167, s[48:49]
	v_cndmask_b32_e64 v210, v210, v168, s[48:49]
	v_cndmask_b32_e64 v211, v211, v169, s[48:49]
	v_cndmask_b32_e64 v204, v204, v223, s[46:47]
	v_cndmask_b32_e64 v205, v205, v224, s[46:47]
	v_cndmask_b32_e64 v206, v206, v225, s[46:47]
	v_cndmask_b32_e64 v207, v207, v226, s[46:47]
	s_mov_b64 exec, s[48:49]
	v_add_u32_e32 v222, 0xdec00, v190
	global_load_dwordx4 v[166:169], v222, s[16:17] offset:16
	s_mov_b64 exec, -1
	v_pk_fma_f32 v[216:217], v[118:119], v[204:205], v[216:217]
	v_pk_fma_f32 v[218:219], v[120:121], v[206:207], v[218:219]
	v_pk_fma_f32 v[216:217], v[114:115], v[208:209], v[216:217]
	v_pk_fma_f32 v[218:219], v[116:117], v[210:211], v[218:219]
	v_mul_f32_e32 v204, 0xbfb8aa3b, v216
	v_mul_f32_e32 v205, 0xbfb8aa3b, v217
	v_mul_f32_e32 v206, 0xbfb8aa3b, v218
	v_mul_f32_e32 v207, 0xbfb8aa3b, v219
	v_exp_f32_e32 v204, v204
	v_exp_f32_e32 v205, v205
	v_exp_f32_e32 v206, v206
	v_exp_f32_e32 v207, v207
	v_add_f32_e32 v204, 1.0, v204
	v_add_f32_e32 v205, 1.0, v205
	v_add_f32_e32 v206, 1.0, v206
	v_add_f32_e32 v207, 1.0, v207
	v_rcp_f32_e32 v204, v204
	v_rcp_f32_e32 v205, v205
	v_rcp_f32_e32 v206, v206
	v_rcp_f32_e32 v207, v207
	v_mul_f32_e32 v204, v216, v204
	v_mul_f32_e32 v205, v217, v205
	v_mul_f32_e32 v206, v218, v206
	v_mul_f32_e32 v207, v219, v207
	v_mul_f32_e32 v204, v212, v204
	v_mul_f32_e32 v205, v213, v205
	v_mul_f32_e32 v206, v214, v206
	v_mul_f32_e32 v207, v215, v207
	v_cvt_pk_bf16_f32 v30, v204, v205
	v_cvt_pk_bf16_f32 v31, v206, v207
	v_pk_fma_f32 v[212:213], v[106:107], v[22:23], v[110:111]
	v_pk_fma_f32 v[214:215], v[108:109], v[24:25], v[112:113]
	s_nop 2
	v_mov_b32_dpp v204, v22 row_shr:1 row_mask:0xf bank_mask:0xf
	v_mov_b32_dpp v208, v22 row_shr:2 row_mask:0xf bank_mask:0xf
	v_mov_b32_dpp v205, v23 row_shr:1 row_mask:0xf bank_mask:0xf
	v_mov_b32_dpp v209, v23 row_shr:2 row_mask:0xf bank_mask:0xf
	v_mov_b32_dpp v206, v24 row_shr:1 row_mask:0xf bank_mask:0xf
	v_mov_b32_dpp v210, v24 row_shr:2 row_mask:0xf bank_mask:0xf
	v_mov_b32_dpp v207, v25 row_shr:1 row_mask:0xf bank_mask:0xf
	v_mov_b32_dpp v211, v25 row_shr:2 row_mask:0xf bank_mask:0xf
	s_waitcnt vmcnt(3)
	v_mov_b32_dpp v223, v170 row_shl:1 row_mask:0xf bank_mask:0xf
	v_mov_b32_dpp v224, v171 row_shl:1 row_mask:0xf bank_mask:0xf
	v_mov_b32_dpp v225, v172 row_shl:1 row_mask:0xf bank_mask:0xf
	v_mov_b32_dpp v226, v173 row_shl:1 row_mask:0xf bank_mask:0xf
	v_cndmask_b32_e64 v208, v208, v170, s[48:49]
	v_cndmask_b32_e64 v209, v209, v171, s[48:49]
	v_cndmask_b32_e64 v210, v210, v172, s[48:49]
	v_cndmask_b32_e64 v211, v211, v173, s[48:49]
	v_cndmask_b32_e64 v204, v204, v223, s[46:47]
	v_cndmask_b32_e64 v205, v205, v224, s[46:47]
	v_cndmask_b32_e64 v206, v206, v225, s[46:47]
	v_cndmask_b32_e64 v207, v207, v226, s[46:47]
	s_mov_b64 exec, s[48:49]
	v_add_u32_e32 v222, 0xf2000, v190
	global_load_dwordx4 v[170:173], v222, s[16:17] offset:16
	s_mov_b64 exec, -1
	v_pk_fma_f32 v[212:213], v[102:103], v[204:205], v[212:213]
	v_pk_fma_f32 v[214:215], v[104:105], v[206:207], v[214:215]
	v_pk_fma_f32 v[212:213], v[98:99], v[208:209], v[212:213]
	v_pk_fma_f32 v[214:215], v[100:101], v[210:211], v[214:215]
	v_pk_fma_f32 v[216:217], v[122:123], v[18:19], v[126:127]
	v_pk_fma_f32 v[218:219], v[124:125], v[20:21], v[128:129]
	s_nop 2
	v_mov_b32_dpp v204, v18 row_shr:1 row_mask:0xf bank_mask:0xf
	v_mov_b32_dpp v208, v18 row_shr:2 row_mask:0xf bank_mask:0xf
	v_mov_b32_dpp v205, v19 row_shr:1 row_mask:0xf bank_mask:0xf
	v_mov_b32_dpp v209, v19 row_shr:2 row_mask:0xf bank_mask:0xf
	v_mov_b32_dpp v206, v20 row_shr:1 row_mask:0xf bank_mask:0xf
	v_mov_b32_dpp v210, v20 row_shr:2 row_mask:0xf bank_mask:0xf
	v_mov_b32_dpp v207, v21 row_shr:1 row_mask:0xf bank_mask:0xf
	v_mov_b32_dpp v211, v21 row_shr:2 row_mask:0xf bank_mask:0xf
	s_waitcnt vmcnt(3)
	v_mov_b32_dpp v223, v174 row_shl:1 row_mask:0xf bank_mask:0xf
	v_mov_b32_dpp v224, v175 row_shl:1 row_mask:0xf bank_mask:0xf
	v_mov_b32_dpp v225, v176 row_shl:1 row_mask:0xf bank_mask:0xf
	v_mov_b32_dpp v226, v177 row_shl:1 row_mask:0xf bank_mask:0xf
	v_cndmask_b32_e64 v208, v208, v174, s[48:49]
	v_cndmask_b32_e64 v209, v209, v175, s[48:49]
	v_cndmask_b32_e64 v210, v210, v176, s[48:49]
	v_cndmask_b32_e64 v211, v211, v177, s[48:49]
	v_cndmask_b32_e64 v204, v204, v223, s[46:47]
	v_cndmask_b32_e64 v205, v205, v224, s[46:47]
	v_cndmask_b32_e64 v206, v206, v225, s[46:47]
	v_cndmask_b32_e64 v207, v207, v226, s[46:47]
	s_mov_b64 exec, s[48:49]
	v_add_u32_e32 v222, 0xf4c00, v190
	global_load_dwordx4 v[174:177], v222, s[16:17] offset:16
	s_mov_b64 exec, -1
	v_pk_fma_f32 v[216:217], v[118:119], v[204:205], v[216:217]
	v_pk_fma_f32 v[218:219], v[120:121], v[206:207], v[218:219]
	v_pk_fma_f32 v[216:217], v[114:115], v[208:209], v[216:217]
	v_pk_fma_f32 v[218:219], v[116:117], v[210:211], v[218:219]
	v_mul_f32_e32 v204, 0xbfb8aa3b, v216
	v_mul_f32_e32 v205, 0xbfb8aa3b, v217
	v_mul_f32_e32 v206, 0xbfb8aa3b, v218
	v_mul_f32_e32 v207, 0xbfb8aa3b, v219
	v_exp_f32_e32 v204, v204
	v_exp_f32_e32 v205, v205
	v_exp_f32_e32 v206, v206
	v_exp_f32_e32 v207, v207
	v_add_f32_e32 v204, 1.0, v204
	v_add_f32_e32 v205, 1.0, v205
	v_add_f32_e32 v206, 1.0, v206
	v_add_f32_e32 v207, 1.0, v207
	v_rcp_f32_e32 v204, v204
	v_rcp_f32_e32 v205, v205
	v_rcp_f32_e32 v206, v206
	v_rcp_f32_e32 v207, v207
	v_mul_f32_e32 v204, v216, v204
	v_mul_f32_e32 v205, v217, v205
	v_mul_f32_e32 v206, v218, v206
	v_mul_f32_e32 v207, v219, v207
	v_mul_f32_e32 v204, v212, v204
	v_mul_f32_e32 v205, v213, v205
	v_mul_f32_e32 v206, v214, v206
	v_mul_f32_e32 v207, v215, v207
	v_cvt_pk_bf16_f32 v22, v204, v205
	v_cvt_pk_bf16_f32 v23, v206, v207
	v_pk_fma_f32 v[212:213], v[106:107], v[14:15], v[110:111]
	v_pk_fma_f32 v[214:215], v[108:109], v[16:17], v[112:113]
	s_nop 2
	v_mov_b32_dpp v204, v14 row_shr:1 row_mask:0xf bank_mask:0xf
	v_mov_b32_dpp v208, v14 row_shr:2 row_mask:0xf bank_mask:0xf
	v_mov_b32_dpp v205, v15 row_shr:1 row_mask:0xf bank_mask:0xf
	v_mov_b32_dpp v209, v15 row_shr:2 row_mask:0xf bank_mask:0xf
	v_mov_b32_dpp v206, v16 row_shr:1 row_mask:0xf bank_mask:0xf
	v_mov_b32_dpp v210, v16 row_shr:2 row_mask:0xf bank_mask:0xf
	v_mov_b32_dpp v207, v17 row_shr:1 row_mask:0xf bank_mask:0xf
	v_mov_b32_dpp v211, v17 row_shr:2 row_mask:0xf bank_mask:0xf
	s_waitcnt vmcnt(3)
	v_mov_b32_dpp v223, v162 row_shl:1 row_mask:0xf bank_mask:0xf
	v_mov_b32_dpp v224, v163 row_shl:1 row_mask:0xf bank_mask:0xf
	v_mov_b32_dpp v225, v164 row_shl:1 row_mask:0xf bank_mask:0xf
	v_mov_b32_dpp v226, v165 row_shl:1 row_mask:0xf bank_mask:0xf
	v_cndmask_b32_e64 v208, v208, v162, s[48:49]
	v_cndmask_b32_e64 v209, v209, v163, s[48:49]
	v_cndmask_b32_e64 v210, v210, v164, s[48:49]
	v_cndmask_b32_e64 v211, v211, v165, s[48:49]
	v_cndmask_b32_e64 v204, v204, v223, s[46:47]
	v_cndmask_b32_e64 v205, v205, v224, s[46:47]
	v_cndmask_b32_e64 v206, v206, v225, s[46:47]
	v_cndmask_b32_e64 v207, v207, v226, s[46:47]
	v_pk_fma_f32 v[212:213], v[102:103], v[204:205], v[212:213]
	v_pk_fma_f32 v[214:215], v[104:105], v[206:207], v[214:215]
	v_pk_fma_f32 v[212:213], v[98:99], v[208:209], v[212:213]
	v_pk_fma_f32 v[214:215], v[100:101], v[210:211], v[214:215]
	v_pk_fma_f32 v[216:217], v[122:123], v[10:11], v[126:127]
	v_pk_fma_f32 v[218:219], v[124:125], v[12:13], v[128:129]
	s_nop 2
	v_mov_b32_dpp v204, v10 row_shr:1 row_mask:0xf bank_mask:0xf
	v_mov_b32_dpp v208, v10 row_shr:2 row_mask:0xf bank_mask:0xf
	v_mov_b32_dpp v205, v11 row_shr:1 row_mask:0xf bank_mask:0xf
	v_mov_b32_dpp v209, v11 row_shr:2 row_mask:0xf bank_mask:0xf
	v_mov_b32_dpp v206, v12 row_shr:1 row_mask:0xf bank_mask:0xf
	v_mov_b32_dpp v210, v12 row_shr:2 row_mask:0xf bank_mask:0xf
	v_mov_b32_dpp v207, v13 row_shr:1 row_mask:0xf bank_mask:0xf
	v_mov_b32_dpp v211, v13 row_shr:2 row_mask:0xf bank_mask:0xf
	s_waitcnt vmcnt(2)
	v_mov_b32_dpp v223, v166 row_shl:1 row_mask:0xf bank_mask:0xf
	v_mov_b32_dpp v224, v167 row_shl:1 row_mask:0xf bank_mask:0xf
	v_mov_b32_dpp v225, v168 row_shl:1 row_mask:0xf bank_mask:0xf
	v_mov_b32_dpp v226, v169 row_shl:1 row_mask:0xf bank_mask:0xf
	v_cndmask_b32_e64 v208, v208, v166, s[48:49]
	v_cndmask_b32_e64 v209, v209, v167, s[48:49]
	v_cndmask_b32_e64 v210, v210, v168, s[48:49]
	v_cndmask_b32_e64 v211, v211, v169, s[48:49]
	v_cndmask_b32_e64 v204, v204, v223, s[46:47]
	v_cndmask_b32_e64 v205, v205, v224, s[46:47]
	v_cndmask_b32_e64 v206, v206, v225, s[46:47]
	v_cndmask_b32_e64 v207, v207, v226, s[46:47]
	v_pk_fma_f32 v[216:217], v[118:119], v[204:205], v[216:217]
	v_pk_fma_f32 v[218:219], v[120:121], v[206:207], v[218:219]
	v_pk_fma_f32 v[216:217], v[114:115], v[208:209], v[216:217]
	v_pk_fma_f32 v[218:219], v[116:117], v[210:211], v[218:219]
	v_mul_f32_e32 v204, 0xbfb8aa3b, v216
	v_mul_f32_e32 v205, 0xbfb8aa3b, v217
	v_mul_f32_e32 v206, 0xbfb8aa3b, v218
	v_mul_f32_e32 v207, 0xbfb8aa3b, v219
	v_exp_f32_e32 v204, v204
	v_exp_f32_e32 v205, v205
	v_exp_f32_e32 v206, v206
	v_exp_f32_e32 v207, v207
	v_add_f32_e32 v204, 1.0, v204
	v_add_f32_e32 v205, 1.0, v205
	v_add_f32_e32 v206, 1.0, v206
	v_add_f32_e32 v207, 1.0, v207
	v_rcp_f32_e32 v204, v204
	v_rcp_f32_e32 v205, v205
	v_rcp_f32_e32 v206, v206
	v_rcp_f32_e32 v207, v207
	v_mul_f32_e32 v204, v216, v204
	v_mul_f32_e32 v205, v217, v205
	v_mul_f32_e32 v206, v218, v206
	v_mul_f32_e32 v207, v219, v207
	v_mul_f32_e32 v204, v212, v204
	v_mul_f32_e32 v205, v213, v205
	v_mul_f32_e32 v206, v214, v206
	v_mul_f32_e32 v207, v215, v207
	v_cvt_pk_bf16_f32 v14, v204, v205
	v_cvt_pk_bf16_f32 v15, v206, v207
	v_pk_fma_f32 v[212:213], v[106:107], v[6:7], v[110:111]
	v_pk_fma_f32 v[214:215], v[108:109], v[8:9], v[112:113]
	s_nop 2
	v_mov_b32_dpp v204, v6 row_shr:1 row_mask:0xf bank_mask:0xf
	v_mov_b32_dpp v208, v6 row_shr:2 row_mask:0xf bank_mask:0xf
	v_mov_b32_dpp v205, v7 row_shr:1 row_mask:0xf bank_mask:0xf
	v_mov_b32_dpp v209, v7 row_shr:2 row_mask:0xf bank_mask:0xf
	v_mov_b32_dpp v206, v8 row_shr:1 row_mask:0xf bank_mask:0xf
	v_mov_b32_dpp v210, v8 row_shr:2 row_mask:0xf bank_mask:0xf
	v_mov_b32_dpp v207, v9 row_shr:1 row_mask:0xf bank_mask:0xf
	v_mov_b32_dpp v211, v9 row_shr:2 row_mask:0xf bank_mask:0xf
	s_waitcnt vmcnt(1)
	v_mov_b32_dpp v223, v170 row_shl:1 row_mask:0xf bank_mask:0xf
	v_mov_b32_dpp v224, v171 row_shl:1 row_mask:0xf bank_mask:0xf
	v_mov_b32_dpp v225, v172 row_shl:1 row_mask:0xf bank_mask:0xf
	v_mov_b32_dpp v226, v173 row_shl:1 row_mask:0xf bank_mask:0xf
	v_cndmask_b32_e64 v208, v208, v170, s[48:49]
	v_cndmask_b32_e64 v209, v209, v171, s[48:49]
	v_cndmask_b32_e64 v210, v210, v172, s[48:49]
	v_cndmask_b32_e64 v211, v211, v173, s[48:49]
	v_cndmask_b32_e64 v204, v204, v223, s[46:47]
	v_cndmask_b32_e64 v205, v205, v224, s[46:47]
	v_cndmask_b32_e64 v206, v206, v225, s[46:47]
	v_cndmask_b32_e64 v207, v207, v226, s[46:47]
	v_pk_fma_f32 v[212:213], v[102:103], v[204:205], v[212:213]
	v_pk_fma_f32 v[214:215], v[104:105], v[206:207], v[214:215]
	v_pk_fma_f32 v[212:213], v[98:99], v[208:209], v[212:213]
	v_pk_fma_f32 v[214:215], v[100:101], v[210:211], v[214:215]
	v_pk_fma_f32 v[216:217], v[122:123], v[2:3], v[126:127]
	v_pk_fma_f32 v[218:219], v[124:125], v[4:5], v[128:129]
	s_nop 2
	v_mov_b32_dpp v204, v2 row_shr:1 row_mask:0xf bank_mask:0xf
	v_mov_b32_dpp v208, v2 row_shr:2 row_mask:0xf bank_mask:0xf
	v_mov_b32_dpp v205, v3 row_shr:1 row_mask:0xf bank_mask:0xf
	v_mov_b32_dpp v209, v3 row_shr:2 row_mask:0xf bank_mask:0xf
	v_mov_b32_dpp v206, v4 row_shr:1 row_mask:0xf bank_mask:0xf
	v_mov_b32_dpp v210, v4 row_shr:2 row_mask:0xf bank_mask:0xf
	v_mov_b32_dpp v207, v5 row_shr:1 row_mask:0xf bank_mask:0xf
	v_mov_b32_dpp v211, v5 row_shr:2 row_mask:0xf bank_mask:0xf
	s_waitcnt vmcnt(0)
	v_mov_b32_dpp v223, v174 row_shl:1 row_mask:0xf bank_mask:0xf
	v_mov_b32_dpp v224, v175 row_shl:1 row_mask:0xf bank_mask:0xf
	v_mov_b32_dpp v225, v176 row_shl:1 row_mask:0xf bank_mask:0xf
	v_mov_b32_dpp v226, v177 row_shl:1 row_mask:0xf bank_mask:0xf
	v_cndmask_b32_e64 v208, v208, v174, s[48:49]
	v_cndmask_b32_e64 v209, v209, v175, s[48:49]
	v_cndmask_b32_e64 v210, v210, v176, s[48:49]
	v_cndmask_b32_e64 v211, v211, v177, s[48:49]
	v_cndmask_b32_e64 v204, v204, v223, s[46:47]
	v_cndmask_b32_e64 v205, v205, v224, s[46:47]
	v_cndmask_b32_e64 v206, v206, v225, s[46:47]
	v_cndmask_b32_e64 v207, v207, v226, s[46:47]
	v_pk_fma_f32 v[216:217], v[118:119], v[204:205], v[216:217]
	v_pk_fma_f32 v[218:219], v[120:121], v[206:207], v[218:219]
	v_pk_fma_f32 v[216:217], v[114:115], v[208:209], v[216:217]
	v_pk_fma_f32 v[218:219], v[116:117], v[210:211], v[218:219]
	v_mul_f32_e32 v204, 0xbfb8aa3b, v216
	v_mul_f32_e32 v205, 0xbfb8aa3b, v217
	v_mul_f32_e32 v206, 0xbfb8aa3b, v218
	v_mul_f32_e32 v207, 0xbfb8aa3b, v219
	v_exp_f32_e32 v204, v204
	v_exp_f32_e32 v205, v205
	v_exp_f32_e32 v206, v206
	v_exp_f32_e32 v207, v207
	v_add_f32_e32 v204, 1.0, v204
	v_add_f32_e32 v205, 1.0, v205
	v_add_f32_e32 v206, 1.0, v206
	v_add_f32_e32 v207, 1.0, v207
	v_rcp_f32_e32 v204, v204
	v_rcp_f32_e32 v205, v205
	v_rcp_f32_e32 v206, v206
	v_rcp_f32_e32 v207, v207
	v_mul_f32_e32 v204, v216, v204
	v_mul_f32_e32 v205, v217, v205
	v_mul_f32_e32 v206, v218, v206
	v_mul_f32_e32 v207, v219, v207
	v_mul_f32_e32 v204, v212, v204
	v_mul_f32_e32 v205, v213, v205
	v_mul_f32_e32 v206, v214, v206
	v_mul_f32_e32 v207, v215, v207
	v_cvt_pk_bf16_f32 v6, v204, v205
	v_cvt_pk_bf16_f32 v7, v206, v207
	v_add_u32_e32 v204, 0xb0000, v231
	s_mov_b32 exec_lo, 0xfffcfffc
	s_mov_b32 exec_hi, 0xfffcfffc
	global_store_dwordx2 v204, v[94:95], s[36:37]
	s_mov_b64 exec, -1
	v_add_u32_e32 v205, 0xc6000, v231
	global_store_dwordx2 v205, v[86:87], s[36:37]
	v_add_u32_e32 v206, 0xdc000, v231
	global_store_dwordx2 v206, v[78:79], s[36:37]
	v_add_u32_e32 v207, 0xf2000, v231
	global_store_dwordx2 v207, v[70:71], s[36:37]
	v_add_u32_e32 v208, 0x8, v231
	s_mov_b32 exec_lo, 0xfffcfffc
	s_mov_b32 exec_hi, 0xfffcfffc
	global_store_dwordx2 v208, v[62:63], s[36:37]
	s_mov_b64 exec, -1
	v_add_u32_e32 v209, 0x16008, v231
	global_store_dwordx2 v209, v[54:55], s[36:37]
	v_add_u32_e32 v210, 0x2c008, v231
	global_store_dwordx2 v210, v[46:47], s[36:37]
	v_add_u32_e32 v211, 0x42008, v231
	global_store_dwordx2 v211, v[38:39], s[36:37]
	v_add_u32_e32 v204, 0xb0008, v231
	s_mov_b32 exec_lo, 0xfffcfffc
	s_mov_b32 exec_hi, 0xfffcfffc
	global_store_dwordx2 v204, v[30:31], s[36:37]
	s_mov_b64 exec, -1
	v_add_u32_e32 v205, 0xc6008, v231
	global_store_dwordx2 v205, v[22:23], s[36:37]
	v_add_u32_e32 v206, 0xdc008, v231
	global_store_dwordx2 v206, v[14:15], s[36:37]
	v_add_u32_e32 v207, 0xf2008, v231
	global_store_dwordx2 v207, v[6:7], s[36:37]
	s_branch .LBB0_4739
